# K-loop MMA blocks: accumulate chains with alternating K-step direction so the MFMA at each chain boundary reuses the previous MFMA's weight-fragment operand (f32 accumulation order of the two K-steps
# speedup vs baseline: 1.0076x; 1.0076x over previous
.LBB0_322:
	s_ashr_i32 s43, s42, 31
	s_lshl_b64 s[46:47], s[42:43], 19
	s_add_u32 s46, s12, s46
	s_addc_u32 s47, s13, s47
	s_and_b64 s[48:49], s[4:5], exec
	s_cselect_b32 s18, s47, s7
	s_cselect_b32 s43, s46, s6
	s_ashr_i32 s45, s44, 31
	s_lshl_b64 s[48:49], s[44:45], 19
	s_add_u32 s48, s59, s48
	s_addc_u32 s49, s60, s49
	s_and_b64 s[50:51], s[4:5], exec
	s_cselect_b32 s45, s49, s9
	s_cselect_b32 s55, s48, s8
	s_add_u32 s6, s6, 0x40080
	s_addc_u32 s7, s7, 0
	s_add_u32 s56, s8, 0x100
	s_addc_u32 s57, s9, 0
	s_mov_b32 s78, -2
	ds_read_b128 v[96:99], v209
	ds_read_b128 v[100:103], v209 offset:1024
	ds_read_b128 v[120:123], v209 offset:2048
	ds_read_b128 v[124:127], v209 offset:3072
	ds_read_b128 v[144:147], v210
	ds_read_b128 v[148:151], v210 offset:1024
	ds_read_b128 v[152:155], v210 offset:2048
	ds_read_b128 v[156:159], v210 offset:3072
	s_add_u32 s8, s6, 0xfffc0080
	s_addc_u32 s9, s7, -1
	s_cmp_eq_u32 s78, 12
	s_cselect_b32 s51, s18, s9
	s_cselect_b32 s50, s43, s8
	s_cselect_b32 s9, s45, s57
	s_cselect_b32 s8, s55, s56
	v_lshl_add_u64 v[206:207], s[6:7], 0, v[170:171]
	s_add_i32 m0, s17, 0xc000
	ds_read_b128 v[178:181], v211
	ds_read_b128 v[182:185], v211 offset:1024
	ds_read_b128 v[186:189], v211 offset:2048
	ds_read_b128 v[190:193], v211 offset:3072
	ds_read_b128 v[194:197], v211 offset:4096
	ds_read_b128 v[198:201], v211 offset:5120
	ds_read_b128 v[202:205], v211 offset:6144
	ds_read_b128 v[218:221], v211 offset:7168
	global_load_lds_dwordx4 v[206:207], off
	s_add_i32 m0, s17, 0xe000
	v_lshl_add_u64 v[206:207], s[6:7], 0, v[172:173]
	global_load_lds_dwordx4 v[206:207], off
	s_waitcnt vmcnt(8) lgkmcnt(0)
	s_barrier
	s_setprio 1
	v_mfma_f32_16x16x32_bf16 v[140:143], v[96:99], v[178:181], 0
	v_mfma_f32_16x16x32_bf16 v[140:143], v[100:103], v[182:185], v[140:143]
	v_mfma_f32_16x16x32_bf16 v[116:119], v[100:103], v[190:193], 0
	v_mfma_f32_16x16x32_bf16 v[116:119], v[96:99], v[186:189], v[116:119]
	v_mfma_f32_16x16x32_bf16 v[92:95], v[96:99], v[194:197], 0
	v_mfma_f32_16x16x32_bf16 v[92:95], v[100:103], v[198:201], v[92:95]
	v_mfma_f32_16x16x32_bf16 v[76:79], v[100:103], v[218:221], 0
	v_mfma_f32_16x16x32_bf16 v[76:79], v[96:99], v[202:205], v[76:79]
	v_mfma_f32_16x16x32_bf16 v[136:139], v[120:123], v[178:181], 0
	v_mfma_f32_16x16x32_bf16 v[136:139], v[124:127], v[182:185], v[136:139]
	v_mfma_f32_16x16x32_bf16 v[112:115], v[124:127], v[190:193], 0
	v_mfma_f32_16x16x32_bf16 v[112:115], v[120:123], v[186:189], v[112:115]
	v_mfma_f32_16x16x32_bf16 v[88:91], v[120:123], v[194:197], 0
	v_mfma_f32_16x16x32_bf16 v[88:91], v[124:127], v[198:201], v[88:91]
	v_mfma_f32_16x16x32_bf16 v[72:75], v[124:127], v[218:221], 0
	v_mfma_f32_16x16x32_bf16 v[72:75], v[120:123], v[202:205], v[72:75]
	v_mfma_f32_16x16x32_bf16 v[132:135], v[144:147], v[178:181], 0
	v_mfma_f32_16x16x32_bf16 v[132:135], v[148:151], v[182:185], v[132:135]
	v_mfma_f32_16x16x32_bf16 v[108:111], v[148:151], v[190:193], 0
	v_mfma_f32_16x16x32_bf16 v[108:111], v[144:147], v[186:189], v[108:111]
	v_mfma_f32_16x16x32_bf16 v[84:87], v[144:147], v[194:197], 0
	v_mfma_f32_16x16x32_bf16 v[84:87], v[148:151], v[198:201], v[84:87]
	v_mfma_f32_16x16x32_bf16 v[68:71], v[148:151], v[218:221], 0
	v_mfma_f32_16x16x32_bf16 v[68:71], v[144:147], v[202:205], v[68:71]
	v_mfma_f32_16x16x32_bf16 v[128:131], v[152:155], v[178:181], 0
	v_mfma_f32_16x16x32_bf16 v[128:131], v[156:159], v[182:185], v[128:131]
	v_mfma_f32_16x16x32_bf16 v[104:107], v[156:159], v[190:193], 0
	v_mfma_f32_16x16x32_bf16 v[104:107], v[152:155], v[186:189], v[104:107]
	s_setprio 2
	s_barrier
	v_mfma_f32_16x16x32_bf16 v[80:83], v[152:155], v[194:197], 0
	v_mfma_f32_16x16x32_bf16 v[80:83], v[156:159], v[198:201], v[80:83]
	v_mfma_f32_16x16x32_bf16 v[64:67], v[156:159], v[218:221], 0
	v_mfma_f32_16x16x32_bf16 v[64:67], v[152:155], v[202:205], v[64:67]
	s_setprio 2
	s_add_i32 s79, s73, s61
	v_lshl_add_u64 v[206:207], s[8:9], 0, v[162:163]
	s_mov_b32 m0, s79
	ds_read_b128 v[178:181], v211 offset:16384
	ds_read_b128 v[182:185], v211 offset:17408
	ds_read_b128 v[186:189], v211 offset:18432
	ds_read_b128 v[190:193], v211 offset:19456
	ds_read_b128 v[194:197], v211 offset:20480
	ds_read_b128 v[198:201], v211 offset:21504
	ds_read_b128 v[202:205], v211 offset:22528
	ds_read_b128 v[218:221], v211 offset:23552
	global_load_lds_dwordx4 v[206:207], off
	s_add_i32 m0, s79, 0x2000
	s_add_u32 s80, s8, 0x40000
	v_lshl_add_u64 v[222:223], s[8:9], 0, v[166:167]
	s_addc_u32 s81, s9, 0
	s_add_i32 s79, s74, s61
	global_load_lds_dwordx4 v[222:223], off
	v_lshl_add_u64 v[224:225], s[80:81], 0, v[162:163]
	s_mov_b32 m0, s79
	v_lshl_add_u64 v[226:227], s[50:51], 0, v[164:165]
	global_load_lds_dwordx4 v[224:225], off
	s_add_i32 m0, s79, 0x2000
	v_lshl_add_u64 v[224:225], s[80:81], 0, v[166:167]
	global_load_lds_dwordx4 v[224:225], off
	s_mov_b32 m0, s17
	v_lshl_add_u64 v[224:225], s[50:51], 0, v[160:161]
	global_load_lds_dwordx4 v[224:225], off
	s_mov_b32 m0, s62
	s_nop 0
	global_load_lds_dwordx4 v[226:227], off
	s_waitcnt vmcnt(8) lgkmcnt(0)
	s_barrier
	s_setprio 1
	v_mfma_f32_16x16x32_bf16 v[60:63], v[96:99], v[178:181], 0
	v_mfma_f32_16x16x32_bf16 v[60:63], v[100:103], v[182:185], v[60:63]
	v_mfma_f32_16x16x32_bf16 v[44:47], v[100:103], v[190:193], 0
	v_mfma_f32_16x16x32_bf16 v[44:47], v[96:99], v[186:189], v[44:47]
	v_mfma_f32_16x16x32_bf16 v[28:31], v[96:99], v[194:197], 0
	v_mfma_f32_16x16x32_bf16 v[28:31], v[100:103], v[198:201], v[28:31]
	v_mfma_f32_16x16x32_bf16 v[12:15], v[100:103], v[218:221], 0
	v_mfma_f32_16x16x32_bf16 v[12:15], v[96:99], v[202:205], v[12:15]
	v_mfma_f32_16x16x32_bf16 v[56:59], v[120:123], v[178:181], 0
	v_mfma_f32_16x16x32_bf16 v[56:59], v[124:127], v[182:185], v[56:59]
	v_mfma_f32_16x16x32_bf16 v[40:43], v[124:127], v[190:193], 0
	v_mfma_f32_16x16x32_bf16 v[40:43], v[120:123], v[186:189], v[40:43]
	v_mfma_f32_16x16x32_bf16 v[24:27], v[120:123], v[194:197], 0
	v_mfma_f32_16x16x32_bf16 v[24:27], v[124:127], v[198:201], v[24:27]
	v_mfma_f32_16x16x32_bf16 v[8:11], v[124:127], v[218:221], 0
	v_mfma_f32_16x16x32_bf16 v[8:11], v[120:123], v[202:205], v[8:11]
	v_mfma_f32_16x16x32_bf16 v[52:55], v[144:147], v[178:181], 0
	v_mfma_f32_16x16x32_bf16 v[52:55], v[148:151], v[182:185], v[52:55]
	v_mfma_f32_16x16x32_bf16 v[36:39], v[148:151], v[190:193], 0
	v_mfma_f32_16x16x32_bf16 v[36:39], v[144:147], v[186:189], v[36:39]
	v_mfma_f32_16x16x32_bf16 v[20:23], v[144:147], v[194:197], 0
	v_mfma_f32_16x16x32_bf16 v[20:23], v[148:151], v[198:201], v[20:23]
	v_mfma_f32_16x16x32_bf16 v[4:7], v[148:151], v[218:221], 0
	v_mfma_f32_16x16x32_bf16 v[4:7], v[144:147], v[202:205], v[4:7]
	v_mfma_f32_16x16x32_bf16 v[48:51], v[152:155], v[178:181], 0
	v_mfma_f32_16x16x32_bf16 v[48:51], v[156:159], v[182:185], v[48:51]
	v_mfma_f32_16x16x32_bf16 v[32:35], v[156:159], v[190:193], 0
	v_mfma_f32_16x16x32_bf16 v[32:35], v[152:155], v[186:189], v[32:35]
	s_setprio 2
	s_barrier
	v_mfma_f32_16x16x32_bf16 v[16:19], v[152:155], v[194:197], 0
	v_mfma_f32_16x16x32_bf16 v[16:19], v[156:159], v[198:201], v[16:19]
	v_mfma_f32_16x16x32_bf16 v[0:3], v[156:159], v[218:221], 0
	v_mfma_f32_16x16x32_bf16 v[0:3], v[152:155], v[202:205], v[0:3]
	s_setprio 0
	s_add_i32 s79, 0, 0x18000
	s_add_i32 s80, 0, 0x1c000
	v_add_u32_e32 v124, s79, v208
	v_add_u32_e32 v156, s80, v208
	ds_read_b128 v[96:99], v124
	ds_read_b128 v[100:103], v124 offset:1024
	ds_read_b128 v[120:123], v124 offset:2048
	ds_read_b128 v[124:127], v124 offset:3072
	ds_read_b128 v[144:147], v156
	ds_read_b128 v[148:151], v156 offset:1024
	ds_read_b128 v[152:155], v156 offset:2048
	ds_read_b128 v[156:159], v156 offset:3072
	s_add_u32 s50, s50, 0x40000
	s_addc_u32 s51, s51, 0
	s_mov_b32 m0, s63
	v_lshl_add_u64 v[228:229], s[50:51], 0, v[160:161]
	ds_read_b128 v[178:181], v211 offset:32768
	ds_read_b128 v[182:185], v211 offset:33792
	ds_read_b128 v[186:189], v211 offset:34816
	ds_read_b128 v[190:193], v211 offset:35840
	ds_read_b128 v[194:197], v211 offset:36864
	ds_read_b128 v[198:201], v211 offset:37888
	ds_read_b128 v[202:205], v211 offset:38912
	ds_read_b128 v[218:221], v211 offset:39936
	global_load_lds_dwordx4 v[228:229], off
	s_mov_b32 m0, s64
	v_lshl_add_u64 v[228:229], s[50:51], 0, v[164:165]
	global_load_lds_dwordx4 v[228:229], off
	s_waitcnt vmcnt(8) lgkmcnt(0)
	s_barrier
	s_setprio 1
	v_mfma_f32_16x16x32_bf16 v[140:143], v[96:99], v[178:181], v[140:143]
	v_mfma_f32_16x16x32_bf16 v[140:143], v[100:103], v[182:185], v[140:143]
	v_mfma_f32_16x16x32_bf16 v[116:119], v[100:103], v[190:193], v[116:119]
	v_mfma_f32_16x16x32_bf16 v[116:119], v[96:99], v[186:189], v[116:119]
	v_mfma_f32_16x16x32_bf16 v[92:95], v[96:99], v[194:197], v[92:95]
	v_mfma_f32_16x16x32_bf16 v[92:95], v[100:103], v[198:201], v[92:95]
	v_mfma_f32_16x16x32_bf16 v[76:79], v[100:103], v[218:221], v[76:79]
	v_mfma_f32_16x16x32_bf16 v[76:79], v[96:99], v[202:205], v[76:79]
	v_mfma_f32_16x16x32_bf16 v[136:139], v[120:123], v[178:181], v[136:139]
	v_mfma_f32_16x16x32_bf16 v[136:139], v[124:127], v[182:185], v[136:139]
	v_mfma_f32_16x16x32_bf16 v[112:115], v[124:127], v[190:193], v[112:115]
	v_mfma_f32_16x16x32_bf16 v[112:115], v[120:123], v[186:189], v[112:115]
	v_mfma_f32_16x16x32_bf16 v[88:91], v[120:123], v[194:197], v[88:91]
	v_mfma_f32_16x16x32_bf16 v[88:91], v[124:127], v[198:201], v[88:91]
	v_mfma_f32_16x16x32_bf16 v[72:75], v[124:127], v[218:221], v[72:75]
	v_mfma_f32_16x16x32_bf16 v[72:75], v[120:123], v[202:205], v[72:75]
	v_mfma_f32_16x16x32_bf16 v[132:135], v[144:147], v[178:181], v[132:135]
	v_mfma_f32_16x16x32_bf16 v[132:135], v[148:151], v[182:185], v[132:135]
	v_mfma_f32_16x16x32_bf16 v[108:111], v[148:151], v[190:193], v[108:111]
	v_mfma_f32_16x16x32_bf16 v[108:111], v[144:147], v[186:189], v[108:111]
	v_mfma_f32_16x16x32_bf16 v[84:87], v[144:147], v[194:197], v[84:87]
	v_mfma_f32_16x16x32_bf16 v[84:87], v[148:151], v[198:201], v[84:87]
	v_mfma_f32_16x16x32_bf16 v[68:71], v[148:151], v[218:221], v[68:71]
	v_mfma_f32_16x16x32_bf16 v[68:71], v[144:147], v[202:205], v[68:71]
	v_mfma_f32_16x16x32_bf16 v[128:131], v[152:155], v[178:181], v[128:131]
	v_mfma_f32_16x16x32_bf16 v[128:131], v[156:159], v[182:185], v[128:131]
	v_mfma_f32_16x16x32_bf16 v[104:107], v[156:159], v[190:193], v[104:107]
	v_mfma_f32_16x16x32_bf16 v[104:107], v[152:155], v[186:189], v[104:107]
	s_setprio 2
	s_barrier
	v_mfma_f32_16x16x32_bf16 v[80:83], v[152:155], v[194:197], v[80:83]
	v_mfma_f32_16x16x32_bf16 v[80:83], v[156:159], v[198:201], v[80:83]
	v_mfma_f32_16x16x32_bf16 v[64:67], v[156:159], v[218:221], v[64:67]
	v_mfma_f32_16x16x32_bf16 v[64:67], v[152:155], v[202:205], v[64:67]
	s_setprio 2
	s_add_i32 s50, s79, s61
	v_lshl_add_u64 v[206:207], v[206:207], 0, s[36:37]
	s_mov_b32 m0, s50
	ds_read_b128 v[178:181], v211 offset:49152
	ds_read_b128 v[182:185], v211 offset:50176
	ds_read_b128 v[186:189], v211 offset:51200
	ds_read_b128 v[190:193], v211 offset:52224
	ds_read_b128 v[194:197], v211 offset:53248
	ds_read_b128 v[198:201], v211 offset:54272
	ds_read_b128 v[202:205], v211 offset:55296
	ds_read_b128 v[218:221], v211 offset:56320
	global_load_lds_dwordx4 v[206:207], off
	s_add_i32 m0, s50, 0x2000
	s_add_u32 s8, s8, 0x40080
	v_lshl_add_u64 v[206:207], v[222:223], 0, s[36:37]
	s_addc_u32 s9, s9, 0
	s_add_i32 s50, s80, s61
	global_load_lds_dwordx4 v[206:207], off
	s_mov_b32 m0, s50
	v_lshl_add_u64 v[206:207], s[8:9], 0, v[162:163]
	global_load_lds_dwordx4 v[206:207], off
	s_add_i32 m0, s50, 0x2000
	v_lshl_add_u64 v[206:207], s[8:9], 0, v[166:167]
	global_load_lds_dwordx4 v[206:207], off
	s_mov_b32 m0, s68
	v_lshl_add_u64 v[206:207], v[224:225], 0, s[36:37]
	global_load_lds_dwordx4 v[206:207], off
	s_mov_b32 m0, s69
	v_lshl_add_u64 v[206:207], v[226:227], 0, s[36:37]
	global_load_lds_dwordx4 v[206:207], off
	s_waitcnt vmcnt(8) lgkmcnt(0)
	s_barrier
	s_setprio 1
	v_mfma_f32_16x16x32_bf16 v[60:63], v[96:99], v[178:181], v[60:63]
	v_mfma_f32_16x16x32_bf16 v[60:63], v[100:103], v[182:185], v[60:63]
	v_mfma_f32_16x16x32_bf16 v[44:47], v[100:103], v[190:193], v[44:47]
	v_mfma_f32_16x16x32_bf16 v[44:47], v[96:99], v[186:189], v[44:47]
	v_mfma_f32_16x16x32_bf16 v[28:31], v[96:99], v[194:197], v[28:31]
	v_mfma_f32_16x16x32_bf16 v[28:31], v[100:103], v[198:201], v[28:31]
	v_mfma_f32_16x16x32_bf16 v[12:15], v[100:103], v[218:221], v[12:15]
	v_mfma_f32_16x16x32_bf16 v[12:15], v[96:99], v[202:205], v[12:15]
	v_mfma_f32_16x16x32_bf16 v[56:59], v[120:123], v[178:181], v[56:59]
	v_mfma_f32_16x16x32_bf16 v[56:59], v[124:127], v[182:185], v[56:59]
	v_mfma_f32_16x16x32_bf16 v[40:43], v[124:127], v[190:193], v[40:43]
	v_mfma_f32_16x16x32_bf16 v[40:43], v[120:123], v[186:189], v[40:43]
	v_mfma_f32_16x16x32_bf16 v[24:27], v[120:123], v[194:197], v[24:27]
	v_mfma_f32_16x16x32_bf16 v[24:27], v[124:127], v[198:201], v[24:27]
	v_mfma_f32_16x16x32_bf16 v[8:11], v[124:127], v[218:221], v[8:11]
	v_mfma_f32_16x16x32_bf16 v[8:11], v[120:123], v[202:205], v[8:11]
	v_mfma_f32_16x16x32_bf16 v[52:55], v[144:147], v[178:181], v[52:55]
	v_mfma_f32_16x16x32_bf16 v[52:55], v[148:151], v[182:185], v[52:55]
	v_mfma_f32_16x16x32_bf16 v[36:39], v[148:151], v[190:193], v[36:39]
	v_mfma_f32_16x16x32_bf16 v[36:39], v[144:147], v[186:189], v[36:39]
	v_mfma_f32_16x16x32_bf16 v[20:23], v[144:147], v[194:197], v[20:23]
	v_mfma_f32_16x16x32_bf16 v[20:23], v[148:151], v[198:201], v[20:23]
	v_mfma_f32_16x16x32_bf16 v[4:7], v[148:151], v[218:221], v[4:7]
	v_mfma_f32_16x16x32_bf16 v[4:7], v[144:147], v[202:205], v[4:7]
	v_mfma_f32_16x16x32_bf16 v[48:51], v[152:155], v[178:181], v[48:51]
	v_mfma_f32_16x16x32_bf16 v[48:51], v[156:159], v[182:185], v[48:51]
	v_mfma_f32_16x16x32_bf16 v[32:35], v[156:159], v[190:193], v[32:35]
	v_mfma_f32_16x16x32_bf16 v[32:35], v[152:155], v[186:189], v[32:35]
	s_setprio 2
	s_barrier
	v_mfma_f32_16x16x32_bf16 v[16:19], v[152:155], v[194:197], v[16:19]
	v_mfma_f32_16x16x32_bf16 v[16:19], v[156:159], v[198:201], v[16:19]
	v_mfma_f32_16x16x32_bf16 v[0:3], v[156:159], v[218:221], v[0:3]
	v_mfma_f32_16x16x32_bf16 v[0:3], v[152:155], v[202:205], v[0:3]
	s_setprio 0
	s_add_i32 s78, s78, 2
	s_add_u32 s6, s6, 0x100
	s_addc_u32 s7, s7, 0
	s_add_u32 s56, s56, 0x100
	s_addc_u32 s57, s57, 0
	s_cmp_gt_u32 s78, 13
.LBB0_323:
	ds_read_b128 v[96:99], v209
	ds_read_b128 v[100:103], v209 offset:1024
	ds_read_b128 v[120:123], v209 offset:2048
	ds_read_b128 v[124:127], v209 offset:3072
	ds_read_b128 v[144:147], v210
	ds_read_b128 v[148:151], v210 offset:1024
	ds_read_b128 v[152:155], v210 offset:2048
	ds_read_b128 v[156:159], v210 offset:3072
	s_add_u32 s8, s6, 0xfffc0080
	s_addc_u32 s9, s7, -1
	s_cmp_eq_u32 s78, 12
	s_cselect_b32 s51, s18, s9
	s_cselect_b32 s50, s43, s8
	s_cselect_b32 s9, s45, s57
	s_cselect_b32 s8, s55, s56
	v_lshl_add_u64 v[206:207], s[6:7], 0, v[170:171]
	s_add_i32 m0, s17, 0xc000
	ds_read_b128 v[178:181], v211
	ds_read_b128 v[182:185], v211 offset:1024
	ds_read_b128 v[186:189], v211 offset:2048
	ds_read_b128 v[190:193], v211 offset:3072
	ds_read_b128 v[194:197], v211 offset:4096
	ds_read_b128 v[198:201], v211 offset:5120
	ds_read_b128 v[202:205], v211 offset:6144
	ds_read_b128 v[218:221], v211 offset:7168
	global_load_lds_dwordx4 v[206:207], off
	s_add_i32 m0, s17, 0xe000
	v_lshl_add_u64 v[206:207], s[6:7], 0, v[172:173]
	global_load_lds_dwordx4 v[206:207], off
	s_waitcnt vmcnt(8) lgkmcnt(0)
	s_barrier
	s_setprio 1
	v_mfma_f32_16x16x32_bf16 v[140:143], v[96:99], v[178:181], v[140:143]
	v_mfma_f32_16x16x32_bf16 v[140:143], v[100:103], v[182:185], v[140:143]
	v_mfma_f32_16x16x32_bf16 v[116:119], v[100:103], v[190:193], v[116:119]
	v_mfma_f32_16x16x32_bf16 v[116:119], v[96:99], v[186:189], v[116:119]
	v_mfma_f32_16x16x32_bf16 v[92:95], v[96:99], v[194:197], v[92:95]
	v_mfma_f32_16x16x32_bf16 v[92:95], v[100:103], v[198:201], v[92:95]
	v_mfma_f32_16x16x32_bf16 v[76:79], v[100:103], v[218:221], v[76:79]
	v_mfma_f32_16x16x32_bf16 v[76:79], v[96:99], v[202:205], v[76:79]
	v_mfma_f32_16x16x32_bf16 v[136:139], v[120:123], v[178:181], v[136:139]
	v_mfma_f32_16x16x32_bf16 v[136:139], v[124:127], v[182:185], v[136:139]
	v_mfma_f32_16x16x32_bf16 v[112:115], v[124:127], v[190:193], v[112:115]
	v_mfma_f32_16x16x32_bf16 v[112:115], v[120:123], v[186:189], v[112:115]
	v_mfma_f32_16x16x32_bf16 v[88:91], v[120:123], v[194:197], v[88:91]
	v_mfma_f32_16x16x32_bf16 v[88:91], v[124:127], v[198:201], v[88:91]
	v_mfma_f32_16x16x32_bf16 v[72:75], v[124:127], v[218:221], v[72:75]
	v_mfma_f32_16x16x32_bf16 v[72:75], v[120:123], v[202:205], v[72:75]
	v_mfma_f32_16x16x32_bf16 v[132:135], v[144:147], v[178:181], v[132:135]
	v_mfma_f32_16x16x32_bf16 v[132:135], v[148:151], v[182:185], v[132:135]
	v_mfma_f32_16x16x32_bf16 v[108:111], v[148:151], v[190:193], v[108:111]
	v_mfma_f32_16x16x32_bf16 v[108:111], v[144:147], v[186:189], v[108:111]
	v_mfma_f32_16x16x32_bf16 v[84:87], v[144:147], v[194:197], v[84:87]
	v_mfma_f32_16x16x32_bf16 v[84:87], v[148:151], v[198:201], v[84:87]
	v_mfma_f32_16x16x32_bf16 v[68:71], v[148:151], v[218:221], v[68:71]
	v_mfma_f32_16x16x32_bf16 v[68:71], v[144:147], v[202:205], v[68:71]
	v_mfma_f32_16x16x32_bf16 v[128:131], v[152:155], v[178:181], v[128:131]
	v_mfma_f32_16x16x32_bf16 v[128:131], v[156:159], v[182:185], v[128:131]
	v_mfma_f32_16x16x32_bf16 v[104:107], v[156:159], v[190:193], v[104:107]
	v_mfma_f32_16x16x32_bf16 v[104:107], v[152:155], v[186:189], v[104:107]
	s_setprio 2
	s_barrier
	v_mfma_f32_16x16x32_bf16 v[80:83], v[152:155], v[194:197], v[80:83]
	v_mfma_f32_16x16x32_bf16 v[80:83], v[156:159], v[198:201], v[80:83]
	v_mfma_f32_16x16x32_bf16 v[64:67], v[156:159], v[218:221], v[64:67]
	v_mfma_f32_16x16x32_bf16 v[64:67], v[152:155], v[202:205], v[64:67]
	s_setprio 2
	s_add_i32 s79, s73, s61
	v_lshl_add_u64 v[206:207], s[8:9], 0, v[162:163]
	s_mov_b32 m0, s79
	ds_read_b128 v[178:181], v211 offset:16384
	ds_read_b128 v[182:185], v211 offset:17408
	ds_read_b128 v[186:189], v211 offset:18432
	ds_read_b128 v[190:193], v211 offset:19456
	ds_read_b128 v[194:197], v211 offset:20480
	ds_read_b128 v[198:201], v211 offset:21504
	ds_read_b128 v[202:205], v211 offset:22528
	ds_read_b128 v[218:221], v211 offset:23552
	global_load_lds_dwordx4 v[206:207], off
	s_add_i32 m0, s79, 0x2000
	s_add_u32 s80, s8, 0x40000
	v_lshl_add_u64 v[222:223], s[8:9], 0, v[166:167]
	s_addc_u32 s81, s9, 0
	s_add_i32 s79, s74, s61
	global_load_lds_dwordx4 v[222:223], off
	v_lshl_add_u64 v[224:225], s[80:81], 0, v[162:163]
	s_mov_b32 m0, s79
	v_lshl_add_u64 v[226:227], s[50:51], 0, v[164:165]
	global_load_lds_dwordx4 v[224:225], off
	s_add_i32 m0, s79, 0x2000
	v_lshl_add_u64 v[224:225], s[80:81], 0, v[166:167]
	global_load_lds_dwordx4 v[224:225], off
	s_mov_b32 m0, s17
	v_lshl_add_u64 v[224:225], s[50:51], 0, v[160:161]
	global_load_lds_dwordx4 v[224:225], off
	s_mov_b32 m0, s62
	s_nop 0
	global_load_lds_dwordx4 v[226:227], off
	s_waitcnt vmcnt(8) lgkmcnt(0)
	s_barrier
	s_setprio 1
	v_mfma_f32_16x16x32_bf16 v[60:63], v[96:99], v[178:181], v[60:63]
	v_mfma_f32_16x16x32_bf16 v[60:63], v[100:103], v[182:185], v[60:63]
	v_mfma_f32_16x16x32_bf16 v[44:47], v[100:103], v[190:193], v[44:47]
	v_mfma_f32_16x16x32_bf16 v[44:47], v[96:99], v[186:189], v[44:47]
	v_mfma_f32_16x16x32_bf16 v[28:31], v[96:99], v[194:197], v[28:31]
	v_mfma_f32_16x16x32_bf16 v[28:31], v[100:103], v[198:201], v[28:31]
	v_mfma_f32_16x16x32_bf16 v[12:15], v[100:103], v[218:221], v[12:15]
	v_mfma_f32_16x16x32_bf16 v[12:15], v[96:99], v[202:205], v[12:15]
	v_mfma_f32_16x16x32_bf16 v[56:59], v[120:123], v[178:181], v[56:59]
	v_mfma_f32_16x16x32_bf16 v[56:59], v[124:127], v[182:185], v[56:59]
	v_mfma_f32_16x16x32_bf16 v[40:43], v[124:127], v[190:193], v[40:43]
	v_mfma_f32_16x16x32_bf16 v[40:43], v[120:123], v[186:189], v[40:43]
	v_mfma_f32_16x16x32_bf16 v[24:27], v[120:123], v[194:197], v[24:27]
	v_mfma_f32_16x16x32_bf16 v[24:27], v[124:127], v[198:201], v[24:27]
	v_mfma_f32_16x16x32_bf16 v[8:11], v[124:127], v[218:221], v[8:11]
	v_mfma_f32_16x16x32_bf16 v[8:11], v[120:123], v[202:205], v[8:11]
	v_mfma_f32_16x16x32_bf16 v[52:55], v[144:147], v[178:181], v[52:55]
	v_mfma_f32_16x16x32_bf16 v[52:55], v[148:151], v[182:185], v[52:55]
	v_mfma_f32_16x16x32_bf16 v[36:39], v[148:151], v[190:193], v[36:39]
	v_mfma_f32_16x16x32_bf16 v[36:39], v[144:147], v[186:189], v[36:39]
	v_mfma_f32_16x16x32_bf16 v[20:23], v[144:147], v[194:197], v[20:23]
	v_mfma_f32_16x16x32_bf16 v[20:23], v[148:151], v[198:201], v[20:23]
	v_mfma_f32_16x16x32_bf16 v[4:7], v[148:151], v[218:221], v[4:7]
	v_mfma_f32_16x16x32_bf16 v[4:7], v[144:147], v[202:205], v[4:7]
	v_mfma_f32_16x16x32_bf16 v[48:51], v[152:155], v[178:181], v[48:51]
	v_mfma_f32_16x16x32_bf16 v[48:51], v[156:159], v[182:185], v[48:51]
	v_mfma_f32_16x16x32_bf16 v[32:35], v[156:159], v[190:193], v[32:35]
	v_mfma_f32_16x16x32_bf16 v[32:35], v[152:155], v[186:189], v[32:35]
	s_setprio 2
	s_barrier
	v_mfma_f32_16x16x32_bf16 v[16:19], v[152:155], v[194:197], v[16:19]
	v_mfma_f32_16x16x32_bf16 v[16:19], v[156:159], v[198:201], v[16:19]
	v_mfma_f32_16x16x32_bf16 v[0:3], v[156:159], v[218:221], v[0:3]
	v_mfma_f32_16x16x32_bf16 v[0:3], v[152:155], v[202:205], v[0:3]
	s_setprio 0
	s_add_i32 s79, 0, 0x18000
	s_add_i32 s80, 0, 0x1c000
	v_add_u32_e32 v124, s79, v208
	v_add_u32_e32 v156, s80, v208
	ds_read_b128 v[96:99], v124
	ds_read_b128 v[100:103], v124 offset:1024
	ds_read_b128 v[120:123], v124 offset:2048
	ds_read_b128 v[124:127], v124 offset:3072
	ds_read_b128 v[144:147], v156
	ds_read_b128 v[148:151], v156 offset:1024
	ds_read_b128 v[152:155], v156 offset:2048
	ds_read_b128 v[156:159], v156 offset:3072
	s_add_u32 s50, s50, 0x40000
	s_addc_u32 s51, s51, 0
	s_mov_b32 m0, s63
	v_lshl_add_u64 v[228:229], s[50:51], 0, v[160:161]
	ds_read_b128 v[178:181], v211 offset:32768
	ds_read_b128 v[182:185], v211 offset:33792
	ds_read_b128 v[186:189], v211 offset:34816
	ds_read_b128 v[190:193], v211 offset:35840
	ds_read_b128 v[194:197], v211 offset:36864
	ds_read_b128 v[198:201], v211 offset:37888
	ds_read_b128 v[202:205], v211 offset:38912
	ds_read_b128 v[218:221], v211 offset:39936
	global_load_lds_dwordx4 v[228:229], off
	s_mov_b32 m0, s64
	v_lshl_add_u64 v[228:229], s[50:51], 0, v[164:165]
	global_load_lds_dwordx4 v[228:229], off
	s_waitcnt vmcnt(8) lgkmcnt(0)
	s_barrier
	s_setprio 1
	v_mfma_f32_16x16x32_bf16 v[140:143], v[96:99], v[178:181], v[140:143]
	v_mfma_f32_16x16x32_bf16 v[140:143], v[100:103], v[182:185], v[140:143]
	v_mfma_f32_16x16x32_bf16 v[116:119], v[100:103], v[190:193], v[116:119]
	v_mfma_f32_16x16x32_bf16 v[116:119], v[96:99], v[186:189], v[116:119]
	v_mfma_f32_16x16x32_bf16 v[92:95], v[96:99], v[194:197], v[92:95]
	v_mfma_f32_16x16x32_bf16 v[92:95], v[100:103], v[198:201], v[92:95]
	v_mfma_f32_16x16x32_bf16 v[76:79], v[100:103], v[218:221], v[76:79]
	v_mfma_f32_16x16x32_bf16 v[76:79], v[96:99], v[202:205], v[76:79]
	v_mfma_f32_16x16x32_bf16 v[136:139], v[120:123], v[178:181], v[136:139]
	v_mfma_f32_16x16x32_bf16 v[136:139], v[124:127], v[182:185], v[136:139]
	v_mfma_f32_16x16x32_bf16 v[112:115], v[124:127], v[190:193], v[112:115]
	v_mfma_f32_16x16x32_bf16 v[112:115], v[120:123], v[186:189], v[112:115]
	v_mfma_f32_16x16x32_bf16 v[88:91], v[120:123], v[194:197], v[88:91]
	v_mfma_f32_16x16x32_bf16 v[88:91], v[124:127], v[198:201], v[88:91]
	v_mfma_f32_16x16x32_bf16 v[72:75], v[124:127], v[218:221], v[72:75]
	v_mfma_f32_16x16x32_bf16 v[72:75], v[120:123], v[202:205], v[72:75]
	v_mfma_f32_16x16x32_bf16 v[132:135], v[144:147], v[178:181], v[132:135]
	v_mfma_f32_16x16x32_bf16 v[132:135], v[148:151], v[182:185], v[132:135]
	v_mfma_f32_16x16x32_bf16 v[108:111], v[148:151], v[190:193], v[108:111]
	v_mfma_f32_16x16x32_bf16 v[108:111], v[144:147], v[186:189], v[108:111]
	v_mfma_f32_16x16x32_bf16 v[84:87], v[144:147], v[194:197], v[84:87]
	v_mfma_f32_16x16x32_bf16 v[84:87], v[148:151], v[198:201], v[84:87]
	v_mfma_f32_16x16x32_bf16 v[68:71], v[148:151], v[218:221], v[68:71]
	v_mfma_f32_16x16x32_bf16 v[68:71], v[144:147], v[202:205], v[68:71]
	v_mfma_f32_16x16x32_bf16 v[128:131], v[152:155], v[178:181], v[128:131]
	v_mfma_f32_16x16x32_bf16 v[128:131], v[156:159], v[182:185], v[128:131]
	v_mfma_f32_16x16x32_bf16 v[104:107], v[156:159], v[190:193], v[104:107]
	v_mfma_f32_16x16x32_bf16 v[104:107], v[152:155], v[186:189], v[104:107]
	s_setprio 2
	s_barrier
	v_mfma_f32_16x16x32_bf16 v[80:83], v[152:155], v[194:197], v[80:83]
	v_mfma_f32_16x16x32_bf16 v[80:83], v[156:159], v[198:201], v[80:83]
	v_mfma_f32_16x16x32_bf16 v[64:67], v[156:159], v[218:221], v[64:67]
	v_mfma_f32_16x16x32_bf16 v[64:67], v[152:155], v[202:205], v[64:67]
	s_setprio 2
	s_add_i32 s50, s79, s61
	v_lshl_add_u64 v[206:207], v[206:207], 0, s[36:37]
	s_mov_b32 m0, s50
	ds_read_b128 v[178:181], v211 offset:49152
	ds_read_b128 v[182:185], v211 offset:50176
	ds_read_b128 v[186:189], v211 offset:51200
	ds_read_b128 v[190:193], v211 offset:52224
	ds_read_b128 v[194:197], v211 offset:53248
	ds_read_b128 v[198:201], v211 offset:54272
	ds_read_b128 v[202:205], v211 offset:55296
	ds_read_b128 v[218:221], v211 offset:56320
	global_load_lds_dwordx4 v[206:207], off
	s_add_i32 m0, s50, 0x2000
	s_add_u32 s8, s8, 0x40080
	v_lshl_add_u64 v[206:207], v[222:223], 0, s[36:37]
	s_addc_u32 s9, s9, 0
	s_add_i32 s50, s80, s61
	global_load_lds_dwordx4 v[206:207], off
	s_mov_b32 m0, s50
	v_lshl_add_u64 v[206:207], s[8:9], 0, v[162:163]
	global_load_lds_dwordx4 v[206:207], off
	s_add_i32 m0, s50, 0x2000
	v_lshl_add_u64 v[206:207], s[8:9], 0, v[166:167]
	global_load_lds_dwordx4 v[206:207], off
	s_mov_b32 m0, s68
	v_lshl_add_u64 v[206:207], v[224:225], 0, s[36:37]
	global_load_lds_dwordx4 v[206:207], off
	s_mov_b32 m0, s69
	v_lshl_add_u64 v[206:207], v[226:227], 0, s[36:37]
	global_load_lds_dwordx4 v[206:207], off
	s_waitcnt vmcnt(8) lgkmcnt(0)
	s_barrier
	s_setprio 1
	v_mfma_f32_16x16x32_bf16 v[60:63], v[96:99], v[178:181], v[60:63]
	v_mfma_f32_16x16x32_bf16 v[60:63], v[100:103], v[182:185], v[60:63]
	v_mfma_f32_16x16x32_bf16 v[44:47], v[100:103], v[190:193], v[44:47]
	v_mfma_f32_16x16x32_bf16 v[44:47], v[96:99], v[186:189], v[44:47]
	v_mfma_f32_16x16x32_bf16 v[28:31], v[96:99], v[194:197], v[28:31]
	v_mfma_f32_16x16x32_bf16 v[28:31], v[100:103], v[198:201], v[28:31]
	v_mfma_f32_16x16x32_bf16 v[12:15], v[100:103], v[218:221], v[12:15]
	v_mfma_f32_16x16x32_bf16 v[12:15], v[96:99], v[202:205], v[12:15]
	v_mfma_f32_16x16x32_bf16 v[56:59], v[120:123], v[178:181], v[56:59]
	v_mfma_f32_16x16x32_bf16 v[56:59], v[124:127], v[182:185], v[56:59]
	v_mfma_f32_16x16x32_bf16 v[40:43], v[124:127], v[190:193], v[40:43]
	v_mfma_f32_16x16x32_bf16 v[40:43], v[120:123], v[186:189], v[40:43]
	v_mfma_f32_16x16x32_bf16 v[24:27], v[120:123], v[194:197], v[24:27]
	v_mfma_f32_16x16x32_bf16 v[24:27], v[124:127], v[198:201], v[24:27]
	v_mfma_f32_16x16x32_bf16 v[8:11], v[124:127], v[218:221], v[8:11]
	v_mfma_f32_16x16x32_bf16 v[8:11], v[120:123], v[202:205], v[8:11]
	v_mfma_f32_16x16x32_bf16 v[52:55], v[144:147], v[178:181], v[52:55]
	v_mfma_f32_16x16x32_bf16 v[52:55], v[148:151], v[182:185], v[52:55]
	v_mfma_f32_16x16x32_bf16 v[36:39], v[148:151], v[190:193], v[36:39]
	v_mfma_f32_16x16x32_bf16 v[36:39], v[144:147], v[186:189], v[36:39]
	v_mfma_f32_16x16x32_bf16 v[20:23], v[144:147], v[194:197], v[20:23]
	v_mfma_f32_16x16x32_bf16 v[20:23], v[148:151], v[198:201], v[20:23]
	v_mfma_f32_16x16x32_bf16 v[4:7], v[148:151], v[218:221], v[4:7]
	v_mfma_f32_16x16x32_bf16 v[4:7], v[144:147], v[202:205], v[4:7]
	v_mfma_f32_16x16x32_bf16 v[48:51], v[152:155], v[178:181], v[48:51]
	v_mfma_f32_16x16x32_bf16 v[48:51], v[156:159], v[182:185], v[48:51]
	v_mfma_f32_16x16x32_bf16 v[32:35], v[156:159], v[190:193], v[32:35]
	v_mfma_f32_16x16x32_bf16 v[32:35], v[152:155], v[186:189], v[32:35]
	s_setprio 2
	s_barrier
	v_mfma_f32_16x16x32_bf16 v[16:19], v[152:155], v[194:197], v[16:19]
	v_mfma_f32_16x16x32_bf16 v[16:19], v[156:159], v[198:201], v[16:19]
	v_mfma_f32_16x16x32_bf16 v[0:3], v[156:159], v[218:221], v[0:3]
	v_mfma_f32_16x16x32_bf16 v[0:3], v[152:155], v[202:205], v[0:3]
	s_setprio 0
	s_add_i32 s78, s78, 2
	s_add_u32 s6, s6, 0x100
	s_addc_u32 s7, s7, 0
	s_add_u32 s56, s56, 0x100
	s_addc_u32 s57, s57, 0
	s_cmp_gt_u32 s78, 13
	s_cbranch_scc0 .LBB0_323

.LBB0_700:
	ds_read_b128 v[130:133], v203
	ds_read_b128 v[134:137], v203 offset:1024
	ds_read_b128 v[138:141], v203 offset:2048
	ds_read_b128 v[142:145], v203 offset:3072
	ds_read_b128 v[146:149], v195
	ds_read_b128 v[150:153], v195 offset:1024
	ds_read_b128 v[154:157], v195 offset:2048
	ds_read_b128 v[158:161], v195 offset:3072
	s_add_u32 s47, s44, 0xfff80080
	s_addc_u32 s48, s45, -1
	s_cmp_eq_u32 s46, 28
	s_cselect_b32 s49, s29, s48
	s_cselect_b32 s48, s71, s47
	s_cselect_b32 s47, s31, s84
	s_cselect_b32 s46, s72, s83
	s_mov_b32 m0, s73
	v_lshl_add_u64 v[174:175], s[44:45], 0, v[180:181]
	ds_read_b128 v[162:165], v211
	ds_read_b128 v[166:169], v211 offset:1024
	ds_read_b128 v[170:173], v211 offset:2048
	ds_read_b128 v[184:187], v211 offset:3072
	ds_read_b128 v[190:193], v211 offset:4096
	ds_read_b128 v[196:199], v211 offset:5120
	ds_read_b128 v[204:207], v211 offset:6144
	ds_read_b128 v[212:215], v211 offset:7168
	global_load_lds_dwordx4 v[174:175], off
	s_mov_b32 m0, s74
	v_lshl_add_u64 v[174:175], s[44:45], 0, v[182:183]
	global_load_lds_dwordx4 v[174:175], off
	s_waitcnt vmcnt(8) lgkmcnt(0)
	s_barrier
	s_setprio 1
	v_mfma_f32_16x16x32_bf16 v[124:127], v[130:133], v[162:165], v[124:127]
	v_mfma_f32_16x16x32_bf16 v[124:127], v[134:137], v[166:169], v[124:127]
	v_mfma_f32_16x16x32_bf16 v[108:111], v[134:137], v[184:187], v[108:111]
	v_mfma_f32_16x16x32_bf16 v[108:111], v[130:133], v[170:173], v[108:111]
	v_mfma_f32_16x16x32_bf16 v[92:95], v[130:133], v[190:193], v[92:95]
	v_mfma_f32_16x16x32_bf16 v[92:95], v[134:137], v[196:199], v[92:95]
	v_mfma_f32_16x16x32_bf16 v[76:79], v[134:137], v[212:215], v[76:79]
	v_mfma_f32_16x16x32_bf16 v[76:79], v[130:133], v[204:207], v[76:79]
	v_mfma_f32_16x16x32_bf16 v[120:123], v[138:141], v[162:165], v[120:123]
	v_mfma_f32_16x16x32_bf16 v[120:123], v[142:145], v[166:169], v[120:123]
	v_mfma_f32_16x16x32_bf16 v[104:107], v[142:145], v[184:187], v[104:107]
	v_mfma_f32_16x16x32_bf16 v[104:107], v[138:141], v[170:173], v[104:107]
	v_mfma_f32_16x16x32_bf16 v[88:91], v[138:141], v[190:193], v[88:91]
	v_mfma_f32_16x16x32_bf16 v[88:91], v[142:145], v[196:199], v[88:91]
	v_mfma_f32_16x16x32_bf16 v[72:75], v[142:145], v[212:215], v[72:75]
	v_mfma_f32_16x16x32_bf16 v[72:75], v[138:141], v[204:207], v[72:75]
	v_mfma_f32_16x16x32_bf16 v[116:119], v[146:149], v[162:165], v[116:119]
	v_mfma_f32_16x16x32_bf16 v[116:119], v[150:153], v[166:169], v[116:119]
	v_mfma_f32_16x16x32_bf16 v[100:103], v[150:153], v[184:187], v[100:103]
	v_mfma_f32_16x16x32_bf16 v[100:103], v[146:149], v[170:173], v[100:103]
	v_mfma_f32_16x16x32_bf16 v[84:87], v[146:149], v[190:193], v[84:87]
	v_mfma_f32_16x16x32_bf16 v[84:87], v[150:153], v[196:199], v[84:87]
	v_mfma_f32_16x16x32_bf16 v[68:71], v[150:153], v[212:215], v[68:71]
	v_mfma_f32_16x16x32_bf16 v[68:71], v[146:149], v[204:207], v[68:71]
	v_mfma_f32_16x16x32_bf16 v[112:115], v[154:157], v[162:165], v[112:115]
	v_mfma_f32_16x16x32_bf16 v[112:115], v[158:161], v[166:169], v[112:115]
	v_mfma_f32_16x16x32_bf16 v[96:99], v[158:161], v[184:187], v[96:99]
	v_mfma_f32_16x16x32_bf16 v[96:99], v[154:157], v[170:173], v[96:99]
	s_setprio 2
	s_barrier
	v_mfma_f32_16x16x32_bf16 v[80:83], v[154:157], v[190:193], v[80:83]
	v_mfma_f32_16x16x32_bf16 v[80:83], v[158:161], v[196:199], v[80:83]
	v_mfma_f32_16x16x32_bf16 v[64:67], v[158:161], v[212:215], v[64:67]
	v_mfma_f32_16x16x32_bf16 v[64:67], v[154:157], v[204:207], v[64:67]
	s_setprio 2
	s_mov_b32 m0, s75
	v_lshl_add_u64 v[174:175], s[46:47], 0, v[176:177]
	s_add_u32 s86, s46, 0x80000
	ds_read_b128 v[162:165], v211 offset:16384
	ds_read_b128 v[166:169], v211 offset:17408
	ds_read_b128 v[170:173], v211 offset:18432
	ds_read_b128 v[184:187], v211 offset:19456
	ds_read_b128 v[190:193], v211 offset:20480
	ds_read_b128 v[196:199], v211 offset:21504
	ds_read_b128 v[204:207], v211 offset:22528
	ds_read_b128 v[212:215], v211 offset:23552
	global_load_lds_dwordx4 v[174:175], off
	v_lshl_add_u64 v[200:201], s[46:47], 0, v[178:179]
	s_mov_b32 m0, s76
	s_addc_u32 s87, s47, 0
	global_load_lds_dwordx4 v[200:201], off
	v_lshl_add_u64 v[208:209], s[86:87], 0, v[176:177]
	s_mov_b32 m0, s77
	v_lshl_add_u64 v[216:217], s[48:49], 0, v[178:179]
	global_load_lds_dwordx4 v[208:209], off
	s_mov_b32 m0, s78
	v_lshl_add_u64 v[208:209], s[86:87], 0, v[178:179]
	global_load_lds_dwordx4 v[208:209], off
	s_mov_b32 m0, s56
	v_lshl_add_u64 v[208:209], s[48:49], 0, v[176:177]
	global_load_lds_dwordx4 v[208:209], off
	s_mov_b32 m0, s57
	s_nop 0
	global_load_lds_dwordx4 v[216:217], off
	s_waitcnt vmcnt(8) lgkmcnt(0)
	s_barrier
	s_setprio 1
	v_mfma_f32_16x16x32_bf16 v[60:63], v[130:133], v[162:165], v[60:63]
	v_mfma_f32_16x16x32_bf16 v[60:63], v[134:137], v[166:169], v[60:63]
	v_mfma_f32_16x16x32_bf16 v[44:47], v[134:137], v[184:187], v[44:47]
	v_mfma_f32_16x16x32_bf16 v[44:47], v[130:133], v[170:173], v[44:47]
	v_mfma_f32_16x16x32_bf16 v[28:31], v[130:133], v[190:193], v[28:31]
	v_mfma_f32_16x16x32_bf16 v[28:31], v[134:137], v[196:199], v[28:31]
	v_mfma_f32_16x16x32_bf16 v[12:15], v[134:137], v[212:215], v[12:15]
	v_mfma_f32_16x16x32_bf16 v[12:15], v[130:133], v[204:207], v[12:15]
	v_mfma_f32_16x16x32_bf16 v[56:59], v[138:141], v[162:165], v[56:59]
	v_mfma_f32_16x16x32_bf16 v[56:59], v[142:145], v[166:169], v[56:59]
	v_mfma_f32_16x16x32_bf16 v[40:43], v[142:145], v[184:187], v[40:43]
	v_mfma_f32_16x16x32_bf16 v[40:43], v[138:141], v[170:173], v[40:43]
	v_mfma_f32_16x16x32_bf16 v[24:27], v[138:141], v[190:193], v[24:27]
	v_mfma_f32_16x16x32_bf16 v[24:27], v[142:145], v[196:199], v[24:27]
	v_mfma_f32_16x16x32_bf16 v[8:11], v[142:145], v[212:215], v[8:11]
	v_mfma_f32_16x16x32_bf16 v[8:11], v[138:141], v[204:207], v[8:11]
	v_mfma_f32_16x16x32_bf16 v[52:55], v[146:149], v[162:165], v[52:55]
	v_mfma_f32_16x16x32_bf16 v[52:55], v[150:153], v[166:169], v[52:55]
	v_mfma_f32_16x16x32_bf16 v[36:39], v[150:153], v[184:187], v[36:39]
	v_mfma_f32_16x16x32_bf16 v[36:39], v[146:149], v[170:173], v[36:39]
	v_mfma_f32_16x16x32_bf16 v[20:23], v[146:149], v[190:193], v[20:23]
	v_mfma_f32_16x16x32_bf16 v[20:23], v[150:153], v[196:199], v[20:23]
	v_mfma_f32_16x16x32_bf16 v[4:7], v[150:153], v[212:215], v[4:7]
	v_mfma_f32_16x16x32_bf16 v[4:7], v[146:149], v[204:207], v[4:7]
	v_mfma_f32_16x16x32_bf16 v[48:51], v[154:157], v[162:165], v[48:51]
	v_mfma_f32_16x16x32_bf16 v[48:51], v[158:161], v[166:169], v[48:51]
	v_mfma_f32_16x16x32_bf16 v[32:35], v[158:161], v[184:187], v[32:35]
	v_mfma_f32_16x16x32_bf16 v[32:35], v[154:157], v[170:173], v[32:35]
	s_setprio 2
	s_barrier
	v_mfma_f32_16x16x32_bf16 v[16:19], v[154:157], v[190:193], v[16:19]
	v_mfma_f32_16x16x32_bf16 v[16:19], v[158:161], v[196:199], v[16:19]
	v_mfma_f32_16x16x32_bf16 v[0:3], v[158:161], v[212:215], v[0:3]
	v_mfma_f32_16x16x32_bf16 v[0:3], v[154:157], v[204:207], v[0:3]
	s_setprio 0
	ds_read_b128 v[130:133], v128
	ds_read_b128 v[134:137], v128 offset:1024
	ds_read_b128 v[138:141], v128 offset:2048
	ds_read_b128 v[142:145], v128 offset:3072
	ds_read_b128 v[146:149], v129
	ds_read_b128 v[150:153], v129 offset:1024
	ds_read_b128 v[154:157], v129 offset:2048
	ds_read_b128 v[158:161], v129 offset:3072
	s_add_u32 s48, s48, 0x80000
	s_addc_u32 s49, s49, 0
	s_mov_b32 m0, s58
	v_lshl_add_u64 v[218:219], s[48:49], 0, v[176:177]
	ds_read_b128 v[162:165], v211 offset:32768
	ds_read_b128 v[166:169], v211 offset:33792
	ds_read_b128 v[170:173], v211 offset:34816
	ds_read_b128 v[184:187], v211 offset:35840
	ds_read_b128 v[190:193], v211 offset:36864
	ds_read_b128 v[196:199], v211 offset:37888
	ds_read_b128 v[204:207], v211 offset:38912
	ds_read_b128 v[212:215], v211 offset:39936
	global_load_lds_dwordx4 v[218:219], off
	s_mov_b32 m0, s59
	v_lshl_add_u64 v[218:219], s[48:49], 0, v[178:179]
	global_load_lds_dwordx4 v[218:219], off
	s_waitcnt vmcnt(8) lgkmcnt(0)
	s_barrier
	s_setprio 1
	v_mfma_f32_16x16x32_bf16 v[124:127], v[130:133], v[162:165], v[124:127]
	v_mfma_f32_16x16x32_bf16 v[124:127], v[134:137], v[166:169], v[124:127]
	v_mfma_f32_16x16x32_bf16 v[108:111], v[134:137], v[184:187], v[108:111]
	v_mfma_f32_16x16x32_bf16 v[108:111], v[130:133], v[170:173], v[108:111]
	v_mfma_f32_16x16x32_bf16 v[92:95], v[130:133], v[190:193], v[92:95]
	v_mfma_f32_16x16x32_bf16 v[92:95], v[134:137], v[196:199], v[92:95]
	v_mfma_f32_16x16x32_bf16 v[76:79], v[134:137], v[212:215], v[76:79]
	v_mfma_f32_16x16x32_bf16 v[76:79], v[130:133], v[204:207], v[76:79]
	v_mfma_f32_16x16x32_bf16 v[120:123], v[138:141], v[162:165], v[120:123]
	v_mfma_f32_16x16x32_bf16 v[120:123], v[142:145], v[166:169], v[120:123]
	v_mfma_f32_16x16x32_bf16 v[104:107], v[142:145], v[184:187], v[104:107]
	v_mfma_f32_16x16x32_bf16 v[104:107], v[138:141], v[170:173], v[104:107]
	v_mfma_f32_16x16x32_bf16 v[88:91], v[138:141], v[190:193], v[88:91]
	v_mfma_f32_16x16x32_bf16 v[88:91], v[142:145], v[196:199], v[88:91]
	v_mfma_f32_16x16x32_bf16 v[72:75], v[142:145], v[212:215], v[72:75]
	v_mfma_f32_16x16x32_bf16 v[72:75], v[138:141], v[204:207], v[72:75]
	v_mfma_f32_16x16x32_bf16 v[116:119], v[146:149], v[162:165], v[116:119]
	v_mfma_f32_16x16x32_bf16 v[116:119], v[150:153], v[166:169], v[116:119]
	v_mfma_f32_16x16x32_bf16 v[100:103], v[150:153], v[184:187], v[100:103]
	v_mfma_f32_16x16x32_bf16 v[100:103], v[146:149], v[170:173], v[100:103]
	v_mfma_f32_16x16x32_bf16 v[84:87], v[146:149], v[190:193], v[84:87]
	v_mfma_f32_16x16x32_bf16 v[84:87], v[150:153], v[196:199], v[84:87]
	v_mfma_f32_16x16x32_bf16 v[68:71], v[150:153], v[212:215], v[68:71]
	v_mfma_f32_16x16x32_bf16 v[68:71], v[146:149], v[204:207], v[68:71]
	v_mfma_f32_16x16x32_bf16 v[112:115], v[154:157], v[162:165], v[112:115]
	v_mfma_f32_16x16x32_bf16 v[112:115], v[158:161], v[166:169], v[112:115]
	v_mfma_f32_16x16x32_bf16 v[96:99], v[158:161], v[184:187], v[96:99]
	v_mfma_f32_16x16x32_bf16 v[96:99], v[154:157], v[170:173], v[96:99]
	s_setprio 2
	s_barrier
	v_mfma_f32_16x16x32_bf16 v[80:83], v[154:157], v[190:193], v[80:83]
	v_mfma_f32_16x16x32_bf16 v[80:83], v[158:161], v[196:199], v[80:83]
	v_mfma_f32_16x16x32_bf16 v[64:67], v[158:161], v[212:215], v[64:67]
	v_mfma_f32_16x16x32_bf16 v[64:67], v[154:157], v[204:207], v[64:67]
	s_setprio 2
	s_mov_b32 m0, s79
	v_lshl_add_u64 v[174:175], v[174:175], 0, s[20:21]
	s_add_u32 s46, s46, 0x80080
	ds_read_b128 v[162:165], v211 offset:49152
	ds_read_b128 v[166:169], v211 offset:50176
	ds_read_b128 v[170:173], v211 offset:51200
	ds_read_b128 v[184:187], v211 offset:52224
	ds_read_b128 v[190:193], v211 offset:53248
	ds_read_b128 v[196:199], v211 offset:54272
	ds_read_b128 v[204:207], v211 offset:55296
	ds_read_b128 v[212:215], v211 offset:56320
	global_load_lds_dwordx4 v[174:175], off
	v_lshl_add_u64 v[174:175], v[200:201], 0, s[20:21]
	s_mov_b32 m0, s80
	s_addc_u32 s47, s47, 0
	global_load_lds_dwordx4 v[174:175], off
	s_mov_b32 m0, s81
	v_lshl_add_u64 v[174:175], s[46:47], 0, v[176:177]
	global_load_lds_dwordx4 v[174:175], off
	s_mov_b32 m0, s82
	v_lshl_add_u64 v[174:175], s[46:47], 0, v[178:179]
	global_load_lds_dwordx4 v[174:175], off
	s_mov_b32 m0, s61
	v_lshl_add_u64 v[174:175], v[208:209], 0, s[20:21]
	global_load_lds_dwordx4 v[174:175], off
	s_mov_b32 m0, s62
	v_lshl_add_u64 v[174:175], v[216:217], 0, s[20:21]
	global_load_lds_dwordx4 v[174:175], off
	s_waitcnt vmcnt(8) lgkmcnt(0)
	s_barrier
	s_setprio 1
	v_mfma_f32_16x16x32_bf16 v[60:63], v[130:133], v[162:165], v[60:63]
	v_mfma_f32_16x16x32_bf16 v[60:63], v[134:137], v[166:169], v[60:63]
	v_mfma_f32_16x16x32_bf16 v[44:47], v[134:137], v[184:187], v[44:47]
	v_mfma_f32_16x16x32_bf16 v[44:47], v[130:133], v[170:173], v[44:47]
	v_mfma_f32_16x16x32_bf16 v[28:31], v[130:133], v[190:193], v[28:31]
	v_mfma_f32_16x16x32_bf16 v[28:31], v[134:137], v[196:199], v[28:31]
	v_mfma_f32_16x16x32_bf16 v[12:15], v[134:137], v[212:215], v[12:15]
	v_mfma_f32_16x16x32_bf16 v[12:15], v[130:133], v[204:207], v[12:15]
	v_mfma_f32_16x16x32_bf16 v[56:59], v[138:141], v[162:165], v[56:59]
	v_mfma_f32_16x16x32_bf16 v[56:59], v[142:145], v[166:169], v[56:59]
	v_mfma_f32_16x16x32_bf16 v[40:43], v[142:145], v[184:187], v[40:43]
	v_mfma_f32_16x16x32_bf16 v[40:43], v[138:141], v[170:173], v[40:43]
	v_mfma_f32_16x16x32_bf16 v[24:27], v[138:141], v[190:193], v[24:27]
	v_mfma_f32_16x16x32_bf16 v[24:27], v[142:145], v[196:199], v[24:27]
	v_mfma_f32_16x16x32_bf16 v[8:11], v[142:145], v[212:215], v[8:11]
	v_mfma_f32_16x16x32_bf16 v[8:11], v[138:141], v[204:207], v[8:11]
	v_mfma_f32_16x16x32_bf16 v[52:55], v[146:149], v[162:165], v[52:55]
	v_mfma_f32_16x16x32_bf16 v[52:55], v[150:153], v[166:169], v[52:55]
	v_mfma_f32_16x16x32_bf16 v[36:39], v[150:153], v[184:187], v[36:39]
	v_mfma_f32_16x16x32_bf16 v[36:39], v[146:149], v[170:173], v[36:39]
	v_mfma_f32_16x16x32_bf16 v[20:23], v[146:149], v[190:193], v[20:23]
	v_mfma_f32_16x16x32_bf16 v[20:23], v[150:153], v[196:199], v[20:23]
	v_mfma_f32_16x16x32_bf16 v[4:7], v[150:153], v[212:215], v[4:7]
	v_mfma_f32_16x16x32_bf16 v[4:7], v[146:149], v[204:207], v[4:7]
	v_mfma_f32_16x16x32_bf16 v[48:51], v[154:157], v[162:165], v[48:51]
	v_mfma_f32_16x16x32_bf16 v[48:51], v[158:161], v[166:169], v[48:51]
	v_mfma_f32_16x16x32_bf16 v[32:35], v[158:161], v[184:187], v[32:35]
	v_mfma_f32_16x16x32_bf16 v[32:35], v[154:157], v[170:173], v[32:35]
	s_setprio 2
	s_barrier
	v_mfma_f32_16x16x32_bf16 v[16:19], v[154:157], v[190:193], v[16:19]
	v_mfma_f32_16x16x32_bf16 v[16:19], v[158:161], v[196:199], v[16:19]
	v_mfma_f32_16x16x32_bf16 v[0:3], v[158:161], v[212:215], v[0:3]
	v_mfma_f32_16x16x32_bf16 v[0:3], v[154:157], v[204:207], v[0:3]
	s_setprio 0
	s_add_i32 s70, s70, 1
	s_add_u32 s44, s44, 0x100
	s_addc_u32 s45, s45, 0
	s_add_u32 s83, s83, 0x100
	s_addc_u32 s84, s84, 0
	s_cmp_gt_u32 s85, 29
	s_cbranch_scc0 .LBB0_698
	s_lshl_b32 s29, s41, 12
	s_and_b32 s29, s29, 0x1000
	s_add_i32 s29, s29, 0
	v_mbcnt_lo_u32_b32 v128, -1, 0
	v_mbcnt_hi_u32_b32 v128, -1, v128
	s_add_i32 s29, s29, s63
	v_lshlrev_b32_e32 v128, 4, v128
	s_add_i32 s29, s29, 0x20400
	v_and_b32_e32 v128, 0xf0, v128
	v_add_u32_e32 v128, s29, v128
	ds_read2_b32 v[214:215], v128 offset0:3 offset1:67
	ds_read2_b32 v[206:207], v128 offset0:131 offset1:195
	v_add_u32_e32 v128, 12, v128
	ds_read2st64_b32 v[196:197], v128 offset0:8 offset1:9
	ds_read2st64_b32 v[190:191], v128 offset0:10 offset1:11
	s_and_b64 vcc, exec, s[22:23]
	s_waitcnt lgkmcnt(0)
	v_mov_b32_e32 v210, v215
	v_mov_b32_e32 v202, v207
	v_mov_b32_e32 v194, v197
	v_mov_b32_e32 v188, v191
	s_cbranch_vccz .LBB0_703
	s_barrier

.LBB0_783:
	s_ashr_i32 s23, s22, 31
	s_lshl_b64 s[26:27], s[22:23], 19
	s_add_u32 s26, s43, s26
	s_addc_u32 s27, s44, s27
	s_and_b64 s[28:29], s[4:5], exec
	s_cselect_b32 s23, s27, s37
	s_cselect_b32 s31, s26, s36
	s_ashr_i32 s25, s24, 31
	s_lshl_b64 s[28:29], s[24:25], 19
	s_add_u32 s28, s45, s28
	s_addc_u32 s29, s46, s29
	s_and_b64 s[40:41], s[4:5], exec
	s_cselect_b32 s25, s29, s39
	s_cselect_b32 s62, s28, s38
	s_add_u32 s36, s36, 0x40080
	s_addc_u32 s37, s37, 0
	s_add_u32 s63, s38, 0x100
	s_addc_u32 s64, s39, 0
	s_mov_b32 s65, -2
	ds_read_b128 v[144:147], v163
	ds_read_b128 v[148:151], v163 offset:1024
	ds_read_b128 v[152:155], v163 offset:2048
	ds_read_b128 v[156:159], v163 offset:3072
	ds_read_b128 v[168:171], v164
	ds_read_b128 v[172:175], v164 offset:1024
	ds_read_b128 v[176:179], v164 offset:2048
	ds_read_b128 v[180:183], v164 offset:3072
	s_add_u32 s38, s36, 0xfffc0080
	s_addc_u32 s39, s37, -1
	s_cmp_eq_u32 s65, 12
	s_cselect_b32 s41, s23, s39
	s_cselect_b32 s40, s31, s38
	s_cselect_b32 s39, s25, s64
	s_cselect_b32 s38, s62, s63
	v_lshl_add_u64 v[160:161], s[36:37], 0, v[136:137]
	s_add_i32 m0, s50, 0xc000
	ds_read_b128 v[184:187], v165
	ds_read_b128 v[188:191], v165 offset:1024
	ds_read_b128 v[192:195], v165 offset:2048
	ds_read_b128 v[196:199], v165 offset:3072
	ds_read_b128 v[200:203], v165 offset:4096
	ds_read_b128 v[204:207], v165 offset:5120
	ds_read_b128 v[208:211], v165 offset:6144
	ds_read_b128 v[212:215], v165 offset:7168
	global_load_lds_dwordx4 v[160:161], off
	s_add_i32 m0, s50, 0xe000
	v_lshl_add_u64 v[160:161], s[36:37], 0, v[138:139]
	global_load_lds_dwordx4 v[160:161], off
	s_waitcnt vmcnt(8) lgkmcnt(0)
	s_barrier
	s_setprio 1
	v_mfma_f32_16x16x32_bf16 v[124:127], v[144:147], v[184:187], 0
	v_mfma_f32_16x16x32_bf16 v[124:127], v[148:151], v[188:191], v[124:127]
	v_mfma_f32_16x16x32_bf16 v[108:111], v[148:151], v[196:199], 0
	v_mfma_f32_16x16x32_bf16 v[108:111], v[144:147], v[192:195], v[108:111]
	v_mfma_f32_16x16x32_bf16 v[92:95], v[144:147], v[200:203], 0
	v_mfma_f32_16x16x32_bf16 v[92:95], v[148:151], v[204:207], v[92:95]
	v_mfma_f32_16x16x32_bf16 v[76:79], v[148:151], v[212:215], 0
	v_mfma_f32_16x16x32_bf16 v[76:79], v[144:147], v[208:211], v[76:79]
	v_mfma_f32_16x16x32_bf16 v[120:123], v[152:155], v[184:187], 0
	v_mfma_f32_16x16x32_bf16 v[120:123], v[156:159], v[188:191], v[120:123]
	v_mfma_f32_16x16x32_bf16 v[104:107], v[156:159], v[196:199], 0
	v_mfma_f32_16x16x32_bf16 v[104:107], v[152:155], v[192:195], v[104:107]
	v_mfma_f32_16x16x32_bf16 v[88:91], v[152:155], v[200:203], 0
	v_mfma_f32_16x16x32_bf16 v[88:91], v[156:159], v[204:207], v[88:91]
	v_mfma_f32_16x16x32_bf16 v[72:75], v[156:159], v[212:215], 0
	v_mfma_f32_16x16x32_bf16 v[72:75], v[152:155], v[208:211], v[72:75]
	v_mfma_f32_16x16x32_bf16 v[116:119], v[168:171], v[184:187], 0
	v_mfma_f32_16x16x32_bf16 v[116:119], v[172:175], v[188:191], v[116:119]
	v_mfma_f32_16x16x32_bf16 v[100:103], v[172:175], v[196:199], 0
	v_mfma_f32_16x16x32_bf16 v[100:103], v[168:171], v[192:195], v[100:103]
	v_mfma_f32_16x16x32_bf16 v[84:87], v[168:171], v[200:203], 0
	v_mfma_f32_16x16x32_bf16 v[84:87], v[172:175], v[204:207], v[84:87]
	v_mfma_f32_16x16x32_bf16 v[68:71], v[172:175], v[212:215], 0
	v_mfma_f32_16x16x32_bf16 v[68:71], v[168:171], v[208:211], v[68:71]
	v_mfma_f32_16x16x32_bf16 v[112:115], v[176:179], v[184:187], 0
	v_mfma_f32_16x16x32_bf16 v[112:115], v[180:183], v[188:191], v[112:115]
	v_mfma_f32_16x16x32_bf16 v[96:99], v[180:183], v[196:199], 0
	v_mfma_f32_16x16x32_bf16 v[96:99], v[176:179], v[192:195], v[96:99]
	s_setprio 2
	s_barrier
	v_mfma_f32_16x16x32_bf16 v[80:83], v[176:179], v[200:203], 0
	v_mfma_f32_16x16x32_bf16 v[80:83], v[180:183], v[204:207], v[80:83]
	v_mfma_f32_16x16x32_bf16 v[64:67], v[180:183], v[212:215], 0
	v_mfma_f32_16x16x32_bf16 v[64:67], v[176:179], v[208:211], v[64:67]
	s_setprio 2
	s_add_i32 s66, s59, s47
	v_lshl_add_u64 v[160:161], s[38:39], 0, v[132:133]
	s_mov_b32 m0, s66
	ds_read_b128 v[184:187], v165 offset:16384
	ds_read_b128 v[188:191], v165 offset:17408
	ds_read_b128 v[192:195], v165 offset:18432
	ds_read_b128 v[196:199], v165 offset:19456
	ds_read_b128 v[200:203], v165 offset:20480
	ds_read_b128 v[204:207], v165 offset:21504
	ds_read_b128 v[208:211], v165 offset:22528
	ds_read_b128 v[212:215], v165 offset:23552
	global_load_lds_dwordx4 v[160:161], off
	s_add_i32 m0, s66, 0x2000
	s_add_u32 s66, s38, 0x40000
	v_lshl_add_u64 v[216:217], s[38:39], 0, v[128:129]
	s_addc_u32 s67, s39, 0
	s_add_i32 s68, s60, s47
	global_load_lds_dwordx4 v[216:217], off
	v_lshl_add_u64 v[218:219], s[66:67], 0, v[132:133]
	s_mov_b32 m0, s68
	v_lshl_add_u64 v[220:221], s[40:41], 0, v[130:131]
	global_load_lds_dwordx4 v[218:219], off
	s_add_i32 m0, s68, 0x2000
	v_lshl_add_u64 v[218:219], s[66:67], 0, v[128:129]
	global_load_lds_dwordx4 v[218:219], off
	s_mov_b32 m0, s50
	v_lshl_add_u64 v[218:219], s[40:41], 0, v[134:135]
	global_load_lds_dwordx4 v[218:219], off
	s_mov_b32 m0, s51
	s_nop 0
	global_load_lds_dwordx4 v[220:221], off
	s_waitcnt vmcnt(8) lgkmcnt(0)
	s_barrier
	s_setprio 1
	v_mfma_f32_16x16x32_bf16 v[60:63], v[144:147], v[184:187], 0
	v_mfma_f32_16x16x32_bf16 v[60:63], v[148:151], v[188:191], v[60:63]
	v_mfma_f32_16x16x32_bf16 v[44:47], v[148:151], v[196:199], 0
	v_mfma_f32_16x16x32_bf16 v[44:47], v[144:147], v[192:195], v[44:47]
	v_mfma_f32_16x16x32_bf16 v[28:31], v[144:147], v[200:203], 0
	v_mfma_f32_16x16x32_bf16 v[28:31], v[148:151], v[204:207], v[28:31]
	v_mfma_f32_16x16x32_bf16 v[12:15], v[148:151], v[212:215], 0
	v_mfma_f32_16x16x32_bf16 v[12:15], v[144:147], v[208:211], v[12:15]
	v_mfma_f32_16x16x32_bf16 v[56:59], v[152:155], v[184:187], 0
	v_mfma_f32_16x16x32_bf16 v[56:59], v[156:159], v[188:191], v[56:59]
	v_mfma_f32_16x16x32_bf16 v[40:43], v[156:159], v[196:199], 0
	v_mfma_f32_16x16x32_bf16 v[40:43], v[152:155], v[192:195], v[40:43]
	v_mfma_f32_16x16x32_bf16 v[24:27], v[152:155], v[200:203], 0
	v_mfma_f32_16x16x32_bf16 v[24:27], v[156:159], v[204:207], v[24:27]
	v_mfma_f32_16x16x32_bf16 v[8:11], v[156:159], v[212:215], 0
	v_mfma_f32_16x16x32_bf16 v[8:11], v[152:155], v[208:211], v[8:11]
	v_mfma_f32_16x16x32_bf16 v[52:55], v[168:171], v[184:187], 0
	v_mfma_f32_16x16x32_bf16 v[52:55], v[172:175], v[188:191], v[52:55]
	v_mfma_f32_16x16x32_bf16 v[36:39], v[172:175], v[196:199], 0
	v_mfma_f32_16x16x32_bf16 v[36:39], v[168:171], v[192:195], v[36:39]
	v_mfma_f32_16x16x32_bf16 v[20:23], v[168:171], v[200:203], 0
	v_mfma_f32_16x16x32_bf16 v[20:23], v[172:175], v[204:207], v[20:23]
	v_mfma_f32_16x16x32_bf16 v[4:7], v[172:175], v[212:215], 0
	v_mfma_f32_16x16x32_bf16 v[4:7], v[168:171], v[208:211], v[4:7]
	v_mfma_f32_16x16x32_bf16 v[48:51], v[176:179], v[184:187], 0
	v_mfma_f32_16x16x32_bf16 v[48:51], v[180:183], v[188:191], v[48:51]
	v_mfma_f32_16x16x32_bf16 v[32:35], v[180:183], v[196:199], 0
	v_mfma_f32_16x16x32_bf16 v[32:35], v[176:179], v[192:195], v[32:35]
	s_setprio 2
	s_barrier
	v_mfma_f32_16x16x32_bf16 v[16:19], v[176:179], v[200:203], 0
	v_mfma_f32_16x16x32_bf16 v[16:19], v[180:183], v[204:207], v[16:19]
	v_mfma_f32_16x16x32_bf16 v[0:3], v[180:183], v[212:215], 0
	v_mfma_f32_16x16x32_bf16 v[0:3], v[176:179], v[208:211], v[0:3]
	s_setprio 0
	s_add_i32 s66, 0, 0x18000
	s_add_i32 s67, 0, 0x1c000
	v_add_u32_e32 v156, s66, v162
	v_add_u32_e32 v167, s67, v162
	ds_read_b128 v[144:147], v156
	ds_read_b128 v[148:151], v156 offset:1024
	ds_read_b128 v[152:155], v156 offset:2048
	ds_read_b128 v[156:159], v156 offset:3072
	ds_read_b128 v[168:171], v167
	ds_read_b128 v[172:175], v167 offset:1024
	ds_read_b128 v[176:179], v167 offset:2048
	ds_read_b128 v[180:183], v167 offset:3072
	s_add_u32 s40, s40, 0x40000
	s_addc_u32 s41, s41, 0
	s_mov_b32 m0, s54
	v_lshl_add_u64 v[222:223], s[40:41], 0, v[134:135]
	ds_read_b128 v[184:187], v165 offset:32768
	ds_read_b128 v[188:191], v165 offset:33792
	ds_read_b128 v[192:195], v165 offset:34816
	ds_read_b128 v[196:199], v165 offset:35840
	ds_read_b128 v[200:203], v165 offset:36864
	ds_read_b128 v[204:207], v165 offset:37888
	ds_read_b128 v[208:211], v165 offset:38912
	ds_read_b128 v[212:215], v165 offset:39936
	global_load_lds_dwordx4 v[222:223], off
	s_mov_b32 m0, s55
	v_lshl_add_u64 v[222:223], s[40:41], 0, v[130:131]
	global_load_lds_dwordx4 v[222:223], off
	s_waitcnt vmcnt(8) lgkmcnt(0)
	s_barrier
	s_setprio 1
	v_mfma_f32_16x16x32_bf16 v[124:127], v[144:147], v[184:187], v[124:127]
	v_mfma_f32_16x16x32_bf16 v[124:127], v[148:151], v[188:191], v[124:127]
	v_mfma_f32_16x16x32_bf16 v[108:111], v[148:151], v[196:199], v[108:111]
	v_mfma_f32_16x16x32_bf16 v[108:111], v[144:147], v[192:195], v[108:111]
	v_mfma_f32_16x16x32_bf16 v[92:95], v[144:147], v[200:203], v[92:95]
	v_mfma_f32_16x16x32_bf16 v[92:95], v[148:151], v[204:207], v[92:95]
	v_mfma_f32_16x16x32_bf16 v[76:79], v[148:151], v[212:215], v[76:79]
	v_mfma_f32_16x16x32_bf16 v[76:79], v[144:147], v[208:211], v[76:79]
	v_mfma_f32_16x16x32_bf16 v[120:123], v[152:155], v[184:187], v[120:123]
	v_mfma_f32_16x16x32_bf16 v[120:123], v[156:159], v[188:191], v[120:123]
	v_mfma_f32_16x16x32_bf16 v[104:107], v[156:159], v[196:199], v[104:107]
	v_mfma_f32_16x16x32_bf16 v[104:107], v[152:155], v[192:195], v[104:107]
	v_mfma_f32_16x16x32_bf16 v[88:91], v[152:155], v[200:203], v[88:91]
	v_mfma_f32_16x16x32_bf16 v[88:91], v[156:159], v[204:207], v[88:91]
	v_mfma_f32_16x16x32_bf16 v[72:75], v[156:159], v[212:215], v[72:75]
	v_mfma_f32_16x16x32_bf16 v[72:75], v[152:155], v[208:211], v[72:75]
	v_mfma_f32_16x16x32_bf16 v[116:119], v[168:171], v[184:187], v[116:119]
	v_mfma_f32_16x16x32_bf16 v[116:119], v[172:175], v[188:191], v[116:119]
	v_mfma_f32_16x16x32_bf16 v[100:103], v[172:175], v[196:199], v[100:103]
	v_mfma_f32_16x16x32_bf16 v[100:103], v[168:171], v[192:195], v[100:103]
	v_mfma_f32_16x16x32_bf16 v[84:87], v[168:171], v[200:203], v[84:87]
	v_mfma_f32_16x16x32_bf16 v[84:87], v[172:175], v[204:207], v[84:87]
	v_mfma_f32_16x16x32_bf16 v[68:71], v[172:175], v[212:215], v[68:71]
	v_mfma_f32_16x16x32_bf16 v[68:71], v[168:171], v[208:211], v[68:71]
	v_mfma_f32_16x16x32_bf16 v[112:115], v[176:179], v[184:187], v[112:115]
	v_mfma_f32_16x16x32_bf16 v[112:115], v[180:183], v[188:191], v[112:115]
	v_mfma_f32_16x16x32_bf16 v[96:99], v[180:183], v[196:199], v[96:99]
	v_mfma_f32_16x16x32_bf16 v[96:99], v[176:179], v[192:195], v[96:99]
	s_setprio 2
	s_barrier
	v_mfma_f32_16x16x32_bf16 v[80:83], v[176:179], v[200:203], v[80:83]
	v_mfma_f32_16x16x32_bf16 v[80:83], v[180:183], v[204:207], v[80:83]
	v_mfma_f32_16x16x32_bf16 v[64:67], v[180:183], v[212:215], v[64:67]
	v_mfma_f32_16x16x32_bf16 v[64:67], v[176:179], v[208:211], v[64:67]
	s_setprio 2
	s_add_i32 s40, s66, s47
	v_lshl_add_u64 v[160:161], v[160:161], 0, s[16:17]
	s_mov_b32 m0, s40
	ds_read_b128 v[184:187], v165 offset:49152
	ds_read_b128 v[188:191], v165 offset:50176
	ds_read_b128 v[192:195], v165 offset:51200
	ds_read_b128 v[196:199], v165 offset:52224
	ds_read_b128 v[200:203], v165 offset:53248
	ds_read_b128 v[204:207], v165 offset:54272
	ds_read_b128 v[208:211], v165 offset:55296
	ds_read_b128 v[212:215], v165 offset:56320
	global_load_lds_dwordx4 v[160:161], off
	s_add_i32 m0, s40, 0x2000
	s_add_u32 s38, s38, 0x40080
	v_lshl_add_u64 v[160:161], v[216:217], 0, s[16:17]
	s_addc_u32 s39, s39, 0
	s_add_i32 s40, s67, s47
	global_load_lds_dwordx4 v[160:161], off
	s_mov_b32 m0, s40
	v_lshl_add_u64 v[160:161], s[38:39], 0, v[132:133]
	global_load_lds_dwordx4 v[160:161], off
	s_add_i32 m0, s40, 0x2000
	v_lshl_add_u64 v[160:161], s[38:39], 0, v[128:129]
	global_load_lds_dwordx4 v[160:161], off
	s_mov_b32 m0, s57
	v_lshl_add_u64 v[160:161], v[218:219], 0, s[16:17]
	global_load_lds_dwordx4 v[160:161], off
	s_mov_b32 m0, s58
	v_lshl_add_u64 v[160:161], v[220:221], 0, s[16:17]
	global_load_lds_dwordx4 v[160:161], off
	s_waitcnt vmcnt(8) lgkmcnt(0)
	s_barrier
	s_setprio 1
	v_mfma_f32_16x16x32_bf16 v[60:63], v[144:147], v[184:187], v[60:63]
	v_mfma_f32_16x16x32_bf16 v[60:63], v[148:151], v[188:191], v[60:63]
	v_mfma_f32_16x16x32_bf16 v[44:47], v[148:151], v[196:199], v[44:47]
	v_mfma_f32_16x16x32_bf16 v[44:47], v[144:147], v[192:195], v[44:47]
	v_mfma_f32_16x16x32_bf16 v[28:31], v[144:147], v[200:203], v[28:31]
	v_mfma_f32_16x16x32_bf16 v[28:31], v[148:151], v[204:207], v[28:31]
	v_mfma_f32_16x16x32_bf16 v[12:15], v[148:151], v[212:215], v[12:15]
	v_mfma_f32_16x16x32_bf16 v[12:15], v[144:147], v[208:211], v[12:15]
	v_mfma_f32_16x16x32_bf16 v[56:59], v[152:155], v[184:187], v[56:59]
	v_mfma_f32_16x16x32_bf16 v[56:59], v[156:159], v[188:191], v[56:59]
	v_mfma_f32_16x16x32_bf16 v[40:43], v[156:159], v[196:199], v[40:43]
	v_mfma_f32_16x16x32_bf16 v[40:43], v[152:155], v[192:195], v[40:43]
	v_mfma_f32_16x16x32_bf16 v[24:27], v[152:155], v[200:203], v[24:27]
	v_mfma_f32_16x16x32_bf16 v[24:27], v[156:159], v[204:207], v[24:27]
	v_mfma_f32_16x16x32_bf16 v[8:11], v[156:159], v[212:215], v[8:11]
	v_mfma_f32_16x16x32_bf16 v[8:11], v[152:155], v[208:211], v[8:11]
	v_mfma_f32_16x16x32_bf16 v[52:55], v[168:171], v[184:187], v[52:55]
	v_mfma_f32_16x16x32_bf16 v[52:55], v[172:175], v[188:191], v[52:55]
	v_mfma_f32_16x16x32_bf16 v[36:39], v[172:175], v[196:199], v[36:39]
	v_mfma_f32_16x16x32_bf16 v[36:39], v[168:171], v[192:195], v[36:39]
	v_mfma_f32_16x16x32_bf16 v[20:23], v[168:171], v[200:203], v[20:23]
	v_mfma_f32_16x16x32_bf16 v[20:23], v[172:175], v[204:207], v[20:23]
	v_mfma_f32_16x16x32_bf16 v[4:7], v[172:175], v[212:215], v[4:7]
	v_mfma_f32_16x16x32_bf16 v[4:7], v[168:171], v[208:211], v[4:7]
	v_mfma_f32_16x16x32_bf16 v[48:51], v[176:179], v[184:187], v[48:51]
	v_mfma_f32_16x16x32_bf16 v[48:51], v[180:183], v[188:191], v[48:51]
	v_mfma_f32_16x16x32_bf16 v[32:35], v[180:183], v[196:199], v[32:35]
	v_mfma_f32_16x16x32_bf16 v[32:35], v[176:179], v[192:195], v[32:35]
	s_setprio 2
	s_barrier
	v_mfma_f32_16x16x32_bf16 v[16:19], v[176:179], v[200:203], v[16:19]
	v_mfma_f32_16x16x32_bf16 v[16:19], v[180:183], v[204:207], v[16:19]
	v_mfma_f32_16x16x32_bf16 v[0:3], v[180:183], v[212:215], v[0:3]
	v_mfma_f32_16x16x32_bf16 v[0:3], v[176:179], v[208:211], v[0:3]
	s_setprio 0
	s_add_i32 s65, s65, 2
	s_add_u32 s36, s36, 0x100
	s_addc_u32 s37, s37, 0
	s_add_u32 s63, s63, 0x100
	s_addc_u32 s64, s64, 0
	s_cmp_gt_u32 s65, 13
.LBB0_784:
	ds_read_b128 v[144:147], v163
	ds_read_b128 v[148:151], v163 offset:1024
	ds_read_b128 v[152:155], v163 offset:2048
	ds_read_b128 v[156:159], v163 offset:3072
	ds_read_b128 v[168:171], v164
	ds_read_b128 v[172:175], v164 offset:1024
	ds_read_b128 v[176:179], v164 offset:2048
	ds_read_b128 v[180:183], v164 offset:3072
	s_add_u32 s38, s36, 0xfffc0080
	s_addc_u32 s39, s37, -1
	s_cmp_eq_u32 s65, 12
	s_cselect_b32 s41, s23, s39
	s_cselect_b32 s40, s31, s38
	s_cselect_b32 s39, s25, s64
	s_cselect_b32 s38, s62, s63
	v_lshl_add_u64 v[160:161], s[36:37], 0, v[136:137]
	s_add_i32 m0, s50, 0xc000
	ds_read_b128 v[184:187], v165
	ds_read_b128 v[188:191], v165 offset:1024
	ds_read_b128 v[192:195], v165 offset:2048
	ds_read_b128 v[196:199], v165 offset:3072
	ds_read_b128 v[200:203], v165 offset:4096
	ds_read_b128 v[204:207], v165 offset:5120
	ds_read_b128 v[208:211], v165 offset:6144
	ds_read_b128 v[212:215], v165 offset:7168
	global_load_lds_dwordx4 v[160:161], off
	s_add_i32 m0, s50, 0xe000
	v_lshl_add_u64 v[160:161], s[36:37], 0, v[138:139]
	global_load_lds_dwordx4 v[160:161], off
	s_waitcnt vmcnt(8) lgkmcnt(0)
	s_barrier
	s_setprio 1
	v_mfma_f32_16x16x32_bf16 v[124:127], v[144:147], v[184:187], v[124:127]
	v_mfma_f32_16x16x32_bf16 v[124:127], v[148:151], v[188:191], v[124:127]
	v_mfma_f32_16x16x32_bf16 v[108:111], v[148:151], v[196:199], v[108:111]
	v_mfma_f32_16x16x32_bf16 v[108:111], v[144:147], v[192:195], v[108:111]
	v_mfma_f32_16x16x32_bf16 v[92:95], v[144:147], v[200:203], v[92:95]
	v_mfma_f32_16x16x32_bf16 v[92:95], v[148:151], v[204:207], v[92:95]
	v_mfma_f32_16x16x32_bf16 v[76:79], v[148:151], v[212:215], v[76:79]
	v_mfma_f32_16x16x32_bf16 v[76:79], v[144:147], v[208:211], v[76:79]
	v_mfma_f32_16x16x32_bf16 v[120:123], v[152:155], v[184:187], v[120:123]
	v_mfma_f32_16x16x32_bf16 v[120:123], v[156:159], v[188:191], v[120:123]
	v_mfma_f32_16x16x32_bf16 v[104:107], v[156:159], v[196:199], v[104:107]
	v_mfma_f32_16x16x32_bf16 v[104:107], v[152:155], v[192:195], v[104:107]
	v_mfma_f32_16x16x32_bf16 v[88:91], v[152:155], v[200:203], v[88:91]
	v_mfma_f32_16x16x32_bf16 v[88:91], v[156:159], v[204:207], v[88:91]
	v_mfma_f32_16x16x32_bf16 v[72:75], v[156:159], v[212:215], v[72:75]
	v_mfma_f32_16x16x32_bf16 v[72:75], v[152:155], v[208:211], v[72:75]
	v_mfma_f32_16x16x32_bf16 v[116:119], v[168:171], v[184:187], v[116:119]
	v_mfma_f32_16x16x32_bf16 v[116:119], v[172:175], v[188:191], v[116:119]
	v_mfma_f32_16x16x32_bf16 v[100:103], v[172:175], v[196:199], v[100:103]
	v_mfma_f32_16x16x32_bf16 v[100:103], v[168:171], v[192:195], v[100:103]
	v_mfma_f32_16x16x32_bf16 v[84:87], v[168:171], v[200:203], v[84:87]
	v_mfma_f32_16x16x32_bf16 v[84:87], v[172:175], v[204:207], v[84:87]
	v_mfma_f32_16x16x32_bf16 v[68:71], v[172:175], v[212:215], v[68:71]
	v_mfma_f32_16x16x32_bf16 v[68:71], v[168:171], v[208:211], v[68:71]
	v_mfma_f32_16x16x32_bf16 v[112:115], v[176:179], v[184:187], v[112:115]
	v_mfma_f32_16x16x32_bf16 v[112:115], v[180:183], v[188:191], v[112:115]
	v_mfma_f32_16x16x32_bf16 v[96:99], v[180:183], v[196:199], v[96:99]
	v_mfma_f32_16x16x32_bf16 v[96:99], v[176:179], v[192:195], v[96:99]
	s_setprio 2
	s_barrier
	v_mfma_f32_16x16x32_bf16 v[80:83], v[176:179], v[200:203], v[80:83]
	v_mfma_f32_16x16x32_bf16 v[80:83], v[180:183], v[204:207], v[80:83]
	v_mfma_f32_16x16x32_bf16 v[64:67], v[180:183], v[212:215], v[64:67]
	v_mfma_f32_16x16x32_bf16 v[64:67], v[176:179], v[208:211], v[64:67]
	s_setprio 2
	s_add_i32 s66, s59, s47
	v_lshl_add_u64 v[160:161], s[38:39], 0, v[132:133]
	s_mov_b32 m0, s66
	ds_read_b128 v[184:187], v165 offset:16384
	ds_read_b128 v[188:191], v165 offset:17408
	ds_read_b128 v[192:195], v165 offset:18432
	ds_read_b128 v[196:199], v165 offset:19456
	ds_read_b128 v[200:203], v165 offset:20480
	ds_read_b128 v[204:207], v165 offset:21504
	ds_read_b128 v[208:211], v165 offset:22528
	ds_read_b128 v[212:215], v165 offset:23552
	global_load_lds_dwordx4 v[160:161], off
	s_add_i32 m0, s66, 0x2000
	s_add_u32 s66, s38, 0x40000
	v_lshl_add_u64 v[216:217], s[38:39], 0, v[128:129]
	s_addc_u32 s67, s39, 0
	s_add_i32 s68, s60, s47
	global_load_lds_dwordx4 v[216:217], off
	v_lshl_add_u64 v[218:219], s[66:67], 0, v[132:133]
	s_mov_b32 m0, s68
	v_lshl_add_u64 v[220:221], s[40:41], 0, v[130:131]
	global_load_lds_dwordx4 v[218:219], off
	s_add_i32 m0, s68, 0x2000
	v_lshl_add_u64 v[218:219], s[66:67], 0, v[128:129]
	global_load_lds_dwordx4 v[218:219], off
	s_mov_b32 m0, s50
	v_lshl_add_u64 v[218:219], s[40:41], 0, v[134:135]
	global_load_lds_dwordx4 v[218:219], off
	s_mov_b32 m0, s51
	s_nop 0
	global_load_lds_dwordx4 v[220:221], off
	s_waitcnt vmcnt(8) lgkmcnt(0)
	s_barrier
	s_setprio 1
	v_mfma_f32_16x16x32_bf16 v[60:63], v[144:147], v[184:187], v[60:63]
	v_mfma_f32_16x16x32_bf16 v[60:63], v[148:151], v[188:191], v[60:63]
	v_mfma_f32_16x16x32_bf16 v[44:47], v[148:151], v[196:199], v[44:47]
	v_mfma_f32_16x16x32_bf16 v[44:47], v[144:147], v[192:195], v[44:47]
	v_mfma_f32_16x16x32_bf16 v[28:31], v[144:147], v[200:203], v[28:31]
	v_mfma_f32_16x16x32_bf16 v[28:31], v[148:151], v[204:207], v[28:31]
	v_mfma_f32_16x16x32_bf16 v[12:15], v[148:151], v[212:215], v[12:15]
	v_mfma_f32_16x16x32_bf16 v[12:15], v[144:147], v[208:211], v[12:15]
	v_mfma_f32_16x16x32_bf16 v[56:59], v[152:155], v[184:187], v[56:59]
	v_mfma_f32_16x16x32_bf16 v[56:59], v[156:159], v[188:191], v[56:59]
	v_mfma_f32_16x16x32_bf16 v[40:43], v[156:159], v[196:199], v[40:43]
	v_mfma_f32_16x16x32_bf16 v[40:43], v[152:155], v[192:195], v[40:43]
	v_mfma_f32_16x16x32_bf16 v[24:27], v[152:155], v[200:203], v[24:27]
	v_mfma_f32_16x16x32_bf16 v[24:27], v[156:159], v[204:207], v[24:27]
	v_mfma_f32_16x16x32_bf16 v[8:11], v[156:159], v[212:215], v[8:11]
	v_mfma_f32_16x16x32_bf16 v[8:11], v[152:155], v[208:211], v[8:11]
	v_mfma_f32_16x16x32_bf16 v[52:55], v[168:171], v[184:187], v[52:55]
	v_mfma_f32_16x16x32_bf16 v[52:55], v[172:175], v[188:191], v[52:55]
	v_mfma_f32_16x16x32_bf16 v[36:39], v[172:175], v[196:199], v[36:39]
	v_mfma_f32_16x16x32_bf16 v[36:39], v[168:171], v[192:195], v[36:39]
	v_mfma_f32_16x16x32_bf16 v[20:23], v[168:171], v[200:203], v[20:23]
	v_mfma_f32_16x16x32_bf16 v[20:23], v[172:175], v[204:207], v[20:23]
	v_mfma_f32_16x16x32_bf16 v[4:7], v[172:175], v[212:215], v[4:7]
	v_mfma_f32_16x16x32_bf16 v[4:7], v[168:171], v[208:211], v[4:7]
	v_mfma_f32_16x16x32_bf16 v[48:51], v[176:179], v[184:187], v[48:51]
	v_mfma_f32_16x16x32_bf16 v[48:51], v[180:183], v[188:191], v[48:51]
	v_mfma_f32_16x16x32_bf16 v[32:35], v[180:183], v[196:199], v[32:35]
	v_mfma_f32_16x16x32_bf16 v[32:35], v[176:179], v[192:195], v[32:35]
	s_setprio 2
	s_barrier
	v_mfma_f32_16x16x32_bf16 v[16:19], v[176:179], v[200:203], v[16:19]
	v_mfma_f32_16x16x32_bf16 v[16:19], v[180:183], v[204:207], v[16:19]
	v_mfma_f32_16x16x32_bf16 v[0:3], v[180:183], v[212:215], v[0:3]
	v_mfma_f32_16x16x32_bf16 v[0:3], v[176:179], v[208:211], v[0:3]
	s_setprio 0
	s_add_i32 s66, 0, 0x18000
	s_add_i32 s67, 0, 0x1c000
	v_add_u32_e32 v156, s66, v162
	v_add_u32_e32 v167, s67, v162
	ds_read_b128 v[144:147], v156
	ds_read_b128 v[148:151], v156 offset:1024
	ds_read_b128 v[152:155], v156 offset:2048
	ds_read_b128 v[156:159], v156 offset:3072
	ds_read_b128 v[168:171], v167
	ds_read_b128 v[172:175], v167 offset:1024
	ds_read_b128 v[176:179], v167 offset:2048
	ds_read_b128 v[180:183], v167 offset:3072
	s_add_u32 s40, s40, 0x40000
	s_addc_u32 s41, s41, 0
	s_mov_b32 m0, s54
	v_lshl_add_u64 v[222:223], s[40:41], 0, v[134:135]
	ds_read_b128 v[184:187], v165 offset:32768
	ds_read_b128 v[188:191], v165 offset:33792
	ds_read_b128 v[192:195], v165 offset:34816
	ds_read_b128 v[196:199], v165 offset:35840
	ds_read_b128 v[200:203], v165 offset:36864
	ds_read_b128 v[204:207], v165 offset:37888
	ds_read_b128 v[208:211], v165 offset:38912
	ds_read_b128 v[212:215], v165 offset:39936
	global_load_lds_dwordx4 v[222:223], off
	s_mov_b32 m0, s55
	v_lshl_add_u64 v[222:223], s[40:41], 0, v[130:131]
	global_load_lds_dwordx4 v[222:223], off
	s_waitcnt vmcnt(8) lgkmcnt(0)
	s_barrier
	s_setprio 1
	v_mfma_f32_16x16x32_bf16 v[124:127], v[144:147], v[184:187], v[124:127]
	v_mfma_f32_16x16x32_bf16 v[124:127], v[148:151], v[188:191], v[124:127]
	v_mfma_f32_16x16x32_bf16 v[108:111], v[148:151], v[196:199], v[108:111]
	v_mfma_f32_16x16x32_bf16 v[108:111], v[144:147], v[192:195], v[108:111]
	v_mfma_f32_16x16x32_bf16 v[92:95], v[144:147], v[200:203], v[92:95]
	v_mfma_f32_16x16x32_bf16 v[92:95], v[148:151], v[204:207], v[92:95]
	v_mfma_f32_16x16x32_bf16 v[76:79], v[148:151], v[212:215], v[76:79]
	v_mfma_f32_16x16x32_bf16 v[76:79], v[144:147], v[208:211], v[76:79]
	v_mfma_f32_16x16x32_bf16 v[120:123], v[152:155], v[184:187], v[120:123]
	v_mfma_f32_16x16x32_bf16 v[120:123], v[156:159], v[188:191], v[120:123]
	v_mfma_f32_16x16x32_bf16 v[104:107], v[156:159], v[196:199], v[104:107]
	v_mfma_f32_16x16x32_bf16 v[104:107], v[152:155], v[192:195], v[104:107]
	v_mfma_f32_16x16x32_bf16 v[88:91], v[152:155], v[200:203], v[88:91]
	v_mfma_f32_16x16x32_bf16 v[88:91], v[156:159], v[204:207], v[88:91]
	v_mfma_f32_16x16x32_bf16 v[72:75], v[156:159], v[212:215], v[72:75]
	v_mfma_f32_16x16x32_bf16 v[72:75], v[152:155], v[208:211], v[72:75]
	v_mfma_f32_16x16x32_bf16 v[116:119], v[168:171], v[184:187], v[116:119]
	v_mfma_f32_16x16x32_bf16 v[116:119], v[172:175], v[188:191], v[116:119]
	v_mfma_f32_16x16x32_bf16 v[100:103], v[172:175], v[196:199], v[100:103]
	v_mfma_f32_16x16x32_bf16 v[100:103], v[168:171], v[192:195], v[100:103]
	v_mfma_f32_16x16x32_bf16 v[84:87], v[168:171], v[200:203], v[84:87]
	v_mfma_f32_16x16x32_bf16 v[84:87], v[172:175], v[204:207], v[84:87]
	v_mfma_f32_16x16x32_bf16 v[68:71], v[172:175], v[212:215], v[68:71]
	v_mfma_f32_16x16x32_bf16 v[68:71], v[168:171], v[208:211], v[68:71]
	v_mfma_f32_16x16x32_bf16 v[112:115], v[176:179], v[184:187], v[112:115]
	v_mfma_f32_16x16x32_bf16 v[112:115], v[180:183], v[188:191], v[112:115]
	v_mfma_f32_16x16x32_bf16 v[96:99], v[180:183], v[196:199], v[96:99]
	v_mfma_f32_16x16x32_bf16 v[96:99], v[176:179], v[192:195], v[96:99]
	s_setprio 2
	s_barrier
	v_mfma_f32_16x16x32_bf16 v[80:83], v[176:179], v[200:203], v[80:83]
	v_mfma_f32_16x16x32_bf16 v[80:83], v[180:183], v[204:207], v[80:83]
	v_mfma_f32_16x16x32_bf16 v[64:67], v[180:183], v[212:215], v[64:67]
	v_mfma_f32_16x16x32_bf16 v[64:67], v[176:179], v[208:211], v[64:67]
	s_setprio 2
	s_add_i32 s40, s66, s47
	v_lshl_add_u64 v[160:161], v[160:161], 0, s[16:17]
	s_mov_b32 m0, s40
	ds_read_b128 v[184:187], v165 offset:49152
	ds_read_b128 v[188:191], v165 offset:50176
	ds_read_b128 v[192:195], v165 offset:51200
	ds_read_b128 v[196:199], v165 offset:52224
	ds_read_b128 v[200:203], v165 offset:53248
	ds_read_b128 v[204:207], v165 offset:54272
	ds_read_b128 v[208:211], v165 offset:55296
	ds_read_b128 v[212:215], v165 offset:56320
	global_load_lds_dwordx4 v[160:161], off
	s_add_i32 m0, s40, 0x2000
	s_add_u32 s38, s38, 0x40080
	v_lshl_add_u64 v[160:161], v[216:217], 0, s[16:17]
	s_addc_u32 s39, s39, 0
	s_add_i32 s40, s67, s47
	global_load_lds_dwordx4 v[160:161], off
	s_mov_b32 m0, s40
	v_lshl_add_u64 v[160:161], s[38:39], 0, v[132:133]
	global_load_lds_dwordx4 v[160:161], off
	s_add_i32 m0, s40, 0x2000
	v_lshl_add_u64 v[160:161], s[38:39], 0, v[128:129]
	global_load_lds_dwordx4 v[160:161], off
	s_mov_b32 m0, s57
	v_lshl_add_u64 v[160:161], v[218:219], 0, s[16:17]
	global_load_lds_dwordx4 v[160:161], off
	s_mov_b32 m0, s58
	v_lshl_add_u64 v[160:161], v[220:221], 0, s[16:17]
	global_load_lds_dwordx4 v[160:161], off
	s_waitcnt vmcnt(8) lgkmcnt(0)
	s_barrier
	s_setprio 1
	v_mfma_f32_16x16x32_bf16 v[60:63], v[144:147], v[184:187], v[60:63]
	v_mfma_f32_16x16x32_bf16 v[60:63], v[148:151], v[188:191], v[60:63]
	v_mfma_f32_16x16x32_bf16 v[44:47], v[148:151], v[196:199], v[44:47]
	v_mfma_f32_16x16x32_bf16 v[44:47], v[144:147], v[192:195], v[44:47]
	v_mfma_f32_16x16x32_bf16 v[28:31], v[144:147], v[200:203], v[28:31]
	v_mfma_f32_16x16x32_bf16 v[28:31], v[148:151], v[204:207], v[28:31]
	v_mfma_f32_16x16x32_bf16 v[12:15], v[148:151], v[212:215], v[12:15]
	v_mfma_f32_16x16x32_bf16 v[12:15], v[144:147], v[208:211], v[12:15]
	v_mfma_f32_16x16x32_bf16 v[56:59], v[152:155], v[184:187], v[56:59]
	v_mfma_f32_16x16x32_bf16 v[56:59], v[156:159], v[188:191], v[56:59]
	v_mfma_f32_16x16x32_bf16 v[40:43], v[156:159], v[196:199], v[40:43]
	v_mfma_f32_16x16x32_bf16 v[40:43], v[152:155], v[192:195], v[40:43]
	v_mfma_f32_16x16x32_bf16 v[24:27], v[152:155], v[200:203], v[24:27]
	v_mfma_f32_16x16x32_bf16 v[24:27], v[156:159], v[204:207], v[24:27]
	v_mfma_f32_16x16x32_bf16 v[8:11], v[156:159], v[212:215], v[8:11]
	v_mfma_f32_16x16x32_bf16 v[8:11], v[152:155], v[208:211], v[8:11]
	v_mfma_f32_16x16x32_bf16 v[52:55], v[168:171], v[184:187], v[52:55]
	v_mfma_f32_16x16x32_bf16 v[52:55], v[172:175], v[188:191], v[52:55]
	v_mfma_f32_16x16x32_bf16 v[36:39], v[172:175], v[196:199], v[36:39]
	v_mfma_f32_16x16x32_bf16 v[36:39], v[168:171], v[192:195], v[36:39]
	v_mfma_f32_16x16x32_bf16 v[20:23], v[168:171], v[200:203], v[20:23]
	v_mfma_f32_16x16x32_bf16 v[20:23], v[172:175], v[204:207], v[20:23]
	v_mfma_f32_16x16x32_bf16 v[4:7], v[172:175], v[212:215], v[4:7]
	v_mfma_f32_16x16x32_bf16 v[4:7], v[168:171], v[208:211], v[4:7]
	v_mfma_f32_16x16x32_bf16 v[48:51], v[176:179], v[184:187], v[48:51]
	v_mfma_f32_16x16x32_bf16 v[48:51], v[180:183], v[188:191], v[48:51]
	v_mfma_f32_16x16x32_bf16 v[32:35], v[180:183], v[196:199], v[32:35]
	v_mfma_f32_16x16x32_bf16 v[32:35], v[176:179], v[192:195], v[32:35]
	s_setprio 2
	s_barrier
	v_mfma_f32_16x16x32_bf16 v[16:19], v[176:179], v[200:203], v[16:19]
	v_mfma_f32_16x16x32_bf16 v[16:19], v[180:183], v[204:207], v[16:19]
	v_mfma_f32_16x16x32_bf16 v[0:3], v[180:183], v[212:215], v[0:3]
	v_mfma_f32_16x16x32_bf16 v[0:3], v[176:179], v[208:211], v[0:3]
	s_setprio 0
	s_add_i32 s65, s65, 2
	s_add_u32 s36, s36, 0x100
	s_addc_u32 s37, s37, 0
	s_add_u32 s63, s63, 0x100
	s_addc_u32 s64, s64, 0
	s_cmp_gt_u32 s65, 13
	s_cbranch_scc0 .LBB0_784

.LBB0_865:
	s_add_u32 s62, s28, 0x100
	s_addc_u32 s63, s29, 0
	s_mov_b32 s64, -2
	ds_read_b128 v[120:123], v233
	ds_read_b128 v[124:127], v233 offset:1024
	ds_read_b128 v[136:139], v233 offset:2048
	ds_read_b128 v[140:143], v233 offset:3072
	ds_read_b128 v[144:147], v234
	ds_read_b128 v[148:151], v234 offset:1024
	ds_read_b128 v[152:155], v234 offset:2048
	ds_read_b128 v[156:159], v234 offset:3072
	s_add_u32 s28, s26, 0x100
	s_addc_u32 s29, s27, 0
	s_cmp_eq_u32 s64, 40
	s_cselect_b32 s37, s7, s29
	s_cselect_b32 s36, s6, s28
	s_cselect_b32 s31, s25, s63
	s_cselect_b32 s30, s24, s62
	v_lshl_add_u64 v[208:209], s[26:27], 0, v[192:193]
	s_add_i32 m0, s44, 0xc000
	ds_read_b128 v[160:163], v235
	ds_read_b128 v[164:167], v235 offset:1024
	ds_read_b128 v[168:171], v235 offset:2048
	ds_read_b128 v[172:175], v235 offset:3072
	ds_read_b128 v[176:179], v235 offset:4096
	ds_read_b128 v[180:183], v235 offset:5120
	ds_read_b128 v[200:203], v235 offset:6144
	ds_read_b128 v[204:207], v235 offset:7168
	global_load_lds_dwordx4 v[208:209], off
	s_add_i32 m0, s44, 0xe000
	v_lshl_add_u64 v[208:209], s[26:27], 0, v[194:195]
	global_load_lds_dwordx4 v[208:209], off
	s_waitcnt vmcnt(8) lgkmcnt(0)
	s_barrier
	s_setprio 1
	v_mfma_f32_16x16x32_bf16 v[132:135], v[120:123], v[160:163], 0
	v_mfma_f32_16x16x32_bf16 v[132:135], v[124:127], v[164:167], v[132:135]
	v_mfma_f32_16x16x32_bf16 v[108:111], v[124:127], v[172:175], 0
	v_mfma_f32_16x16x32_bf16 v[108:111], v[120:123], v[168:171], v[108:111]
	v_mfma_f32_16x16x32_bf16 v[92:95], v[120:123], v[176:179], 0
	v_mfma_f32_16x16x32_bf16 v[92:95], v[124:127], v[180:183], v[92:95]
	v_mfma_f32_16x16x32_bf16 v[76:79], v[124:127], v[204:207], 0
	v_mfma_f32_16x16x32_bf16 v[76:79], v[120:123], v[200:203], v[76:79]
	v_mfma_f32_16x16x32_bf16 v[128:131], v[136:139], v[160:163], 0
	v_mfma_f32_16x16x32_bf16 v[128:131], v[140:143], v[164:167], v[128:131]
	v_mfma_f32_16x16x32_bf16 v[104:107], v[140:143], v[172:175], 0
	v_mfma_f32_16x16x32_bf16 v[104:107], v[136:139], v[168:171], v[104:107]
	v_mfma_f32_16x16x32_bf16 v[88:91], v[136:139], v[176:179], 0
	v_mfma_f32_16x16x32_bf16 v[88:91], v[140:143], v[180:183], v[88:91]
	v_mfma_f32_16x16x32_bf16 v[72:75], v[140:143], v[204:207], 0
	v_mfma_f32_16x16x32_bf16 v[72:75], v[136:139], v[200:203], v[72:75]
	v_mfma_f32_16x16x32_bf16 v[116:119], v[144:147], v[160:163], 0
	v_mfma_f32_16x16x32_bf16 v[116:119], v[148:151], v[164:167], v[116:119]
	v_mfma_f32_16x16x32_bf16 v[100:103], v[148:151], v[172:175], 0
	v_mfma_f32_16x16x32_bf16 v[100:103], v[144:147], v[168:171], v[100:103]
	v_mfma_f32_16x16x32_bf16 v[84:87], v[144:147], v[176:179], 0
	v_mfma_f32_16x16x32_bf16 v[84:87], v[148:151], v[180:183], v[84:87]
	v_mfma_f32_16x16x32_bf16 v[68:71], v[148:151], v[204:207], 0
	v_mfma_f32_16x16x32_bf16 v[68:71], v[144:147], v[200:203], v[68:71]
	v_mfma_f32_16x16x32_bf16 v[112:115], v[152:155], v[160:163], 0
	v_mfma_f32_16x16x32_bf16 v[112:115], v[156:159], v[164:167], v[112:115]
	v_mfma_f32_16x16x32_bf16 v[96:99], v[156:159], v[172:175], 0
	v_mfma_f32_16x16x32_bf16 v[96:99], v[152:155], v[168:171], v[96:99]
	s_setprio 2
	s_barrier
	v_mfma_f32_16x16x32_bf16 v[80:83], v[152:155], v[176:179], 0
	v_mfma_f32_16x16x32_bf16 v[80:83], v[156:159], v[180:183], v[80:83]
	v_mfma_f32_16x16x32_bf16 v[64:67], v[156:159], v[204:207], 0
	v_mfma_f32_16x16x32_bf16 v[64:67], v[152:155], v[200:203], v[64:67]
	s_setprio 2
	s_add_i32 s26, s56, s43
	v_lshl_add_u64 v[208:209], s[30:31], 0, v[186:187]
	s_mov_b32 m0, s26
	ds_read_b128 v[160:163], v235 offset:16384
	ds_read_b128 v[164:167], v235 offset:17408
	ds_read_b128 v[168:171], v235 offset:18432
	ds_read_b128 v[172:175], v235 offset:19456
	ds_read_b128 v[176:179], v235 offset:20480
	ds_read_b128 v[180:183], v235 offset:21504
	ds_read_b128 v[200:203], v235 offset:22528
	ds_read_b128 v[204:207], v235 offset:23552
	global_load_lds_dwordx4 v[208:209], off
	s_add_i32 m0, s26, 0x2000
	s_add_u32 s26, s30, 0xb0000
	v_lshl_add_u64 v[210:211], s[30:31], 0, v[190:191]
	s_addc_u32 s27, s31, 0
	s_add_i32 s65, s57, s43
	global_load_lds_dwordx4 v[210:211], off
	v_lshl_add_u64 v[212:213], s[26:27], 0, v[186:187]
	s_mov_b32 m0, s65
	v_lshl_add_u64 v[214:215], s[36:37], 0, v[188:189]
	global_load_lds_dwordx4 v[212:213], off
	s_add_i32 m0, s65, 0x2000
	v_lshl_add_u64 v[212:213], s[26:27], 0, v[190:191]
	global_load_lds_dwordx4 v[212:213], off
	s_mov_b32 m0, s44
	v_lshl_add_u64 v[212:213], s[36:37], 0, v[184:185]
	global_load_lds_dwordx4 v[212:213], off
	s_mov_b32 m0, s45
	s_nop 0
	global_load_lds_dwordx4 v[214:215], off
	s_waitcnt vmcnt(8) lgkmcnt(0)
	s_barrier
	s_setprio 1
	v_mfma_f32_16x16x32_bf16 v[60:63], v[120:123], v[160:163], 0
	v_mfma_f32_16x16x32_bf16 v[60:63], v[124:127], v[164:167], v[60:63]
	v_mfma_f32_16x16x32_bf16 v[44:47], v[124:127], v[172:175], 0
	v_mfma_f32_16x16x32_bf16 v[44:47], v[120:123], v[168:171], v[44:47]
	v_mfma_f32_16x16x32_bf16 v[28:31], v[120:123], v[176:179], 0
	v_mfma_f32_16x16x32_bf16 v[28:31], v[124:127], v[180:183], v[28:31]
	v_mfma_f32_16x16x32_bf16 v[12:15], v[124:127], v[204:207], 0
	v_mfma_f32_16x16x32_bf16 v[12:15], v[120:123], v[200:203], v[12:15]
	v_mfma_f32_16x16x32_bf16 v[56:59], v[136:139], v[160:163], 0
	v_mfma_f32_16x16x32_bf16 v[56:59], v[140:143], v[164:167], v[56:59]
	v_mfma_f32_16x16x32_bf16 v[40:43], v[140:143], v[172:175], 0
	v_mfma_f32_16x16x32_bf16 v[40:43], v[136:139], v[168:171], v[40:43]
	v_mfma_f32_16x16x32_bf16 v[24:27], v[136:139], v[176:179], 0
	v_mfma_f32_16x16x32_bf16 v[24:27], v[140:143], v[180:183], v[24:27]
	v_mfma_f32_16x16x32_bf16 v[8:11], v[140:143], v[204:207], 0
	v_mfma_f32_16x16x32_bf16 v[8:11], v[136:139], v[200:203], v[8:11]
	v_mfma_f32_16x16x32_bf16 v[52:55], v[144:147], v[160:163], 0
	v_mfma_f32_16x16x32_bf16 v[52:55], v[148:151], v[164:167], v[52:55]
	v_mfma_f32_16x16x32_bf16 v[36:39], v[148:151], v[172:175], 0
	v_mfma_f32_16x16x32_bf16 v[36:39], v[144:147], v[168:171], v[36:39]
	v_mfma_f32_16x16x32_bf16 v[20:23], v[144:147], v[176:179], 0
	v_mfma_f32_16x16x32_bf16 v[20:23], v[148:151], v[180:183], v[20:23]
	v_mfma_f32_16x16x32_bf16 v[4:7], v[148:151], v[204:207], 0
	v_mfma_f32_16x16x32_bf16 v[4:7], v[144:147], v[200:203], v[4:7]
	v_mfma_f32_16x16x32_bf16 v[48:51], v[152:155], v[160:163], 0
	v_mfma_f32_16x16x32_bf16 v[48:51], v[156:159], v[164:167], v[48:51]
	v_mfma_f32_16x16x32_bf16 v[32:35], v[156:159], v[172:175], 0
	v_mfma_f32_16x16x32_bf16 v[32:35], v[152:155], v[168:171], v[32:35]
	s_setprio 2
	s_barrier
	v_mfma_f32_16x16x32_bf16 v[16:19], v[152:155], v[176:179], 0
	v_mfma_f32_16x16x32_bf16 v[16:19], v[156:159], v[180:183], v[16:19]
	v_mfma_f32_16x16x32_bf16 v[0:3], v[156:159], v[204:207], 0
	v_mfma_f32_16x16x32_bf16 v[0:3], v[152:155], v[200:203], v[0:3]
	s_setprio 0
	s_add_i32 s65, 0, 0x18000
	s_add_i32 s66, 0, 0x1c000
	v_add_u32_e32 v140, s65, v232
	v_add_u32_e32 v156, s66, v232
	ds_read_b128 v[120:123], v140
	ds_read_b128 v[124:127], v140 offset:1024
	ds_read_b128 v[136:139], v140 offset:2048
	ds_read_b128 v[140:143], v140 offset:3072
	ds_read_b128 v[144:147], v156
	ds_read_b128 v[148:151], v156 offset:1024
	ds_read_b128 v[152:155], v156 offset:2048
	ds_read_b128 v[156:159], v156 offset:3072
	s_add_u32 s26, s36, 0xb0000
	s_addc_u32 s27, s37, 0
	s_mov_b32 m0, s46
	v_lshl_add_u64 v[216:217], s[26:27], 0, v[184:185]
	ds_read_b128 v[160:163], v235 offset:32768
	ds_read_b128 v[164:167], v235 offset:33792
	ds_read_b128 v[168:171], v235 offset:34816
	ds_read_b128 v[172:175], v235 offset:35840
	ds_read_b128 v[176:179], v235 offset:36864
	ds_read_b128 v[180:183], v235 offset:37888
	ds_read_b128 v[200:203], v235 offset:38912
	ds_read_b128 v[204:207], v235 offset:39936
	global_load_lds_dwordx4 v[216:217], off
	s_mov_b32 m0, s47
	v_lshl_add_u64 v[216:217], s[26:27], 0, v[188:189]
	global_load_lds_dwordx4 v[216:217], off
	s_waitcnt vmcnt(8) lgkmcnt(0)
	s_barrier
	s_setprio 1
	v_mfma_f32_16x16x32_bf16 v[132:135], v[120:123], v[160:163], v[132:135]
	v_mfma_f32_16x16x32_bf16 v[132:135], v[124:127], v[164:167], v[132:135]
	v_mfma_f32_16x16x32_bf16 v[108:111], v[124:127], v[172:175], v[108:111]
	v_mfma_f32_16x16x32_bf16 v[108:111], v[120:123], v[168:171], v[108:111]
	v_mfma_f32_16x16x32_bf16 v[92:95], v[120:123], v[176:179], v[92:95]
	v_mfma_f32_16x16x32_bf16 v[92:95], v[124:127], v[180:183], v[92:95]
	v_mfma_f32_16x16x32_bf16 v[76:79], v[124:127], v[204:207], v[76:79]
	v_mfma_f32_16x16x32_bf16 v[76:79], v[120:123], v[200:203], v[76:79]
	v_mfma_f32_16x16x32_bf16 v[128:131], v[136:139], v[160:163], v[128:131]
	v_mfma_f32_16x16x32_bf16 v[128:131], v[140:143], v[164:167], v[128:131]
	v_mfma_f32_16x16x32_bf16 v[104:107], v[140:143], v[172:175], v[104:107]
	v_mfma_f32_16x16x32_bf16 v[104:107], v[136:139], v[168:171], v[104:107]
	v_mfma_f32_16x16x32_bf16 v[88:91], v[136:139], v[176:179], v[88:91]
	v_mfma_f32_16x16x32_bf16 v[88:91], v[140:143], v[180:183], v[88:91]
	v_mfma_f32_16x16x32_bf16 v[72:75], v[140:143], v[204:207], v[72:75]
	v_mfma_f32_16x16x32_bf16 v[72:75], v[136:139], v[200:203], v[72:75]
	v_mfma_f32_16x16x32_bf16 v[116:119], v[144:147], v[160:163], v[116:119]
	v_mfma_f32_16x16x32_bf16 v[116:119], v[148:151], v[164:167], v[116:119]
	v_mfma_f32_16x16x32_bf16 v[100:103], v[148:151], v[172:175], v[100:103]
	v_mfma_f32_16x16x32_bf16 v[100:103], v[144:147], v[168:171], v[100:103]
	v_mfma_f32_16x16x32_bf16 v[84:87], v[144:147], v[176:179], v[84:87]
	v_mfma_f32_16x16x32_bf16 v[84:87], v[148:151], v[180:183], v[84:87]
	v_mfma_f32_16x16x32_bf16 v[68:71], v[148:151], v[204:207], v[68:71]
	v_mfma_f32_16x16x32_bf16 v[68:71], v[144:147], v[200:203], v[68:71]
	v_mfma_f32_16x16x32_bf16 v[112:115], v[152:155], v[160:163], v[112:115]
	v_mfma_f32_16x16x32_bf16 v[112:115], v[156:159], v[164:167], v[112:115]
	v_mfma_f32_16x16x32_bf16 v[96:99], v[156:159], v[172:175], v[96:99]
	v_mfma_f32_16x16x32_bf16 v[96:99], v[152:155], v[168:171], v[96:99]
	s_setprio 2
	s_barrier
	v_mfma_f32_16x16x32_bf16 v[80:83], v[152:155], v[176:179], v[80:83]
	v_mfma_f32_16x16x32_bf16 v[80:83], v[156:159], v[180:183], v[80:83]
	v_mfma_f32_16x16x32_bf16 v[64:67], v[156:159], v[204:207], v[64:67]
	v_mfma_f32_16x16x32_bf16 v[64:67], v[152:155], v[200:203], v[64:67]
	s_setprio 2
	s_add_i32 s26, s65, s43
	v_lshl_add_u64 v[208:209], v[208:209], 0, s[20:21]
	s_mov_b32 m0, s26
	ds_read_b128 v[160:163], v235 offset:49152
	ds_read_b128 v[164:167], v235 offset:50176
	ds_read_b128 v[168:171], v235 offset:51200
	ds_read_b128 v[172:175], v235 offset:52224
	ds_read_b128 v[176:179], v235 offset:53248
	ds_read_b128 v[180:183], v235 offset:54272
	ds_read_b128 v[200:203], v235 offset:55296
	ds_read_b128 v[204:207], v235 offset:56320
	global_load_lds_dwordx4 v[208:209], off
	s_add_i32 m0, s26, 0x2000
	s_add_u32 s26, s30, 0xb0080
	v_lshl_add_u64 v[208:209], v[210:211], 0, s[20:21]
	s_addc_u32 s27, s31, 0
	s_add_i32 s30, s66, s43
	global_load_lds_dwordx4 v[208:209], off
	s_mov_b32 m0, s30
	v_lshl_add_u64 v[208:209], s[26:27], 0, v[186:187]
	global_load_lds_dwordx4 v[208:209], off
	s_add_i32 m0, s30, 0x2000
	v_lshl_add_u64 v[208:209], s[26:27], 0, v[190:191]
	global_load_lds_dwordx4 v[208:209], off
	s_mov_b32 m0, s49
	v_lshl_add_u64 v[208:209], v[212:213], 0, s[20:21]
	global_load_lds_dwordx4 v[208:209], off
	s_mov_b32 m0, s50
	v_lshl_add_u64 v[208:209], v[214:215], 0, s[20:21]
	global_load_lds_dwordx4 v[208:209], off
	s_waitcnt vmcnt(8) lgkmcnt(0)
	s_barrier
	s_setprio 1
	v_mfma_f32_16x16x32_bf16 v[60:63], v[120:123], v[160:163], v[60:63]
	v_mfma_f32_16x16x32_bf16 v[60:63], v[124:127], v[164:167], v[60:63]
	v_mfma_f32_16x16x32_bf16 v[44:47], v[124:127], v[172:175], v[44:47]
	v_mfma_f32_16x16x32_bf16 v[44:47], v[120:123], v[168:171], v[44:47]
	v_mfma_f32_16x16x32_bf16 v[28:31], v[120:123], v[176:179], v[28:31]
	v_mfma_f32_16x16x32_bf16 v[28:31], v[124:127], v[180:183], v[28:31]
	v_mfma_f32_16x16x32_bf16 v[12:15], v[124:127], v[204:207], v[12:15]
	v_mfma_f32_16x16x32_bf16 v[12:15], v[120:123], v[200:203], v[12:15]
	v_mfma_f32_16x16x32_bf16 v[56:59], v[136:139], v[160:163], v[56:59]
	v_mfma_f32_16x16x32_bf16 v[56:59], v[140:143], v[164:167], v[56:59]
	v_mfma_f32_16x16x32_bf16 v[40:43], v[140:143], v[172:175], v[40:43]
	v_mfma_f32_16x16x32_bf16 v[40:43], v[136:139], v[168:171], v[40:43]
	v_mfma_f32_16x16x32_bf16 v[24:27], v[136:139], v[176:179], v[24:27]
	v_mfma_f32_16x16x32_bf16 v[24:27], v[140:143], v[180:183], v[24:27]
	v_mfma_f32_16x16x32_bf16 v[8:11], v[140:143], v[204:207], v[8:11]
	v_mfma_f32_16x16x32_bf16 v[8:11], v[136:139], v[200:203], v[8:11]
	v_mfma_f32_16x16x32_bf16 v[52:55], v[144:147], v[160:163], v[52:55]
	v_mfma_f32_16x16x32_bf16 v[52:55], v[148:151], v[164:167], v[52:55]
	v_mfma_f32_16x16x32_bf16 v[36:39], v[148:151], v[172:175], v[36:39]
	v_mfma_f32_16x16x32_bf16 v[36:39], v[144:147], v[168:171], v[36:39]
	v_mfma_f32_16x16x32_bf16 v[20:23], v[144:147], v[176:179], v[20:23]
	v_mfma_f32_16x16x32_bf16 v[20:23], v[148:151], v[180:183], v[20:23]
	v_mfma_f32_16x16x32_bf16 v[4:7], v[148:151], v[204:207], v[4:7]
	v_mfma_f32_16x16x32_bf16 v[4:7], v[144:147], v[200:203], v[4:7]
	v_mfma_f32_16x16x32_bf16 v[48:51], v[152:155], v[160:163], v[48:51]
	v_mfma_f32_16x16x32_bf16 v[48:51], v[156:159], v[164:167], v[48:51]
	v_mfma_f32_16x16x32_bf16 v[32:35], v[156:159], v[172:175], v[32:35]
	v_mfma_f32_16x16x32_bf16 v[32:35], v[152:155], v[168:171], v[32:35]
	s_setprio 2
	s_barrier
	v_mfma_f32_16x16x32_bf16 v[16:19], v[152:155], v[176:179], v[16:19]
	v_mfma_f32_16x16x32_bf16 v[16:19], v[156:159], v[180:183], v[16:19]
	v_mfma_f32_16x16x32_bf16 v[0:3], v[156:159], v[204:207], v[0:3]
	v_mfma_f32_16x16x32_bf16 v[0:3], v[152:155], v[200:203], v[0:3]
	s_setprio 0
	s_add_i32 s64, s64, 2
	s_add_u32 s62, s62, 0x100
	s_addc_u32 s63, s63, 0
	s_cmp_gt_u32 s64, 41
	s_mov_b64 s[26:27], s[28:29]
.LBB0_866:
	ds_read_b128 v[120:123], v233
	ds_read_b128 v[124:127], v233 offset:1024
	ds_read_b128 v[136:139], v233 offset:2048
	ds_read_b128 v[140:143], v233 offset:3072
	ds_read_b128 v[144:147], v234
	ds_read_b128 v[148:151], v234 offset:1024
	ds_read_b128 v[152:155], v234 offset:2048
	ds_read_b128 v[156:159], v234 offset:3072
	s_add_u32 s28, s26, 0x100
	s_addc_u32 s29, s27, 0
	s_cmp_eq_u32 s64, 40
	s_cselect_b32 s37, s7, s29
	s_cselect_b32 s36, s6, s28
	s_cselect_b32 s31, s25, s63
	s_cselect_b32 s30, s24, s62
	v_lshl_add_u64 v[208:209], s[26:27], 0, v[192:193]
	s_add_i32 m0, s44, 0xc000
	ds_read_b128 v[160:163], v235
	ds_read_b128 v[164:167], v235 offset:1024
	ds_read_b128 v[168:171], v235 offset:2048
	ds_read_b128 v[172:175], v235 offset:3072
	ds_read_b128 v[176:179], v235 offset:4096
	ds_read_b128 v[180:183], v235 offset:5120
	ds_read_b128 v[200:203], v235 offset:6144
	ds_read_b128 v[204:207], v235 offset:7168
	global_load_lds_dwordx4 v[208:209], off
	s_add_i32 m0, s44, 0xe000
	v_lshl_add_u64 v[208:209], s[26:27], 0, v[194:195]
	global_load_lds_dwordx4 v[208:209], off
	s_waitcnt vmcnt(8) lgkmcnt(0)
	s_barrier
	s_setprio 1
	v_mfma_f32_16x16x32_bf16 v[132:135], v[120:123], v[160:163], v[132:135]
	v_mfma_f32_16x16x32_bf16 v[132:135], v[124:127], v[164:167], v[132:135]
	v_mfma_f32_16x16x32_bf16 v[108:111], v[124:127], v[172:175], v[108:111]
	v_mfma_f32_16x16x32_bf16 v[108:111], v[120:123], v[168:171], v[108:111]
	v_mfma_f32_16x16x32_bf16 v[92:95], v[120:123], v[176:179], v[92:95]
	v_mfma_f32_16x16x32_bf16 v[92:95], v[124:127], v[180:183], v[92:95]
	v_mfma_f32_16x16x32_bf16 v[76:79], v[124:127], v[204:207], v[76:79]
	v_mfma_f32_16x16x32_bf16 v[76:79], v[120:123], v[200:203], v[76:79]
	v_mfma_f32_16x16x32_bf16 v[128:131], v[136:139], v[160:163], v[128:131]
	v_mfma_f32_16x16x32_bf16 v[128:131], v[140:143], v[164:167], v[128:131]
	v_mfma_f32_16x16x32_bf16 v[104:107], v[140:143], v[172:175], v[104:107]
	v_mfma_f32_16x16x32_bf16 v[104:107], v[136:139], v[168:171], v[104:107]
	v_mfma_f32_16x16x32_bf16 v[88:91], v[136:139], v[176:179], v[88:91]
	v_mfma_f32_16x16x32_bf16 v[88:91], v[140:143], v[180:183], v[88:91]
	v_mfma_f32_16x16x32_bf16 v[72:75], v[140:143], v[204:207], v[72:75]
	v_mfma_f32_16x16x32_bf16 v[72:75], v[136:139], v[200:203], v[72:75]
	v_mfma_f32_16x16x32_bf16 v[116:119], v[144:147], v[160:163], v[116:119]
	v_mfma_f32_16x16x32_bf16 v[116:119], v[148:151], v[164:167], v[116:119]
	v_mfma_f32_16x16x32_bf16 v[100:103], v[148:151], v[172:175], v[100:103]
	v_mfma_f32_16x16x32_bf16 v[100:103], v[144:147], v[168:171], v[100:103]
	v_mfma_f32_16x16x32_bf16 v[84:87], v[144:147], v[176:179], v[84:87]
	v_mfma_f32_16x16x32_bf16 v[84:87], v[148:151], v[180:183], v[84:87]
	v_mfma_f32_16x16x32_bf16 v[68:71], v[148:151], v[204:207], v[68:71]
	v_mfma_f32_16x16x32_bf16 v[68:71], v[144:147], v[200:203], v[68:71]
	v_mfma_f32_16x16x32_bf16 v[112:115], v[152:155], v[160:163], v[112:115]
	v_mfma_f32_16x16x32_bf16 v[112:115], v[156:159], v[164:167], v[112:115]
	v_mfma_f32_16x16x32_bf16 v[96:99], v[156:159], v[172:175], v[96:99]
	v_mfma_f32_16x16x32_bf16 v[96:99], v[152:155], v[168:171], v[96:99]
	s_setprio 2
	s_barrier
	v_mfma_f32_16x16x32_bf16 v[80:83], v[152:155], v[176:179], v[80:83]
	v_mfma_f32_16x16x32_bf16 v[80:83], v[156:159], v[180:183], v[80:83]
	v_mfma_f32_16x16x32_bf16 v[64:67], v[156:159], v[204:207], v[64:67]
	v_mfma_f32_16x16x32_bf16 v[64:67], v[152:155], v[200:203], v[64:67]
	s_setprio 2
	s_add_i32 s26, s56, s43
	v_lshl_add_u64 v[208:209], s[30:31], 0, v[186:187]
	s_mov_b32 m0, s26
	ds_read_b128 v[160:163], v235 offset:16384
	ds_read_b128 v[164:167], v235 offset:17408
	ds_read_b128 v[168:171], v235 offset:18432
	ds_read_b128 v[172:175], v235 offset:19456
	ds_read_b128 v[176:179], v235 offset:20480
	ds_read_b128 v[180:183], v235 offset:21504
	ds_read_b128 v[200:203], v235 offset:22528
	ds_read_b128 v[204:207], v235 offset:23552
	global_load_lds_dwordx4 v[208:209], off
	s_add_i32 m0, s26, 0x2000
	s_add_u32 s26, s30, 0xb0000
	v_lshl_add_u64 v[210:211], s[30:31], 0, v[190:191]
	s_addc_u32 s27, s31, 0
	s_add_i32 s65, s57, s43
	global_load_lds_dwordx4 v[210:211], off
	v_lshl_add_u64 v[212:213], s[26:27], 0, v[186:187]
	s_mov_b32 m0, s65
	v_lshl_add_u64 v[214:215], s[36:37], 0, v[188:189]
	global_load_lds_dwordx4 v[212:213], off
	s_add_i32 m0, s65, 0x2000
	v_lshl_add_u64 v[212:213], s[26:27], 0, v[190:191]
	global_load_lds_dwordx4 v[212:213], off
	s_mov_b32 m0, s44
	v_lshl_add_u64 v[212:213], s[36:37], 0, v[184:185]
	global_load_lds_dwordx4 v[212:213], off
	s_mov_b32 m0, s45
	s_nop 0
	global_load_lds_dwordx4 v[214:215], off
	s_waitcnt vmcnt(8) lgkmcnt(0)
	s_barrier
	s_setprio 1
	v_mfma_f32_16x16x32_bf16 v[60:63], v[120:123], v[160:163], v[60:63]
	v_mfma_f32_16x16x32_bf16 v[60:63], v[124:127], v[164:167], v[60:63]
	v_mfma_f32_16x16x32_bf16 v[44:47], v[124:127], v[172:175], v[44:47]
	v_mfma_f32_16x16x32_bf16 v[44:47], v[120:123], v[168:171], v[44:47]
	v_mfma_f32_16x16x32_bf16 v[28:31], v[120:123], v[176:179], v[28:31]
	v_mfma_f32_16x16x32_bf16 v[28:31], v[124:127], v[180:183], v[28:31]
	v_mfma_f32_16x16x32_bf16 v[12:15], v[124:127], v[204:207], v[12:15]
	v_mfma_f32_16x16x32_bf16 v[12:15], v[120:123], v[200:203], v[12:15]
	v_mfma_f32_16x16x32_bf16 v[56:59], v[136:139], v[160:163], v[56:59]
	v_mfma_f32_16x16x32_bf16 v[56:59], v[140:143], v[164:167], v[56:59]
	v_mfma_f32_16x16x32_bf16 v[40:43], v[140:143], v[172:175], v[40:43]
	v_mfma_f32_16x16x32_bf16 v[40:43], v[136:139], v[168:171], v[40:43]
	v_mfma_f32_16x16x32_bf16 v[24:27], v[136:139], v[176:179], v[24:27]
	v_mfma_f32_16x16x32_bf16 v[24:27], v[140:143], v[180:183], v[24:27]
	v_mfma_f32_16x16x32_bf16 v[8:11], v[140:143], v[204:207], v[8:11]
	v_mfma_f32_16x16x32_bf16 v[8:11], v[136:139], v[200:203], v[8:11]
	v_mfma_f32_16x16x32_bf16 v[52:55], v[144:147], v[160:163], v[52:55]
	v_mfma_f32_16x16x32_bf16 v[52:55], v[148:151], v[164:167], v[52:55]
	v_mfma_f32_16x16x32_bf16 v[36:39], v[148:151], v[172:175], v[36:39]
	v_mfma_f32_16x16x32_bf16 v[36:39], v[144:147], v[168:171], v[36:39]
	v_mfma_f32_16x16x32_bf16 v[20:23], v[144:147], v[176:179], v[20:23]
	v_mfma_f32_16x16x32_bf16 v[20:23], v[148:151], v[180:183], v[20:23]
	v_mfma_f32_16x16x32_bf16 v[4:7], v[148:151], v[204:207], v[4:7]
	v_mfma_f32_16x16x32_bf16 v[4:7], v[144:147], v[200:203], v[4:7]
	v_mfma_f32_16x16x32_bf16 v[48:51], v[152:155], v[160:163], v[48:51]
	v_mfma_f32_16x16x32_bf16 v[48:51], v[156:159], v[164:167], v[48:51]
	v_mfma_f32_16x16x32_bf16 v[32:35], v[156:159], v[172:175], v[32:35]
	v_mfma_f32_16x16x32_bf16 v[32:35], v[152:155], v[168:171], v[32:35]
	s_setprio 2
	s_barrier
	v_mfma_f32_16x16x32_bf16 v[16:19], v[152:155], v[176:179], v[16:19]
	v_mfma_f32_16x16x32_bf16 v[16:19], v[156:159], v[180:183], v[16:19]
	v_mfma_f32_16x16x32_bf16 v[0:3], v[156:159], v[204:207], v[0:3]
	v_mfma_f32_16x16x32_bf16 v[0:3], v[152:155], v[200:203], v[0:3]
	s_setprio 0
	s_add_i32 s65, 0, 0x18000
	s_add_i32 s66, 0, 0x1c000
	v_add_u32_e32 v140, s65, v232
	v_add_u32_e32 v156, s66, v232
	ds_read_b128 v[120:123], v140
	ds_read_b128 v[124:127], v140 offset:1024
	ds_read_b128 v[136:139], v140 offset:2048
	ds_read_b128 v[140:143], v140 offset:3072
	ds_read_b128 v[144:147], v156
	ds_read_b128 v[148:151], v156 offset:1024
	ds_read_b128 v[152:155], v156 offset:2048
	ds_read_b128 v[156:159], v156 offset:3072
	s_add_u32 s26, s36, 0xb0000
	s_addc_u32 s27, s37, 0
	s_mov_b32 m0, s46
	v_lshl_add_u64 v[216:217], s[26:27], 0, v[184:185]
	ds_read_b128 v[160:163], v235 offset:32768
	ds_read_b128 v[164:167], v235 offset:33792
	ds_read_b128 v[168:171], v235 offset:34816
	ds_read_b128 v[172:175], v235 offset:35840
	ds_read_b128 v[176:179], v235 offset:36864
	ds_read_b128 v[180:183], v235 offset:37888
	ds_read_b128 v[200:203], v235 offset:38912
	ds_read_b128 v[204:207], v235 offset:39936
	global_load_lds_dwordx4 v[216:217], off
	s_mov_b32 m0, s47
	v_lshl_add_u64 v[216:217], s[26:27], 0, v[188:189]
	global_load_lds_dwordx4 v[216:217], off
	s_waitcnt vmcnt(8) lgkmcnt(0)
	s_barrier
	s_setprio 1
	v_mfma_f32_16x16x32_bf16 v[132:135], v[120:123], v[160:163], v[132:135]
	v_mfma_f32_16x16x32_bf16 v[132:135], v[124:127], v[164:167], v[132:135]
	v_mfma_f32_16x16x32_bf16 v[108:111], v[124:127], v[172:175], v[108:111]
	v_mfma_f32_16x16x32_bf16 v[108:111], v[120:123], v[168:171], v[108:111]
	v_mfma_f32_16x16x32_bf16 v[92:95], v[120:123], v[176:179], v[92:95]
	v_mfma_f32_16x16x32_bf16 v[92:95], v[124:127], v[180:183], v[92:95]
	v_mfma_f32_16x16x32_bf16 v[76:79], v[124:127], v[204:207], v[76:79]
	v_mfma_f32_16x16x32_bf16 v[76:79], v[120:123], v[200:203], v[76:79]
	v_mfma_f32_16x16x32_bf16 v[128:131], v[136:139], v[160:163], v[128:131]
	v_mfma_f32_16x16x32_bf16 v[128:131], v[140:143], v[164:167], v[128:131]
	v_mfma_f32_16x16x32_bf16 v[104:107], v[140:143], v[172:175], v[104:107]
	v_mfma_f32_16x16x32_bf16 v[104:107], v[136:139], v[168:171], v[104:107]
	v_mfma_f32_16x16x32_bf16 v[88:91], v[136:139], v[176:179], v[88:91]
	v_mfma_f32_16x16x32_bf16 v[88:91], v[140:143], v[180:183], v[88:91]
	v_mfma_f32_16x16x32_bf16 v[72:75], v[140:143], v[204:207], v[72:75]
	v_mfma_f32_16x16x32_bf16 v[72:75], v[136:139], v[200:203], v[72:75]
	v_mfma_f32_16x16x32_bf16 v[116:119], v[144:147], v[160:163], v[116:119]
	v_mfma_f32_16x16x32_bf16 v[116:119], v[148:151], v[164:167], v[116:119]
	v_mfma_f32_16x16x32_bf16 v[100:103], v[148:151], v[172:175], v[100:103]
	v_mfma_f32_16x16x32_bf16 v[100:103], v[144:147], v[168:171], v[100:103]
	v_mfma_f32_16x16x32_bf16 v[84:87], v[144:147], v[176:179], v[84:87]
	v_mfma_f32_16x16x32_bf16 v[84:87], v[148:151], v[180:183], v[84:87]
	v_mfma_f32_16x16x32_bf16 v[68:71], v[148:151], v[204:207], v[68:71]
	v_mfma_f32_16x16x32_bf16 v[68:71], v[144:147], v[200:203], v[68:71]
	v_mfma_f32_16x16x32_bf16 v[112:115], v[152:155], v[160:163], v[112:115]
	v_mfma_f32_16x16x32_bf16 v[112:115], v[156:159], v[164:167], v[112:115]
	v_mfma_f32_16x16x32_bf16 v[96:99], v[156:159], v[172:175], v[96:99]
	v_mfma_f32_16x16x32_bf16 v[96:99], v[152:155], v[168:171], v[96:99]
	s_setprio 2
	s_barrier
	v_mfma_f32_16x16x32_bf16 v[80:83], v[152:155], v[176:179], v[80:83]
	v_mfma_f32_16x16x32_bf16 v[80:83], v[156:159], v[180:183], v[80:83]
	v_mfma_f32_16x16x32_bf16 v[64:67], v[156:159], v[204:207], v[64:67]
	v_mfma_f32_16x16x32_bf16 v[64:67], v[152:155], v[200:203], v[64:67]
	s_setprio 2
	s_add_i32 s26, s65, s43
	v_lshl_add_u64 v[208:209], v[208:209], 0, s[20:21]
	s_mov_b32 m0, s26
	ds_read_b128 v[160:163], v235 offset:49152
	ds_read_b128 v[164:167], v235 offset:50176
	ds_read_b128 v[168:171], v235 offset:51200
	ds_read_b128 v[172:175], v235 offset:52224
	ds_read_b128 v[176:179], v235 offset:53248
	ds_read_b128 v[180:183], v235 offset:54272
	ds_read_b128 v[200:203], v235 offset:55296
	ds_read_b128 v[204:207], v235 offset:56320
	global_load_lds_dwordx4 v[208:209], off
	s_add_i32 m0, s26, 0x2000
	s_add_u32 s26, s30, 0xb0080
	v_lshl_add_u64 v[208:209], v[210:211], 0, s[20:21]
	s_addc_u32 s27, s31, 0
	s_add_i32 s30, s66, s43
	global_load_lds_dwordx4 v[208:209], off
	s_mov_b32 m0, s30
	v_lshl_add_u64 v[208:209], s[26:27], 0, v[186:187]
	global_load_lds_dwordx4 v[208:209], off
	s_add_i32 m0, s30, 0x2000
	v_lshl_add_u64 v[208:209], s[26:27], 0, v[190:191]
	global_load_lds_dwordx4 v[208:209], off
	s_mov_b32 m0, s49
	v_lshl_add_u64 v[208:209], v[212:213], 0, s[20:21]
	global_load_lds_dwordx4 v[208:209], off
	s_mov_b32 m0, s50
	v_lshl_add_u64 v[208:209], v[214:215], 0, s[20:21]
	global_load_lds_dwordx4 v[208:209], off
	s_waitcnt vmcnt(8) lgkmcnt(0)
	s_barrier
	s_setprio 1
	v_mfma_f32_16x16x32_bf16 v[60:63], v[120:123], v[160:163], v[60:63]
	v_mfma_f32_16x16x32_bf16 v[60:63], v[124:127], v[164:167], v[60:63]
	v_mfma_f32_16x16x32_bf16 v[44:47], v[124:127], v[172:175], v[44:47]
	v_mfma_f32_16x16x32_bf16 v[44:47], v[120:123], v[168:171], v[44:47]
	v_mfma_f32_16x16x32_bf16 v[28:31], v[120:123], v[176:179], v[28:31]
	v_mfma_f32_16x16x32_bf16 v[28:31], v[124:127], v[180:183], v[28:31]
	v_mfma_f32_16x16x32_bf16 v[12:15], v[124:127], v[204:207], v[12:15]
	v_mfma_f32_16x16x32_bf16 v[12:15], v[120:123], v[200:203], v[12:15]
	v_mfma_f32_16x16x32_bf16 v[56:59], v[136:139], v[160:163], v[56:59]
	v_mfma_f32_16x16x32_bf16 v[56:59], v[140:143], v[164:167], v[56:59]
	v_mfma_f32_16x16x32_bf16 v[40:43], v[140:143], v[172:175], v[40:43]
	v_mfma_f32_16x16x32_bf16 v[40:43], v[136:139], v[168:171], v[40:43]
	v_mfma_f32_16x16x32_bf16 v[24:27], v[136:139], v[176:179], v[24:27]
	v_mfma_f32_16x16x32_bf16 v[24:27], v[140:143], v[180:183], v[24:27]
	v_mfma_f32_16x16x32_bf16 v[8:11], v[140:143], v[204:207], v[8:11]
	v_mfma_f32_16x16x32_bf16 v[8:11], v[136:139], v[200:203], v[8:11]
	v_mfma_f32_16x16x32_bf16 v[52:55], v[144:147], v[160:163], v[52:55]
	v_mfma_f32_16x16x32_bf16 v[52:55], v[148:151], v[164:167], v[52:55]
	v_mfma_f32_16x16x32_bf16 v[36:39], v[148:151], v[172:175], v[36:39]
	v_mfma_f32_16x16x32_bf16 v[36:39], v[144:147], v[168:171], v[36:39]
	v_mfma_f32_16x16x32_bf16 v[20:23], v[144:147], v[176:179], v[20:23]
	v_mfma_f32_16x16x32_bf16 v[20:23], v[148:151], v[180:183], v[20:23]
	v_mfma_f32_16x16x32_bf16 v[4:7], v[148:151], v[204:207], v[4:7]
	v_mfma_f32_16x16x32_bf16 v[4:7], v[144:147], v[200:203], v[4:7]
	v_mfma_f32_16x16x32_bf16 v[48:51], v[152:155], v[160:163], v[48:51]
	v_mfma_f32_16x16x32_bf16 v[48:51], v[156:159], v[164:167], v[48:51]
	v_mfma_f32_16x16x32_bf16 v[32:35], v[156:159], v[172:175], v[32:35]
	v_mfma_f32_16x16x32_bf16 v[32:35], v[152:155], v[168:171], v[32:35]
	s_setprio 2
	s_barrier
	v_mfma_f32_16x16x32_bf16 v[16:19], v[152:155], v[176:179], v[16:19]
	v_mfma_f32_16x16x32_bf16 v[16:19], v[156:159], v[180:183], v[16:19]
	v_mfma_f32_16x16x32_bf16 v[0:3], v[156:159], v[204:207], v[0:3]
	v_mfma_f32_16x16x32_bf16 v[0:3], v[152:155], v[200:203], v[0:3]
	s_setprio 0
	s_add_i32 s64, s64, 2
	s_add_u32 s62, s62, 0x100
	s_addc_u32 s63, s63, 0
	s_cmp_gt_u32 s64, 41
	s_mov_b64 s[26:27], s[28:29]
	s_cbranch_scc0 .LBB0_866

.LBB0_951:
	s_ashr_i32 s27, s26, 31
	s_lshl_b64 s[30:31], s[26:27], 19
	s_add_u32 s30, s47, s30
	s_addc_u32 s31, s48, s31
	s_and_b64 s[36:37], s[4:5], exec
	s_cselect_b32 s27, s31, s7
	s_cselect_b32 s39, s30, s6
	s_ashr_i32 s29, s28, 31
	s_lshl_b64 s[36:37], s[28:29], 19
	s_add_u32 s36, s49, s36
	s_addc_u32 s37, s50, s37
	s_and_b64 s[44:45], s[4:5], exec
	s_cselect_b32 s29, s37, s41
	s_cselect_b32 s43, s36, s40
	s_add_u32 s6, s6, 0x40080
	s_addc_u32 s7, s7, 0
	s_add_u32 s71, s40, 0x100
	s_addc_u32 s72, s41, 0
	s_mov_b32 s73, -2
	ds_read_b128 v[144:147], v179
	ds_read_b128 v[148:151], v179 offset:1024
	ds_read_b128 v[152:155], v179 offset:2048
	ds_read_b128 v[156:159], v179 offset:3072
	ds_read_b128 v[160:163], v180
	ds_read_b128 v[164:167], v180 offset:1024
	ds_read_b128 v[168:171], v180 offset:2048
	ds_read_b128 v[172:175], v180 offset:3072
	s_add_u32 s40, s6, 0xfffc0080
	s_addc_u32 s41, s7, -1
	s_cmp_eq_u32 s73, 12
	s_cselect_b32 s45, s27, s41
	s_cselect_b32 s44, s39, s40
	s_cselect_b32 s41, s29, s72
	s_cselect_b32 s40, s43, s71
	v_lshl_add_u64 v[176:177], s[6:7], 0, v[136:137]
	s_add_i32 m0, s54, 0xc000
	ds_read_b128 v[184:187], v181
	ds_read_b128 v[188:191], v181 offset:1024
	ds_read_b128 v[192:195], v181 offset:2048
	ds_read_b128 v[196:199], v181 offset:3072
	ds_read_b128 v[200:203], v181 offset:4096
	ds_read_b128 v[204:207], v181 offset:5120
	ds_read_b128 v[208:211], v181 offset:6144
	ds_read_b128 v[212:215], v181 offset:7168
	global_load_lds_dwordx4 v[176:177], off
	s_add_i32 m0, s54, 0xe000
	v_lshl_add_u64 v[176:177], s[6:7], 0, v[138:139]
	global_load_lds_dwordx4 v[176:177], off
	s_waitcnt vmcnt(8) lgkmcnt(0)
	s_barrier
	s_setprio 1
	v_mfma_f32_16x16x32_bf16 v[124:127], v[144:147], v[184:187], 0
	v_mfma_f32_16x16x32_bf16 v[124:127], v[148:151], v[188:191], v[124:127]
	v_mfma_f32_16x16x32_bf16 v[108:111], v[148:151], v[196:199], 0
	v_mfma_f32_16x16x32_bf16 v[108:111], v[144:147], v[192:195], v[108:111]
	v_mfma_f32_16x16x32_bf16 v[92:95], v[144:147], v[200:203], 0
	v_mfma_f32_16x16x32_bf16 v[92:95], v[148:151], v[204:207], v[92:95]
	v_mfma_f32_16x16x32_bf16 v[76:79], v[148:151], v[212:215], 0
	v_mfma_f32_16x16x32_bf16 v[76:79], v[144:147], v[208:211], v[76:79]
	v_mfma_f32_16x16x32_bf16 v[120:123], v[152:155], v[184:187], 0
	v_mfma_f32_16x16x32_bf16 v[120:123], v[156:159], v[188:191], v[120:123]
	v_mfma_f32_16x16x32_bf16 v[104:107], v[156:159], v[196:199], 0
	v_mfma_f32_16x16x32_bf16 v[104:107], v[152:155], v[192:195], v[104:107]
	v_mfma_f32_16x16x32_bf16 v[88:91], v[152:155], v[200:203], 0
	v_mfma_f32_16x16x32_bf16 v[88:91], v[156:159], v[204:207], v[88:91]
	v_mfma_f32_16x16x32_bf16 v[72:75], v[156:159], v[212:215], 0
	v_mfma_f32_16x16x32_bf16 v[72:75], v[152:155], v[208:211], v[72:75]
	v_mfma_f32_16x16x32_bf16 v[116:119], v[160:163], v[184:187], 0
	v_mfma_f32_16x16x32_bf16 v[116:119], v[164:167], v[188:191], v[116:119]
	v_mfma_f32_16x16x32_bf16 v[100:103], v[164:167], v[196:199], 0
	v_mfma_f32_16x16x32_bf16 v[100:103], v[160:163], v[192:195], v[100:103]
	v_mfma_f32_16x16x32_bf16 v[84:87], v[160:163], v[200:203], 0
	v_mfma_f32_16x16x32_bf16 v[84:87], v[164:167], v[204:207], v[84:87]
	v_mfma_f32_16x16x32_bf16 v[68:71], v[164:167], v[212:215], 0
	v_mfma_f32_16x16x32_bf16 v[68:71], v[160:163], v[208:211], v[68:71]
	v_mfma_f32_16x16x32_bf16 v[112:115], v[168:171], v[184:187], 0
	v_mfma_f32_16x16x32_bf16 v[112:115], v[172:175], v[188:191], v[112:115]
	v_mfma_f32_16x16x32_bf16 v[96:99], v[172:175], v[196:199], 0
	v_mfma_f32_16x16x32_bf16 v[96:99], v[168:171], v[192:195], v[96:99]
	s_setprio 2
	s_barrier
	v_mfma_f32_16x16x32_bf16 v[80:83], v[168:171], v[200:203], 0
	v_mfma_f32_16x16x32_bf16 v[80:83], v[172:175], v[204:207], v[80:83]
	v_mfma_f32_16x16x32_bf16 v[64:67], v[172:175], v[212:215], 0
	v_mfma_f32_16x16x32_bf16 v[64:67], v[168:171], v[208:211], v[64:67]
	s_setprio 2
	s_add_i32 s74, s69, s51
	v_lshl_add_u64 v[176:177], s[40:41], 0, v[130:131]
	s_mov_b32 m0, s74
	ds_read_b128 v[184:187], v181 offset:16384
	ds_read_b128 v[188:191], v181 offset:17408
	ds_read_b128 v[192:195], v181 offset:18432
	ds_read_b128 v[196:199], v181 offset:19456
	ds_read_b128 v[200:203], v181 offset:20480
	ds_read_b128 v[204:207], v181 offset:21504
	ds_read_b128 v[208:211], v181 offset:22528
	ds_read_b128 v[212:215], v181 offset:23552
	global_load_lds_dwordx4 v[176:177], off
	s_add_i32 m0, s74, 0x2000
	s_add_u32 s74, s40, 0x40000
	v_lshl_add_u64 v[216:217], s[40:41], 0, v[134:135]
	s_addc_u32 s75, s41, 0
	s_add_i32 s76, s70, s51
	global_load_lds_dwordx4 v[216:217], off
	v_lshl_add_u64 v[218:219], s[74:75], 0, v[130:131]
	s_mov_b32 m0, s76
	v_lshl_add_u64 v[220:221], s[44:45], 0, v[132:133]
	global_load_lds_dwordx4 v[218:219], off
	s_add_i32 m0, s76, 0x2000
	v_lshl_add_u64 v[218:219], s[74:75], 0, v[134:135]
	global_load_lds_dwordx4 v[218:219], off
	s_mov_b32 m0, s54
	v_lshl_add_u64 v[218:219], s[44:45], 0, v[128:129]
	global_load_lds_dwordx4 v[218:219], off
	s_mov_b32 m0, s55
	s_nop 0
	global_load_lds_dwordx4 v[220:221], off
	s_waitcnt vmcnt(8) lgkmcnt(0)
	s_barrier
	s_setprio 1
	v_mfma_f32_16x16x32_bf16 v[60:63], v[144:147], v[184:187], 0
	v_mfma_f32_16x16x32_bf16 v[60:63], v[148:151], v[188:191], v[60:63]
	v_mfma_f32_16x16x32_bf16 v[44:47], v[148:151], v[196:199], 0
	v_mfma_f32_16x16x32_bf16 v[44:47], v[144:147], v[192:195], v[44:47]
	v_mfma_f32_16x16x32_bf16 v[28:31], v[144:147], v[200:203], 0
	v_mfma_f32_16x16x32_bf16 v[28:31], v[148:151], v[204:207], v[28:31]
	v_mfma_f32_16x16x32_bf16 v[12:15], v[148:151], v[212:215], 0
	v_mfma_f32_16x16x32_bf16 v[12:15], v[144:147], v[208:211], v[12:15]
	v_mfma_f32_16x16x32_bf16 v[56:59], v[152:155], v[184:187], 0
	v_mfma_f32_16x16x32_bf16 v[56:59], v[156:159], v[188:191], v[56:59]
	v_mfma_f32_16x16x32_bf16 v[40:43], v[156:159], v[196:199], 0
	v_mfma_f32_16x16x32_bf16 v[40:43], v[152:155], v[192:195], v[40:43]
	v_mfma_f32_16x16x32_bf16 v[24:27], v[152:155], v[200:203], 0
	v_mfma_f32_16x16x32_bf16 v[24:27], v[156:159], v[204:207], v[24:27]
	v_mfma_f32_16x16x32_bf16 v[8:11], v[156:159], v[212:215], 0
	v_mfma_f32_16x16x32_bf16 v[8:11], v[152:155], v[208:211], v[8:11]
	v_mfma_f32_16x16x32_bf16 v[52:55], v[160:163], v[184:187], 0
	v_mfma_f32_16x16x32_bf16 v[52:55], v[164:167], v[188:191], v[52:55]
	v_mfma_f32_16x16x32_bf16 v[36:39], v[164:167], v[196:199], 0
	v_mfma_f32_16x16x32_bf16 v[36:39], v[160:163], v[192:195], v[36:39]
	v_mfma_f32_16x16x32_bf16 v[20:23], v[160:163], v[200:203], 0
	v_mfma_f32_16x16x32_bf16 v[20:23], v[164:167], v[204:207], v[20:23]
	v_mfma_f32_16x16x32_bf16 v[4:7], v[164:167], v[212:215], 0
	v_mfma_f32_16x16x32_bf16 v[4:7], v[160:163], v[208:211], v[4:7]
	v_mfma_f32_16x16x32_bf16 v[48:51], v[168:171], v[184:187], 0
	v_mfma_f32_16x16x32_bf16 v[48:51], v[172:175], v[188:191], v[48:51]
	v_mfma_f32_16x16x32_bf16 v[32:35], v[172:175], v[196:199], 0
	v_mfma_f32_16x16x32_bf16 v[32:35], v[168:171], v[192:195], v[32:35]
	s_setprio 2
	s_barrier
	v_mfma_f32_16x16x32_bf16 v[16:19], v[168:171], v[200:203], 0
	v_mfma_f32_16x16x32_bf16 v[16:19], v[172:175], v[204:207], v[16:19]
	v_mfma_f32_16x16x32_bf16 v[0:3], v[172:175], v[212:215], 0
	v_mfma_f32_16x16x32_bf16 v[0:3], v[168:171], v[208:211], v[0:3]
	s_setprio 0
	s_add_i32 s74, 0, 0x18000
	s_add_i32 s75, 0, 0x1c000
	v_add_u32_e32 v156, s74, v178
	v_add_u32_e32 v172, s75, v178
	ds_read_b128 v[144:147], v156
	ds_read_b128 v[148:151], v156 offset:1024
	ds_read_b128 v[152:155], v156 offset:2048
	ds_read_b128 v[156:159], v156 offset:3072
	ds_read_b128 v[160:163], v172
	ds_read_b128 v[164:167], v172 offset:1024
	ds_read_b128 v[168:171], v172 offset:2048
	ds_read_b128 v[172:175], v172 offset:3072
	s_add_u32 s44, s44, 0x40000
	s_addc_u32 s45, s45, 0
	s_mov_b32 m0, s56
	v_lshl_add_u64 v[222:223], s[44:45], 0, v[128:129]
	ds_read_b128 v[184:187], v181 offset:32768
	ds_read_b128 v[188:191], v181 offset:33792
	ds_read_b128 v[192:195], v181 offset:34816
	ds_read_b128 v[196:199], v181 offset:35840
	ds_read_b128 v[200:203], v181 offset:36864
	ds_read_b128 v[204:207], v181 offset:37888
	ds_read_b128 v[208:211], v181 offset:38912
	ds_read_b128 v[212:215], v181 offset:39936
	global_load_lds_dwordx4 v[222:223], off
	s_mov_b32 m0, s57
	v_lshl_add_u64 v[222:223], s[44:45], 0, v[132:133]
	global_load_lds_dwordx4 v[222:223], off
	s_waitcnt vmcnt(8) lgkmcnt(0)
	s_barrier
	s_setprio 1
	v_mfma_f32_16x16x32_bf16 v[124:127], v[144:147], v[184:187], v[124:127]
	v_mfma_f32_16x16x32_bf16 v[124:127], v[148:151], v[188:191], v[124:127]
	v_mfma_f32_16x16x32_bf16 v[108:111], v[148:151], v[196:199], v[108:111]
	v_mfma_f32_16x16x32_bf16 v[108:111], v[144:147], v[192:195], v[108:111]
	v_mfma_f32_16x16x32_bf16 v[92:95], v[144:147], v[200:203], v[92:95]
	v_mfma_f32_16x16x32_bf16 v[92:95], v[148:151], v[204:207], v[92:95]
	v_mfma_f32_16x16x32_bf16 v[76:79], v[148:151], v[212:215], v[76:79]
	v_mfma_f32_16x16x32_bf16 v[76:79], v[144:147], v[208:211], v[76:79]
	v_mfma_f32_16x16x32_bf16 v[120:123], v[152:155], v[184:187], v[120:123]
	v_mfma_f32_16x16x32_bf16 v[120:123], v[156:159], v[188:191], v[120:123]
	v_mfma_f32_16x16x32_bf16 v[104:107], v[156:159], v[196:199], v[104:107]
	v_mfma_f32_16x16x32_bf16 v[104:107], v[152:155], v[192:195], v[104:107]
	v_mfma_f32_16x16x32_bf16 v[88:91], v[152:155], v[200:203], v[88:91]
	v_mfma_f32_16x16x32_bf16 v[88:91], v[156:159], v[204:207], v[88:91]
	v_mfma_f32_16x16x32_bf16 v[72:75], v[156:159], v[212:215], v[72:75]
	v_mfma_f32_16x16x32_bf16 v[72:75], v[152:155], v[208:211], v[72:75]
	v_mfma_f32_16x16x32_bf16 v[116:119], v[160:163], v[184:187], v[116:119]
	v_mfma_f32_16x16x32_bf16 v[116:119], v[164:167], v[188:191], v[116:119]
	v_mfma_f32_16x16x32_bf16 v[100:103], v[164:167], v[196:199], v[100:103]
	v_mfma_f32_16x16x32_bf16 v[100:103], v[160:163], v[192:195], v[100:103]
	v_mfma_f32_16x16x32_bf16 v[84:87], v[160:163], v[200:203], v[84:87]
	v_mfma_f32_16x16x32_bf16 v[84:87], v[164:167], v[204:207], v[84:87]
	v_mfma_f32_16x16x32_bf16 v[68:71], v[164:167], v[212:215], v[68:71]
	v_mfma_f32_16x16x32_bf16 v[68:71], v[160:163], v[208:211], v[68:71]
	v_mfma_f32_16x16x32_bf16 v[112:115], v[168:171], v[184:187], v[112:115]
	v_mfma_f32_16x16x32_bf16 v[112:115], v[172:175], v[188:191], v[112:115]
	v_mfma_f32_16x16x32_bf16 v[96:99], v[172:175], v[196:199], v[96:99]
	v_mfma_f32_16x16x32_bf16 v[96:99], v[168:171], v[192:195], v[96:99]
	s_setprio 2
	s_barrier
	v_mfma_f32_16x16x32_bf16 v[80:83], v[168:171], v[200:203], v[80:83]
	v_mfma_f32_16x16x32_bf16 v[80:83], v[172:175], v[204:207], v[80:83]
	v_mfma_f32_16x16x32_bf16 v[64:67], v[172:175], v[212:215], v[64:67]
	v_mfma_f32_16x16x32_bf16 v[64:67], v[168:171], v[208:211], v[64:67]
	s_setprio 2
	s_add_i32 s44, s74, s51
	v_lshl_add_u64 v[176:177], v[176:177], 0, s[22:23]
	s_mov_b32 m0, s44
	ds_read_b128 v[184:187], v181 offset:49152
	ds_read_b128 v[188:191], v181 offset:50176
	ds_read_b128 v[192:195], v181 offset:51200
	ds_read_b128 v[196:199], v181 offset:52224
	ds_read_b128 v[200:203], v181 offset:53248
	ds_read_b128 v[204:207], v181 offset:54272
	ds_read_b128 v[208:211], v181 offset:55296
	ds_read_b128 v[212:215], v181 offset:56320
	global_load_lds_dwordx4 v[176:177], off
	s_add_i32 m0, s44, 0x2000
	s_add_u32 s40, s40, 0x40080
	v_lshl_add_u64 v[176:177], v[216:217], 0, s[22:23]
	s_addc_u32 s41, s41, 0
	s_add_i32 s44, s75, s51
	global_load_lds_dwordx4 v[176:177], off
	s_mov_b32 m0, s44
	v_lshl_add_u64 v[176:177], s[40:41], 0, v[130:131]
	global_load_lds_dwordx4 v[176:177], off
	s_add_i32 m0, s44, 0x2000
	v_lshl_add_u64 v[176:177], s[40:41], 0, v[134:135]
	global_load_lds_dwordx4 v[176:177], off
	s_mov_b32 m0, s64
	v_lshl_add_u64 v[176:177], v[218:219], 0, s[22:23]
	global_load_lds_dwordx4 v[176:177], off
	s_mov_b32 m0, s65
	v_lshl_add_u64 v[176:177], v[220:221], 0, s[22:23]
	global_load_lds_dwordx4 v[176:177], off
	s_waitcnt vmcnt(8) lgkmcnt(0)
	s_barrier
	s_setprio 1
	v_mfma_f32_16x16x32_bf16 v[60:63], v[144:147], v[184:187], v[60:63]
	v_mfma_f32_16x16x32_bf16 v[60:63], v[148:151], v[188:191], v[60:63]
	v_mfma_f32_16x16x32_bf16 v[44:47], v[148:151], v[196:199], v[44:47]
	v_mfma_f32_16x16x32_bf16 v[44:47], v[144:147], v[192:195], v[44:47]
	v_mfma_f32_16x16x32_bf16 v[28:31], v[144:147], v[200:203], v[28:31]
	v_mfma_f32_16x16x32_bf16 v[28:31], v[148:151], v[204:207], v[28:31]
	v_mfma_f32_16x16x32_bf16 v[12:15], v[148:151], v[212:215], v[12:15]
	v_mfma_f32_16x16x32_bf16 v[12:15], v[144:147], v[208:211], v[12:15]
	v_mfma_f32_16x16x32_bf16 v[56:59], v[152:155], v[184:187], v[56:59]
	v_mfma_f32_16x16x32_bf16 v[56:59], v[156:159], v[188:191], v[56:59]
	v_mfma_f32_16x16x32_bf16 v[40:43], v[156:159], v[196:199], v[40:43]
	v_mfma_f32_16x16x32_bf16 v[40:43], v[152:155], v[192:195], v[40:43]
	v_mfma_f32_16x16x32_bf16 v[24:27], v[152:155], v[200:203], v[24:27]
	v_mfma_f32_16x16x32_bf16 v[24:27], v[156:159], v[204:207], v[24:27]
	v_mfma_f32_16x16x32_bf16 v[8:11], v[156:159], v[212:215], v[8:11]
	v_mfma_f32_16x16x32_bf16 v[8:11], v[152:155], v[208:211], v[8:11]
	v_mfma_f32_16x16x32_bf16 v[52:55], v[160:163], v[184:187], v[52:55]
	v_mfma_f32_16x16x32_bf16 v[52:55], v[164:167], v[188:191], v[52:55]
	v_mfma_f32_16x16x32_bf16 v[36:39], v[164:167], v[196:199], v[36:39]
	v_mfma_f32_16x16x32_bf16 v[36:39], v[160:163], v[192:195], v[36:39]
	v_mfma_f32_16x16x32_bf16 v[20:23], v[160:163], v[200:203], v[20:23]
	v_mfma_f32_16x16x32_bf16 v[20:23], v[164:167], v[204:207], v[20:23]
	v_mfma_f32_16x16x32_bf16 v[4:7], v[164:167], v[212:215], v[4:7]
	v_mfma_f32_16x16x32_bf16 v[4:7], v[160:163], v[208:211], v[4:7]
	v_mfma_f32_16x16x32_bf16 v[48:51], v[168:171], v[184:187], v[48:51]
	v_mfma_f32_16x16x32_bf16 v[48:51], v[172:175], v[188:191], v[48:51]
	v_mfma_f32_16x16x32_bf16 v[32:35], v[172:175], v[196:199], v[32:35]
	v_mfma_f32_16x16x32_bf16 v[32:35], v[168:171], v[192:195], v[32:35]
	s_setprio 2
	s_barrier
	v_mfma_f32_16x16x32_bf16 v[16:19], v[168:171], v[200:203], v[16:19]
	v_mfma_f32_16x16x32_bf16 v[16:19], v[172:175], v[204:207], v[16:19]
	v_mfma_f32_16x16x32_bf16 v[0:3], v[172:175], v[212:215], v[0:3]
	v_mfma_f32_16x16x32_bf16 v[0:3], v[168:171], v[208:211], v[0:3]
	s_setprio 0
	s_add_i32 s73, s73, 2
	s_add_u32 s6, s6, 0x100
	s_addc_u32 s7, s7, 0
	s_add_u32 s71, s71, 0x100
	s_addc_u32 s72, s72, 0
	s_cmp_gt_u32 s73, 13
.LBB0_952:
	ds_read_b128 v[144:147], v179
	ds_read_b128 v[148:151], v179 offset:1024
	ds_read_b128 v[152:155], v179 offset:2048
	ds_read_b128 v[156:159], v179 offset:3072
	ds_read_b128 v[160:163], v180
	ds_read_b128 v[164:167], v180 offset:1024
	ds_read_b128 v[168:171], v180 offset:2048
	ds_read_b128 v[172:175], v180 offset:3072
	s_add_u32 s40, s6, 0xfffc0080
	s_addc_u32 s41, s7, -1
	s_cmp_eq_u32 s73, 12
	s_cselect_b32 s45, s27, s41
	s_cselect_b32 s44, s39, s40
	s_cselect_b32 s41, s29, s72
	s_cselect_b32 s40, s43, s71
	v_lshl_add_u64 v[176:177], s[6:7], 0, v[136:137]
	s_add_i32 m0, s54, 0xc000
	ds_read_b128 v[184:187], v181
	ds_read_b128 v[188:191], v181 offset:1024
	ds_read_b128 v[192:195], v181 offset:2048
	ds_read_b128 v[196:199], v181 offset:3072
	ds_read_b128 v[200:203], v181 offset:4096
	ds_read_b128 v[204:207], v181 offset:5120
	ds_read_b128 v[208:211], v181 offset:6144
	ds_read_b128 v[212:215], v181 offset:7168
	global_load_lds_dwordx4 v[176:177], off
	s_add_i32 m0, s54, 0xe000
	v_lshl_add_u64 v[176:177], s[6:7], 0, v[138:139]
	global_load_lds_dwordx4 v[176:177], off
	s_waitcnt vmcnt(8) lgkmcnt(0)
	s_barrier
	s_setprio 1
	v_mfma_f32_16x16x32_bf16 v[124:127], v[144:147], v[184:187], v[124:127]
	v_mfma_f32_16x16x32_bf16 v[124:127], v[148:151], v[188:191], v[124:127]
	v_mfma_f32_16x16x32_bf16 v[108:111], v[148:151], v[196:199], v[108:111]
	v_mfma_f32_16x16x32_bf16 v[108:111], v[144:147], v[192:195], v[108:111]
	v_mfma_f32_16x16x32_bf16 v[92:95], v[144:147], v[200:203], v[92:95]
	v_mfma_f32_16x16x32_bf16 v[92:95], v[148:151], v[204:207], v[92:95]
	v_mfma_f32_16x16x32_bf16 v[76:79], v[148:151], v[212:215], v[76:79]
	v_mfma_f32_16x16x32_bf16 v[76:79], v[144:147], v[208:211], v[76:79]
	v_mfma_f32_16x16x32_bf16 v[120:123], v[152:155], v[184:187], v[120:123]
	v_mfma_f32_16x16x32_bf16 v[120:123], v[156:159], v[188:191], v[120:123]
	v_mfma_f32_16x16x32_bf16 v[104:107], v[156:159], v[196:199], v[104:107]
	v_mfma_f32_16x16x32_bf16 v[104:107], v[152:155], v[192:195], v[104:107]
	v_mfma_f32_16x16x32_bf16 v[88:91], v[152:155], v[200:203], v[88:91]
	v_mfma_f32_16x16x32_bf16 v[88:91], v[156:159], v[204:207], v[88:91]
	v_mfma_f32_16x16x32_bf16 v[72:75], v[156:159], v[212:215], v[72:75]
	v_mfma_f32_16x16x32_bf16 v[72:75], v[152:155], v[208:211], v[72:75]
	v_mfma_f32_16x16x32_bf16 v[116:119], v[160:163], v[184:187], v[116:119]
	v_mfma_f32_16x16x32_bf16 v[116:119], v[164:167], v[188:191], v[116:119]
	v_mfma_f32_16x16x32_bf16 v[100:103], v[164:167], v[196:199], v[100:103]
	v_mfma_f32_16x16x32_bf16 v[100:103], v[160:163], v[192:195], v[100:103]
	v_mfma_f32_16x16x32_bf16 v[84:87], v[160:163], v[200:203], v[84:87]
	v_mfma_f32_16x16x32_bf16 v[84:87], v[164:167], v[204:207], v[84:87]
	v_mfma_f32_16x16x32_bf16 v[68:71], v[164:167], v[212:215], v[68:71]
	v_mfma_f32_16x16x32_bf16 v[68:71], v[160:163], v[208:211], v[68:71]
	v_mfma_f32_16x16x32_bf16 v[112:115], v[168:171], v[184:187], v[112:115]
	v_mfma_f32_16x16x32_bf16 v[112:115], v[172:175], v[188:191], v[112:115]
	v_mfma_f32_16x16x32_bf16 v[96:99], v[172:175], v[196:199], v[96:99]
	v_mfma_f32_16x16x32_bf16 v[96:99], v[168:171], v[192:195], v[96:99]
	s_setprio 2
	s_barrier
	v_mfma_f32_16x16x32_bf16 v[80:83], v[168:171], v[200:203], v[80:83]
	v_mfma_f32_16x16x32_bf16 v[80:83], v[172:175], v[204:207], v[80:83]
	v_mfma_f32_16x16x32_bf16 v[64:67], v[172:175], v[212:215], v[64:67]
	v_mfma_f32_16x16x32_bf16 v[64:67], v[168:171], v[208:211], v[64:67]
	s_setprio 2
	s_add_i32 s74, s69, s51
	v_lshl_add_u64 v[176:177], s[40:41], 0, v[130:131]
	s_mov_b32 m0, s74
	ds_read_b128 v[184:187], v181 offset:16384
	ds_read_b128 v[188:191], v181 offset:17408
	ds_read_b128 v[192:195], v181 offset:18432
	ds_read_b128 v[196:199], v181 offset:19456
	ds_read_b128 v[200:203], v181 offset:20480
	ds_read_b128 v[204:207], v181 offset:21504
	ds_read_b128 v[208:211], v181 offset:22528
	ds_read_b128 v[212:215], v181 offset:23552
	global_load_lds_dwordx4 v[176:177], off
	s_add_i32 m0, s74, 0x2000
	s_add_u32 s74, s40, 0x40000
	v_lshl_add_u64 v[216:217], s[40:41], 0, v[134:135]
	s_addc_u32 s75, s41, 0
	s_add_i32 s76, s70, s51
	global_load_lds_dwordx4 v[216:217], off
	v_lshl_add_u64 v[218:219], s[74:75], 0, v[130:131]
	s_mov_b32 m0, s76
	v_lshl_add_u64 v[220:221], s[44:45], 0, v[132:133]
	global_load_lds_dwordx4 v[218:219], off
	s_add_i32 m0, s76, 0x2000
	v_lshl_add_u64 v[218:219], s[74:75], 0, v[134:135]
	global_load_lds_dwordx4 v[218:219], off
	s_mov_b32 m0, s54
	v_lshl_add_u64 v[218:219], s[44:45], 0, v[128:129]
	global_load_lds_dwordx4 v[218:219], off
	s_mov_b32 m0, s55
	s_nop 0
	global_load_lds_dwordx4 v[220:221], off
	s_waitcnt vmcnt(8) lgkmcnt(0)
	s_barrier
	s_setprio 1
	v_mfma_f32_16x16x32_bf16 v[60:63], v[144:147], v[184:187], v[60:63]
	v_mfma_f32_16x16x32_bf16 v[60:63], v[148:151], v[188:191], v[60:63]
	v_mfma_f32_16x16x32_bf16 v[44:47], v[148:151], v[196:199], v[44:47]
	v_mfma_f32_16x16x32_bf16 v[44:47], v[144:147], v[192:195], v[44:47]
	v_mfma_f32_16x16x32_bf16 v[28:31], v[144:147], v[200:203], v[28:31]
	v_mfma_f32_16x16x32_bf16 v[28:31], v[148:151], v[204:207], v[28:31]
	v_mfma_f32_16x16x32_bf16 v[12:15], v[148:151], v[212:215], v[12:15]
	v_mfma_f32_16x16x32_bf16 v[12:15], v[144:147], v[208:211], v[12:15]
	v_mfma_f32_16x16x32_bf16 v[56:59], v[152:155], v[184:187], v[56:59]
	v_mfma_f32_16x16x32_bf16 v[56:59], v[156:159], v[188:191], v[56:59]
	v_mfma_f32_16x16x32_bf16 v[40:43], v[156:159], v[196:199], v[40:43]
	v_mfma_f32_16x16x32_bf16 v[40:43], v[152:155], v[192:195], v[40:43]
	v_mfma_f32_16x16x32_bf16 v[24:27], v[152:155], v[200:203], v[24:27]
	v_mfma_f32_16x16x32_bf16 v[24:27], v[156:159], v[204:207], v[24:27]
	v_mfma_f32_16x16x32_bf16 v[8:11], v[156:159], v[212:215], v[8:11]
	v_mfma_f32_16x16x32_bf16 v[8:11], v[152:155], v[208:211], v[8:11]
	v_mfma_f32_16x16x32_bf16 v[52:55], v[160:163], v[184:187], v[52:55]
	v_mfma_f32_16x16x32_bf16 v[52:55], v[164:167], v[188:191], v[52:55]
	v_mfma_f32_16x16x32_bf16 v[36:39], v[164:167], v[196:199], v[36:39]
	v_mfma_f32_16x16x32_bf16 v[36:39], v[160:163], v[192:195], v[36:39]
	v_mfma_f32_16x16x32_bf16 v[20:23], v[160:163], v[200:203], v[20:23]
	v_mfma_f32_16x16x32_bf16 v[20:23], v[164:167], v[204:207], v[20:23]
	v_mfma_f32_16x16x32_bf16 v[4:7], v[164:167], v[212:215], v[4:7]
	v_mfma_f32_16x16x32_bf16 v[4:7], v[160:163], v[208:211], v[4:7]
	v_mfma_f32_16x16x32_bf16 v[48:51], v[168:171], v[184:187], v[48:51]
	v_mfma_f32_16x16x32_bf16 v[48:51], v[172:175], v[188:191], v[48:51]
	v_mfma_f32_16x16x32_bf16 v[32:35], v[172:175], v[196:199], v[32:35]
	v_mfma_f32_16x16x32_bf16 v[32:35], v[168:171], v[192:195], v[32:35]
	s_setprio 2
	s_barrier
	v_mfma_f32_16x16x32_bf16 v[16:19], v[168:171], v[200:203], v[16:19]
	v_mfma_f32_16x16x32_bf16 v[16:19], v[172:175], v[204:207], v[16:19]
	v_mfma_f32_16x16x32_bf16 v[0:3], v[172:175], v[212:215], v[0:3]
	v_mfma_f32_16x16x32_bf16 v[0:3], v[168:171], v[208:211], v[0:3]
	s_setprio 0
	s_add_i32 s74, 0, 0x18000
	s_add_i32 s75, 0, 0x1c000
	v_add_u32_e32 v156, s74, v178
	v_add_u32_e32 v172, s75, v178
	ds_read_b128 v[144:147], v156
	ds_read_b128 v[148:151], v156 offset:1024
	ds_read_b128 v[152:155], v156 offset:2048
	ds_read_b128 v[156:159], v156 offset:3072
	ds_read_b128 v[160:163], v172
	ds_read_b128 v[164:167], v172 offset:1024
	ds_read_b128 v[168:171], v172 offset:2048
	ds_read_b128 v[172:175], v172 offset:3072
	s_add_u32 s44, s44, 0x40000
	s_addc_u32 s45, s45, 0
	s_mov_b32 m0, s56
	v_lshl_add_u64 v[222:223], s[44:45], 0, v[128:129]
	ds_read_b128 v[184:187], v181 offset:32768
	ds_read_b128 v[188:191], v181 offset:33792
	ds_read_b128 v[192:195], v181 offset:34816
	ds_read_b128 v[196:199], v181 offset:35840
	ds_read_b128 v[200:203], v181 offset:36864
	ds_read_b128 v[204:207], v181 offset:37888
	ds_read_b128 v[208:211], v181 offset:38912
	ds_read_b128 v[212:215], v181 offset:39936
	global_load_lds_dwordx4 v[222:223], off
	s_mov_b32 m0, s57
	v_lshl_add_u64 v[222:223], s[44:45], 0, v[132:133]
	global_load_lds_dwordx4 v[222:223], off
	s_waitcnt vmcnt(8) lgkmcnt(0)
	s_barrier
	s_setprio 1
	v_mfma_f32_16x16x32_bf16 v[124:127], v[144:147], v[184:187], v[124:127]
	v_mfma_f32_16x16x32_bf16 v[124:127], v[148:151], v[188:191], v[124:127]
	v_mfma_f32_16x16x32_bf16 v[108:111], v[148:151], v[196:199], v[108:111]
	v_mfma_f32_16x16x32_bf16 v[108:111], v[144:147], v[192:195], v[108:111]
	v_mfma_f32_16x16x32_bf16 v[92:95], v[144:147], v[200:203], v[92:95]
	v_mfma_f32_16x16x32_bf16 v[92:95], v[148:151], v[204:207], v[92:95]
	v_mfma_f32_16x16x32_bf16 v[76:79], v[148:151], v[212:215], v[76:79]
	v_mfma_f32_16x16x32_bf16 v[76:79], v[144:147], v[208:211], v[76:79]
	v_mfma_f32_16x16x32_bf16 v[120:123], v[152:155], v[184:187], v[120:123]
	v_mfma_f32_16x16x32_bf16 v[120:123], v[156:159], v[188:191], v[120:123]
	v_mfma_f32_16x16x32_bf16 v[104:107], v[156:159], v[196:199], v[104:107]
	v_mfma_f32_16x16x32_bf16 v[104:107], v[152:155], v[192:195], v[104:107]
	v_mfma_f32_16x16x32_bf16 v[88:91], v[152:155], v[200:203], v[88:91]
	v_mfma_f32_16x16x32_bf16 v[88:91], v[156:159], v[204:207], v[88:91]
	v_mfma_f32_16x16x32_bf16 v[72:75], v[156:159], v[212:215], v[72:75]
	v_mfma_f32_16x16x32_bf16 v[72:75], v[152:155], v[208:211], v[72:75]
	v_mfma_f32_16x16x32_bf16 v[116:119], v[160:163], v[184:187], v[116:119]
	v_mfma_f32_16x16x32_bf16 v[116:119], v[164:167], v[188:191], v[116:119]
	v_mfma_f32_16x16x32_bf16 v[100:103], v[164:167], v[196:199], v[100:103]
	v_mfma_f32_16x16x32_bf16 v[100:103], v[160:163], v[192:195], v[100:103]
	v_mfma_f32_16x16x32_bf16 v[84:87], v[160:163], v[200:203], v[84:87]
	v_mfma_f32_16x16x32_bf16 v[84:87], v[164:167], v[204:207], v[84:87]
	v_mfma_f32_16x16x32_bf16 v[68:71], v[164:167], v[212:215], v[68:71]
	v_mfma_f32_16x16x32_bf16 v[68:71], v[160:163], v[208:211], v[68:71]
	v_mfma_f32_16x16x32_bf16 v[112:115], v[168:171], v[184:187], v[112:115]
	v_mfma_f32_16x16x32_bf16 v[112:115], v[172:175], v[188:191], v[112:115]
	v_mfma_f32_16x16x32_bf16 v[96:99], v[172:175], v[196:199], v[96:99]
	v_mfma_f32_16x16x32_bf16 v[96:99], v[168:171], v[192:195], v[96:99]
	s_setprio 2
	s_barrier
	v_mfma_f32_16x16x32_bf16 v[80:83], v[168:171], v[200:203], v[80:83]
	v_mfma_f32_16x16x32_bf16 v[80:83], v[172:175], v[204:207], v[80:83]
	v_mfma_f32_16x16x32_bf16 v[64:67], v[172:175], v[212:215], v[64:67]
	v_mfma_f32_16x16x32_bf16 v[64:67], v[168:171], v[208:211], v[64:67]
	s_setprio 2
	s_add_i32 s44, s74, s51
	v_lshl_add_u64 v[176:177], v[176:177], 0, s[22:23]
	s_mov_b32 m0, s44
	ds_read_b128 v[184:187], v181 offset:49152
	ds_read_b128 v[188:191], v181 offset:50176
	ds_read_b128 v[192:195], v181 offset:51200
	ds_read_b128 v[196:199], v181 offset:52224
	ds_read_b128 v[200:203], v181 offset:53248
	ds_read_b128 v[204:207], v181 offset:54272
	ds_read_b128 v[208:211], v181 offset:55296
	ds_read_b128 v[212:215], v181 offset:56320
	global_load_lds_dwordx4 v[176:177], off
	s_add_i32 m0, s44, 0x2000
	s_add_u32 s40, s40, 0x40080
	v_lshl_add_u64 v[176:177], v[216:217], 0, s[22:23]
	s_addc_u32 s41, s41, 0
	s_add_i32 s44, s75, s51
	global_load_lds_dwordx4 v[176:177], off
	s_mov_b32 m0, s44
	v_lshl_add_u64 v[176:177], s[40:41], 0, v[130:131]
	global_load_lds_dwordx4 v[176:177], off
	s_add_i32 m0, s44, 0x2000
	v_lshl_add_u64 v[176:177], s[40:41], 0, v[134:135]
	global_load_lds_dwordx4 v[176:177], off
	s_mov_b32 m0, s64
	v_lshl_add_u64 v[176:177], v[218:219], 0, s[22:23]
	global_load_lds_dwordx4 v[176:177], off
	s_mov_b32 m0, s65
	v_lshl_add_u64 v[176:177], v[220:221], 0, s[22:23]
	global_load_lds_dwordx4 v[176:177], off
	s_waitcnt vmcnt(8) lgkmcnt(0)
	s_barrier
	s_setprio 1
	v_mfma_f32_16x16x32_bf16 v[60:63], v[144:147], v[184:187], v[60:63]
	v_mfma_f32_16x16x32_bf16 v[60:63], v[148:151], v[188:191], v[60:63]
	v_mfma_f32_16x16x32_bf16 v[44:47], v[148:151], v[196:199], v[44:47]
	v_mfma_f32_16x16x32_bf16 v[44:47], v[144:147], v[192:195], v[44:47]
	v_mfma_f32_16x16x32_bf16 v[28:31], v[144:147], v[200:203], v[28:31]
	v_mfma_f32_16x16x32_bf16 v[28:31], v[148:151], v[204:207], v[28:31]
	v_mfma_f32_16x16x32_bf16 v[12:15], v[148:151], v[212:215], v[12:15]
	v_mfma_f32_16x16x32_bf16 v[12:15], v[144:147], v[208:211], v[12:15]
	v_mfma_f32_16x16x32_bf16 v[56:59], v[152:155], v[184:187], v[56:59]
	v_mfma_f32_16x16x32_bf16 v[56:59], v[156:159], v[188:191], v[56:59]
	v_mfma_f32_16x16x32_bf16 v[40:43], v[156:159], v[196:199], v[40:43]
	v_mfma_f32_16x16x32_bf16 v[40:43], v[152:155], v[192:195], v[40:43]
	v_mfma_f32_16x16x32_bf16 v[24:27], v[152:155], v[200:203], v[24:27]
	v_mfma_f32_16x16x32_bf16 v[24:27], v[156:159], v[204:207], v[24:27]
	v_mfma_f32_16x16x32_bf16 v[8:11], v[156:159], v[212:215], v[8:11]
	v_mfma_f32_16x16x32_bf16 v[8:11], v[152:155], v[208:211], v[8:11]
	v_mfma_f32_16x16x32_bf16 v[52:55], v[160:163], v[184:187], v[52:55]
	v_mfma_f32_16x16x32_bf16 v[52:55], v[164:167], v[188:191], v[52:55]
	v_mfma_f32_16x16x32_bf16 v[36:39], v[164:167], v[196:199], v[36:39]
	v_mfma_f32_16x16x32_bf16 v[36:39], v[160:163], v[192:195], v[36:39]
	v_mfma_f32_16x16x32_bf16 v[20:23], v[160:163], v[200:203], v[20:23]
	v_mfma_f32_16x16x32_bf16 v[20:23], v[164:167], v[204:207], v[20:23]
	v_mfma_f32_16x16x32_bf16 v[4:7], v[164:167], v[212:215], v[4:7]
	v_mfma_f32_16x16x32_bf16 v[4:7], v[160:163], v[208:211], v[4:7]
	v_mfma_f32_16x16x32_bf16 v[48:51], v[168:171], v[184:187], v[48:51]
	v_mfma_f32_16x16x32_bf16 v[48:51], v[172:175], v[188:191], v[48:51]
	v_mfma_f32_16x16x32_bf16 v[32:35], v[172:175], v[196:199], v[32:35]
	v_mfma_f32_16x16x32_bf16 v[32:35], v[168:171], v[192:195], v[32:35]
	s_setprio 2
	s_barrier
	v_mfma_f32_16x16x32_bf16 v[16:19], v[168:171], v[200:203], v[16:19]
	v_mfma_f32_16x16x32_bf16 v[16:19], v[172:175], v[204:207], v[16:19]
	v_mfma_f32_16x16x32_bf16 v[0:3], v[172:175], v[212:215], v[0:3]
	v_mfma_f32_16x16x32_bf16 v[0:3], v[168:171], v[208:211], v[0:3]
	s_setprio 0
	s_add_i32 s73, s73, 2
	s_add_u32 s6, s6, 0x100
	s_addc_u32 s7, s7, 0
	s_add_u32 s71, s71, 0x100
	s_addc_u32 s72, s72, 0
	s_cmp_gt_u32 s73, 13
	s_cbranch_scc0 .LBB0_952

.LBB0_1145:
	s_ashr_i32 s23, s22, 31
	s_lshl_b64 s[26:27], s[22:23], 19
	s_add_u32 s26, s45, s26
	s_addc_u32 s27, s46, s27
	s_and_b64 s[28:29], s[4:5], exec
	s_cselect_b32 s23, s27, s39
	s_cselect_b32 s31, s26, s38
	s_ashr_i32 s25, s24, 31
	s_lshl_b64 s[28:29], s[24:25], 19
	s_add_u32 s28, s47, s28
	s_addc_u32 s29, s48, s29
	s_and_b64 s[42:43], s[4:5], exec
	s_cselect_b32 s25, s29, s41
	s_cselect_b32 s37, s28, s40
	s_add_u32 s38, s38, 0x40080
	s_addc_u32 s39, s39, 0
	s_add_u32 s64, s40, 0x100
	s_addc_u32 s65, s41, 0
	s_mov_b32 s66, -2
	ds_read_b128 v[120:123], v233
	ds_read_b128 v[132:135], v233 offset:1024
	ds_read_b128 v[136:139], v233 offset:2048
	ds_read_b128 v[140:143], v233 offset:3072
	ds_read_b128 v[144:147], v234
	ds_read_b128 v[148:151], v234 offset:1024
	ds_read_b128 v[152:155], v234 offset:2048
	ds_read_b128 v[156:159], v234 offset:3072
	s_add_u32 s40, s38, 0xfffc0080
	s_addc_u32 s41, s39, -1
	s_cmp_eq_u32 s66, 12
	s_cselect_b32 s43, s23, s41
	s_cselect_b32 s42, s31, s40
	s_cselect_b32 s41, s25, s65
	s_cselect_b32 s40, s37, s64
	v_lshl_add_u64 v[208:209], s[38:39], 0, v[192:193]
	s_add_i32 m0, s50, 0xc000
	ds_read_b128 v[160:163], v235
	ds_read_b128 v[164:167], v235 offset:1024
	ds_read_b128 v[168:171], v235 offset:2048
	ds_read_b128 v[172:175], v235 offset:3072
	ds_read_b128 v[176:179], v235 offset:4096
	ds_read_b128 v[180:183], v235 offset:5120
	ds_read_b128 v[200:203], v235 offset:6144
	ds_read_b128 v[204:207], v235 offset:7168
	global_load_lds_dwordx4 v[208:209], off
	s_add_i32 m0, s50, 0xe000
	v_lshl_add_u64 v[208:209], s[38:39], 0, v[194:195]
	global_load_lds_dwordx4 v[208:209], off
	s_waitcnt vmcnt(8) lgkmcnt(0)
	s_barrier
	s_setprio 1
	v_mfma_f32_16x16x32_bf16 v[128:131], v[120:123], v[160:163], 0
	v_mfma_f32_16x16x32_bf16 v[128:131], v[132:135], v[164:167], v[128:131]
	v_mfma_f32_16x16x32_bf16 v[108:111], v[132:135], v[172:175], 0
	v_mfma_f32_16x16x32_bf16 v[108:111], v[120:123], v[168:171], v[108:111]
	v_mfma_f32_16x16x32_bf16 v[92:95], v[120:123], v[176:179], 0
	v_mfma_f32_16x16x32_bf16 v[92:95], v[132:135], v[180:183], v[92:95]
	v_mfma_f32_16x16x32_bf16 v[76:79], v[132:135], v[204:207], 0
	v_mfma_f32_16x16x32_bf16 v[76:79], v[120:123], v[200:203], v[76:79]
	v_mfma_f32_16x16x32_bf16 v[124:127], v[136:139], v[160:163], 0
	v_mfma_f32_16x16x32_bf16 v[124:127], v[140:143], v[164:167], v[124:127]
	v_mfma_f32_16x16x32_bf16 v[104:107], v[140:143], v[172:175], 0
	v_mfma_f32_16x16x32_bf16 v[104:107], v[136:139], v[168:171], v[104:107]
	v_mfma_f32_16x16x32_bf16 v[88:91], v[136:139], v[176:179], 0
	v_mfma_f32_16x16x32_bf16 v[88:91], v[140:143], v[180:183], v[88:91]
	v_mfma_f32_16x16x32_bf16 v[72:75], v[140:143], v[204:207], 0
	v_mfma_f32_16x16x32_bf16 v[72:75], v[136:139], v[200:203], v[72:75]
	v_mfma_f32_16x16x32_bf16 v[116:119], v[144:147], v[160:163], 0
	v_mfma_f32_16x16x32_bf16 v[116:119], v[148:151], v[164:167], v[116:119]
	v_mfma_f32_16x16x32_bf16 v[100:103], v[148:151], v[172:175], 0
	v_mfma_f32_16x16x32_bf16 v[100:103], v[144:147], v[168:171], v[100:103]
	v_mfma_f32_16x16x32_bf16 v[84:87], v[144:147], v[176:179], 0
	v_mfma_f32_16x16x32_bf16 v[84:87], v[148:151], v[180:183], v[84:87]
	v_mfma_f32_16x16x32_bf16 v[68:71], v[148:151], v[204:207], 0
	v_mfma_f32_16x16x32_bf16 v[68:71], v[144:147], v[200:203], v[68:71]
	v_mfma_f32_16x16x32_bf16 v[112:115], v[152:155], v[160:163], 0
	v_mfma_f32_16x16x32_bf16 v[112:115], v[156:159], v[164:167], v[112:115]
	v_mfma_f32_16x16x32_bf16 v[96:99], v[156:159], v[172:175], 0
	v_mfma_f32_16x16x32_bf16 v[96:99], v[152:155], v[168:171], v[96:99]
	s_setprio 2
	s_barrier
	v_mfma_f32_16x16x32_bf16 v[80:83], v[152:155], v[176:179], 0
	v_mfma_f32_16x16x32_bf16 v[80:83], v[156:159], v[180:183], v[80:83]
	v_mfma_f32_16x16x32_bf16 v[64:67], v[156:159], v[204:207], 0
	v_mfma_f32_16x16x32_bf16 v[64:67], v[152:155], v[200:203], v[64:67]
	s_setprio 2
	s_add_i32 s67, s62, s49
	v_lshl_add_u64 v[208:209], s[40:41], 0, v[186:187]
	s_mov_b32 m0, s67
	ds_read_b128 v[160:163], v235 offset:16384
	ds_read_b128 v[164:167], v235 offset:17408
	ds_read_b128 v[168:171], v235 offset:18432
	ds_read_b128 v[172:175], v235 offset:19456
	ds_read_b128 v[176:179], v235 offset:20480
	ds_read_b128 v[180:183], v235 offset:21504
	ds_read_b128 v[200:203], v235 offset:22528
	ds_read_b128 v[204:207], v235 offset:23552
	global_load_lds_dwordx4 v[208:209], off
	s_add_i32 m0, s67, 0x2000
	s_add_u32 s68, s40, 0x40000
	v_lshl_add_u64 v[210:211], s[40:41], 0, v[190:191]
	s_addc_u32 s69, s41, 0
	s_add_i32 s67, s63, s49
	global_load_lds_dwordx4 v[210:211], off
	v_lshl_add_u64 v[212:213], s[68:69], 0, v[186:187]
	s_mov_b32 m0, s67
	v_lshl_add_u64 v[214:215], s[42:43], 0, v[188:189]
	global_load_lds_dwordx4 v[212:213], off
	s_add_i32 m0, s67, 0x2000
	v_lshl_add_u64 v[212:213], s[68:69], 0, v[190:191]
	global_load_lds_dwordx4 v[212:213], off
	s_mov_b32 m0, s50
	v_lshl_add_u64 v[212:213], s[42:43], 0, v[184:185]
	global_load_lds_dwordx4 v[212:213], off
	s_mov_b32 m0, s51
	s_nop 0
	global_load_lds_dwordx4 v[214:215], off
	s_waitcnt vmcnt(8) lgkmcnt(0)
	s_barrier
	s_setprio 1
	v_mfma_f32_16x16x32_bf16 v[60:63], v[120:123], v[160:163], 0
	v_mfma_f32_16x16x32_bf16 v[60:63], v[132:135], v[164:167], v[60:63]
	v_mfma_f32_16x16x32_bf16 v[44:47], v[132:135], v[172:175], 0
	v_mfma_f32_16x16x32_bf16 v[44:47], v[120:123], v[168:171], v[44:47]
	v_mfma_f32_16x16x32_bf16 v[28:31], v[120:123], v[176:179], 0
	v_mfma_f32_16x16x32_bf16 v[28:31], v[132:135], v[180:183], v[28:31]
	v_mfma_f32_16x16x32_bf16 v[12:15], v[132:135], v[204:207], 0
	v_mfma_f32_16x16x32_bf16 v[12:15], v[120:123], v[200:203], v[12:15]
	v_mfma_f32_16x16x32_bf16 v[56:59], v[136:139], v[160:163], 0
	v_mfma_f32_16x16x32_bf16 v[56:59], v[140:143], v[164:167], v[56:59]
	v_mfma_f32_16x16x32_bf16 v[40:43], v[140:143], v[172:175], 0
	v_mfma_f32_16x16x32_bf16 v[40:43], v[136:139], v[168:171], v[40:43]
	v_mfma_f32_16x16x32_bf16 v[24:27], v[136:139], v[176:179], 0
	v_mfma_f32_16x16x32_bf16 v[24:27], v[140:143], v[180:183], v[24:27]
	v_mfma_f32_16x16x32_bf16 v[8:11], v[140:143], v[204:207], 0
	v_mfma_f32_16x16x32_bf16 v[8:11], v[136:139], v[200:203], v[8:11]
	v_mfma_f32_16x16x32_bf16 v[52:55], v[144:147], v[160:163], 0
	v_mfma_f32_16x16x32_bf16 v[52:55], v[148:151], v[164:167], v[52:55]
	v_mfma_f32_16x16x32_bf16 v[36:39], v[148:151], v[172:175], 0
	v_mfma_f32_16x16x32_bf16 v[36:39], v[144:147], v[168:171], v[36:39]
	v_mfma_f32_16x16x32_bf16 v[20:23], v[144:147], v[176:179], 0
	v_mfma_f32_16x16x32_bf16 v[20:23], v[148:151], v[180:183], v[20:23]
	v_mfma_f32_16x16x32_bf16 v[4:7], v[148:151], v[204:207], 0
	v_mfma_f32_16x16x32_bf16 v[4:7], v[144:147], v[200:203], v[4:7]
	v_mfma_f32_16x16x32_bf16 v[48:51], v[152:155], v[160:163], 0
	v_mfma_f32_16x16x32_bf16 v[48:51], v[156:159], v[164:167], v[48:51]
	v_mfma_f32_16x16x32_bf16 v[32:35], v[156:159], v[172:175], 0
	v_mfma_f32_16x16x32_bf16 v[32:35], v[152:155], v[168:171], v[32:35]
	s_setprio 2
	s_barrier
	v_mfma_f32_16x16x32_bf16 v[16:19], v[152:155], v[176:179], 0
	v_mfma_f32_16x16x32_bf16 v[16:19], v[156:159], v[180:183], v[16:19]
	v_mfma_f32_16x16x32_bf16 v[0:3], v[156:159], v[204:207], 0
	v_mfma_f32_16x16x32_bf16 v[0:3], v[152:155], v[200:203], v[0:3]
	s_setprio 0
	s_add_i32 s67, 0, 0x18000
	s_add_i32 s68, 0, 0x1c000
	v_add_u32_e32 v140, s67, v232
	v_add_u32_e32 v156, s68, v232
	ds_read_b128 v[120:123], v140
	ds_read_b128 v[132:135], v140 offset:1024
	ds_read_b128 v[136:139], v140 offset:2048
	ds_read_b128 v[140:143], v140 offset:3072
	ds_read_b128 v[144:147], v156
	ds_read_b128 v[148:151], v156 offset:1024
	ds_read_b128 v[152:155], v156 offset:2048
	ds_read_b128 v[156:159], v156 offset:3072
	s_add_u32 s42, s42, 0x40000
	s_addc_u32 s43, s43, 0
	s_mov_b32 m0, s54
	v_lshl_add_u64 v[216:217], s[42:43], 0, v[184:185]
	ds_read_b128 v[160:163], v235 offset:32768
	ds_read_b128 v[164:167], v235 offset:33792
	ds_read_b128 v[168:171], v235 offset:34816
	ds_read_b128 v[172:175], v235 offset:35840
	ds_read_b128 v[176:179], v235 offset:36864
	ds_read_b128 v[180:183], v235 offset:37888
	ds_read_b128 v[200:203], v235 offset:38912
	ds_read_b128 v[204:207], v235 offset:39936
	global_load_lds_dwordx4 v[216:217], off
	s_mov_b32 m0, s55
	v_lshl_add_u64 v[216:217], s[42:43], 0, v[188:189]
	global_load_lds_dwordx4 v[216:217], off
	s_waitcnt vmcnt(8) lgkmcnt(0)
	s_barrier
	s_setprio 1
	v_mfma_f32_16x16x32_bf16 v[128:131], v[120:123], v[160:163], v[128:131]
	v_mfma_f32_16x16x32_bf16 v[128:131], v[132:135], v[164:167], v[128:131]
	v_mfma_f32_16x16x32_bf16 v[108:111], v[132:135], v[172:175], v[108:111]
	v_mfma_f32_16x16x32_bf16 v[108:111], v[120:123], v[168:171], v[108:111]
	v_mfma_f32_16x16x32_bf16 v[92:95], v[120:123], v[176:179], v[92:95]
	v_mfma_f32_16x16x32_bf16 v[92:95], v[132:135], v[180:183], v[92:95]
	v_mfma_f32_16x16x32_bf16 v[76:79], v[132:135], v[204:207], v[76:79]
	v_mfma_f32_16x16x32_bf16 v[76:79], v[120:123], v[200:203], v[76:79]
	v_mfma_f32_16x16x32_bf16 v[124:127], v[136:139], v[160:163], v[124:127]
	v_mfma_f32_16x16x32_bf16 v[124:127], v[140:143], v[164:167], v[124:127]
	v_mfma_f32_16x16x32_bf16 v[104:107], v[140:143], v[172:175], v[104:107]
	v_mfma_f32_16x16x32_bf16 v[104:107], v[136:139], v[168:171], v[104:107]
	v_mfma_f32_16x16x32_bf16 v[88:91], v[136:139], v[176:179], v[88:91]
	v_mfma_f32_16x16x32_bf16 v[88:91], v[140:143], v[180:183], v[88:91]
	v_mfma_f32_16x16x32_bf16 v[72:75], v[140:143], v[204:207], v[72:75]
	v_mfma_f32_16x16x32_bf16 v[72:75], v[136:139], v[200:203], v[72:75]
	v_mfma_f32_16x16x32_bf16 v[116:119], v[144:147], v[160:163], v[116:119]
	v_mfma_f32_16x16x32_bf16 v[116:119], v[148:151], v[164:167], v[116:119]
	v_mfma_f32_16x16x32_bf16 v[100:103], v[148:151], v[172:175], v[100:103]
	v_mfma_f32_16x16x32_bf16 v[100:103], v[144:147], v[168:171], v[100:103]
	v_mfma_f32_16x16x32_bf16 v[84:87], v[144:147], v[176:179], v[84:87]
	v_mfma_f32_16x16x32_bf16 v[84:87], v[148:151], v[180:183], v[84:87]
	v_mfma_f32_16x16x32_bf16 v[68:71], v[148:151], v[204:207], v[68:71]
	v_mfma_f32_16x16x32_bf16 v[68:71], v[144:147], v[200:203], v[68:71]
	v_mfma_f32_16x16x32_bf16 v[112:115], v[152:155], v[160:163], v[112:115]
	v_mfma_f32_16x16x32_bf16 v[112:115], v[156:159], v[164:167], v[112:115]
	v_mfma_f32_16x16x32_bf16 v[96:99], v[156:159], v[172:175], v[96:99]
	v_mfma_f32_16x16x32_bf16 v[96:99], v[152:155], v[168:171], v[96:99]
	s_setprio 2
	s_barrier
	v_mfma_f32_16x16x32_bf16 v[80:83], v[152:155], v[176:179], v[80:83]
	v_mfma_f32_16x16x32_bf16 v[80:83], v[156:159], v[180:183], v[80:83]
	v_mfma_f32_16x16x32_bf16 v[64:67], v[156:159], v[204:207], v[64:67]
	v_mfma_f32_16x16x32_bf16 v[64:67], v[152:155], v[200:203], v[64:67]
	s_setprio 2
	s_add_i32 s42, s67, s49
	v_lshl_add_u64 v[208:209], v[208:209], 0, s[18:19]
	s_mov_b32 m0, s42
	ds_read_b128 v[160:163], v235 offset:49152
	ds_read_b128 v[164:167], v235 offset:50176
	ds_read_b128 v[168:171], v235 offset:51200
	ds_read_b128 v[172:175], v235 offset:52224
	ds_read_b128 v[176:179], v235 offset:53248
	ds_read_b128 v[180:183], v235 offset:54272
	ds_read_b128 v[200:203], v235 offset:55296
	ds_read_b128 v[204:207], v235 offset:56320
	global_load_lds_dwordx4 v[208:209], off
	s_add_i32 m0, s42, 0x2000
	s_add_u32 s40, s40, 0x40080
	v_lshl_add_u64 v[208:209], v[210:211], 0, s[18:19]
	s_addc_u32 s41, s41, 0
	s_add_i32 s42, s68, s49
	global_load_lds_dwordx4 v[208:209], off
	s_mov_b32 m0, s42
	v_lshl_add_u64 v[208:209], s[40:41], 0, v[186:187]
	global_load_lds_dwordx4 v[208:209], off
	s_add_i32 m0, s42, 0x2000
	v_lshl_add_u64 v[208:209], s[40:41], 0, v[190:191]
	global_load_lds_dwordx4 v[208:209], off
	s_mov_b32 m0, s57
	v_lshl_add_u64 v[208:209], v[212:213], 0, s[18:19]
	global_load_lds_dwordx4 v[208:209], off
	s_mov_b32 m0, s58
	v_lshl_add_u64 v[208:209], v[214:215], 0, s[18:19]
	global_load_lds_dwordx4 v[208:209], off
	s_waitcnt vmcnt(8) lgkmcnt(0)
	s_barrier
	s_setprio 1
	v_mfma_f32_16x16x32_bf16 v[60:63], v[120:123], v[160:163], v[60:63]
	v_mfma_f32_16x16x32_bf16 v[60:63], v[132:135], v[164:167], v[60:63]
	v_mfma_f32_16x16x32_bf16 v[44:47], v[132:135], v[172:175], v[44:47]
	v_mfma_f32_16x16x32_bf16 v[44:47], v[120:123], v[168:171], v[44:47]
	v_mfma_f32_16x16x32_bf16 v[28:31], v[120:123], v[176:179], v[28:31]
	v_mfma_f32_16x16x32_bf16 v[28:31], v[132:135], v[180:183], v[28:31]
	v_mfma_f32_16x16x32_bf16 v[12:15], v[132:135], v[204:207], v[12:15]
	v_mfma_f32_16x16x32_bf16 v[12:15], v[120:123], v[200:203], v[12:15]
	v_mfma_f32_16x16x32_bf16 v[56:59], v[136:139], v[160:163], v[56:59]
	v_mfma_f32_16x16x32_bf16 v[56:59], v[140:143], v[164:167], v[56:59]
	v_mfma_f32_16x16x32_bf16 v[40:43], v[140:143], v[172:175], v[40:43]
	v_mfma_f32_16x16x32_bf16 v[40:43], v[136:139], v[168:171], v[40:43]
	v_mfma_f32_16x16x32_bf16 v[24:27], v[136:139], v[176:179], v[24:27]
	v_mfma_f32_16x16x32_bf16 v[24:27], v[140:143], v[180:183], v[24:27]
	v_mfma_f32_16x16x32_bf16 v[8:11], v[140:143], v[204:207], v[8:11]
	v_mfma_f32_16x16x32_bf16 v[8:11], v[136:139], v[200:203], v[8:11]
	v_mfma_f32_16x16x32_bf16 v[52:55], v[144:147], v[160:163], v[52:55]
	v_mfma_f32_16x16x32_bf16 v[52:55], v[148:151], v[164:167], v[52:55]
	v_mfma_f32_16x16x32_bf16 v[36:39], v[148:151], v[172:175], v[36:39]
	v_mfma_f32_16x16x32_bf16 v[36:39], v[144:147], v[168:171], v[36:39]
	v_mfma_f32_16x16x32_bf16 v[20:23], v[144:147], v[176:179], v[20:23]
	v_mfma_f32_16x16x32_bf16 v[20:23], v[148:151], v[180:183], v[20:23]
	v_mfma_f32_16x16x32_bf16 v[4:7], v[148:151], v[204:207], v[4:7]
	v_mfma_f32_16x16x32_bf16 v[4:7], v[144:147], v[200:203], v[4:7]
	v_mfma_f32_16x16x32_bf16 v[48:51], v[152:155], v[160:163], v[48:51]
	v_mfma_f32_16x16x32_bf16 v[48:51], v[156:159], v[164:167], v[48:51]
	v_mfma_f32_16x16x32_bf16 v[32:35], v[156:159], v[172:175], v[32:35]
	v_mfma_f32_16x16x32_bf16 v[32:35], v[152:155], v[168:171], v[32:35]
	s_setprio 2
	s_barrier
	v_mfma_f32_16x16x32_bf16 v[16:19], v[152:155], v[176:179], v[16:19]
	v_mfma_f32_16x16x32_bf16 v[16:19], v[156:159], v[180:183], v[16:19]
	v_mfma_f32_16x16x32_bf16 v[0:3], v[156:159], v[204:207], v[0:3]
	v_mfma_f32_16x16x32_bf16 v[0:3], v[152:155], v[200:203], v[0:3]
	s_setprio 0
	s_add_i32 s66, s66, 2
	s_add_u32 s38, s38, 0x100
	s_addc_u32 s39, s39, 0
	s_add_u32 s64, s64, 0x100
	s_addc_u32 s65, s65, 0
	s_cmp_gt_u32 s66, 13
.LBB0_1146:
	ds_read_b128 v[120:123], v233
	ds_read_b128 v[132:135], v233 offset:1024
	ds_read_b128 v[136:139], v233 offset:2048
	ds_read_b128 v[140:143], v233 offset:3072
	ds_read_b128 v[144:147], v234
	ds_read_b128 v[148:151], v234 offset:1024
	ds_read_b128 v[152:155], v234 offset:2048
	ds_read_b128 v[156:159], v234 offset:3072
	s_add_u32 s40, s38, 0xfffc0080
	s_addc_u32 s41, s39, -1
	s_cmp_eq_u32 s66, 12
	s_cselect_b32 s43, s23, s41
	s_cselect_b32 s42, s31, s40
	s_cselect_b32 s41, s25, s65
	s_cselect_b32 s40, s37, s64
	v_lshl_add_u64 v[208:209], s[38:39], 0, v[192:193]
	s_add_i32 m0, s50, 0xc000
	ds_read_b128 v[160:163], v235
	ds_read_b128 v[164:167], v235 offset:1024
	ds_read_b128 v[168:171], v235 offset:2048
	ds_read_b128 v[172:175], v235 offset:3072
	ds_read_b128 v[176:179], v235 offset:4096
	ds_read_b128 v[180:183], v235 offset:5120
	ds_read_b128 v[200:203], v235 offset:6144
	ds_read_b128 v[204:207], v235 offset:7168
	global_load_lds_dwordx4 v[208:209], off
	s_add_i32 m0, s50, 0xe000
	v_lshl_add_u64 v[208:209], s[38:39], 0, v[194:195]
	global_load_lds_dwordx4 v[208:209], off
	s_waitcnt vmcnt(8) lgkmcnt(0)
	s_barrier
	s_setprio 1
	v_mfma_f32_16x16x32_bf16 v[128:131], v[120:123], v[160:163], v[128:131]
	v_mfma_f32_16x16x32_bf16 v[128:131], v[132:135], v[164:167], v[128:131]
	v_mfma_f32_16x16x32_bf16 v[108:111], v[132:135], v[172:175], v[108:111]
	v_mfma_f32_16x16x32_bf16 v[108:111], v[120:123], v[168:171], v[108:111]
	v_mfma_f32_16x16x32_bf16 v[92:95], v[120:123], v[176:179], v[92:95]
	v_mfma_f32_16x16x32_bf16 v[92:95], v[132:135], v[180:183], v[92:95]
	v_mfma_f32_16x16x32_bf16 v[76:79], v[132:135], v[204:207], v[76:79]
	v_mfma_f32_16x16x32_bf16 v[76:79], v[120:123], v[200:203], v[76:79]
	v_mfma_f32_16x16x32_bf16 v[124:127], v[136:139], v[160:163], v[124:127]
	v_mfma_f32_16x16x32_bf16 v[124:127], v[140:143], v[164:167], v[124:127]
	v_mfma_f32_16x16x32_bf16 v[104:107], v[140:143], v[172:175], v[104:107]
	v_mfma_f32_16x16x32_bf16 v[104:107], v[136:139], v[168:171], v[104:107]
	v_mfma_f32_16x16x32_bf16 v[88:91], v[136:139], v[176:179], v[88:91]
	v_mfma_f32_16x16x32_bf16 v[88:91], v[140:143], v[180:183], v[88:91]
	v_mfma_f32_16x16x32_bf16 v[72:75], v[140:143], v[204:207], v[72:75]
	v_mfma_f32_16x16x32_bf16 v[72:75], v[136:139], v[200:203], v[72:75]
	v_mfma_f32_16x16x32_bf16 v[116:119], v[144:147], v[160:163], v[116:119]
	v_mfma_f32_16x16x32_bf16 v[116:119], v[148:151], v[164:167], v[116:119]
	v_mfma_f32_16x16x32_bf16 v[100:103], v[148:151], v[172:175], v[100:103]
	v_mfma_f32_16x16x32_bf16 v[100:103], v[144:147], v[168:171], v[100:103]
	v_mfma_f32_16x16x32_bf16 v[84:87], v[144:147], v[176:179], v[84:87]
	v_mfma_f32_16x16x32_bf16 v[84:87], v[148:151], v[180:183], v[84:87]
	v_mfma_f32_16x16x32_bf16 v[68:71], v[148:151], v[204:207], v[68:71]
	v_mfma_f32_16x16x32_bf16 v[68:71], v[144:147], v[200:203], v[68:71]
	v_mfma_f32_16x16x32_bf16 v[112:115], v[152:155], v[160:163], v[112:115]
	v_mfma_f32_16x16x32_bf16 v[112:115], v[156:159], v[164:167], v[112:115]
	v_mfma_f32_16x16x32_bf16 v[96:99], v[156:159], v[172:175], v[96:99]
	v_mfma_f32_16x16x32_bf16 v[96:99], v[152:155], v[168:171], v[96:99]
	s_setprio 2
	s_barrier
	v_mfma_f32_16x16x32_bf16 v[80:83], v[152:155], v[176:179], v[80:83]
	v_mfma_f32_16x16x32_bf16 v[80:83], v[156:159], v[180:183], v[80:83]
	v_mfma_f32_16x16x32_bf16 v[64:67], v[156:159], v[204:207], v[64:67]
	v_mfma_f32_16x16x32_bf16 v[64:67], v[152:155], v[200:203], v[64:67]
	s_setprio 2
	s_add_i32 s67, s62, s49
	v_lshl_add_u64 v[208:209], s[40:41], 0, v[186:187]
	s_mov_b32 m0, s67
	ds_read_b128 v[160:163], v235 offset:16384
	ds_read_b128 v[164:167], v235 offset:17408
	ds_read_b128 v[168:171], v235 offset:18432
	ds_read_b128 v[172:175], v235 offset:19456
	ds_read_b128 v[176:179], v235 offset:20480
	ds_read_b128 v[180:183], v235 offset:21504
	ds_read_b128 v[200:203], v235 offset:22528
	ds_read_b128 v[204:207], v235 offset:23552
	global_load_lds_dwordx4 v[208:209], off
	s_add_i32 m0, s67, 0x2000
	s_add_u32 s68, s40, 0x40000
	v_lshl_add_u64 v[210:211], s[40:41], 0, v[190:191]
	s_addc_u32 s69, s41, 0
	s_add_i32 s67, s63, s49
	global_load_lds_dwordx4 v[210:211], off
	v_lshl_add_u64 v[212:213], s[68:69], 0, v[186:187]
	s_mov_b32 m0, s67
	v_lshl_add_u64 v[214:215], s[42:43], 0, v[188:189]
	global_load_lds_dwordx4 v[212:213], off
	s_add_i32 m0, s67, 0x2000
	v_lshl_add_u64 v[212:213], s[68:69], 0, v[190:191]
	global_load_lds_dwordx4 v[212:213], off
	s_mov_b32 m0, s50
	v_lshl_add_u64 v[212:213], s[42:43], 0, v[184:185]
	global_load_lds_dwordx4 v[212:213], off
	s_mov_b32 m0, s51
	s_nop 0
	global_load_lds_dwordx4 v[214:215], off
	s_waitcnt vmcnt(8) lgkmcnt(0)
	s_barrier
	s_setprio 1
	v_mfma_f32_16x16x32_bf16 v[60:63], v[120:123], v[160:163], v[60:63]
	v_mfma_f32_16x16x32_bf16 v[60:63], v[132:135], v[164:167], v[60:63]
	v_mfma_f32_16x16x32_bf16 v[44:47], v[132:135], v[172:175], v[44:47]
	v_mfma_f32_16x16x32_bf16 v[44:47], v[120:123], v[168:171], v[44:47]
	v_mfma_f32_16x16x32_bf16 v[28:31], v[120:123], v[176:179], v[28:31]
	v_mfma_f32_16x16x32_bf16 v[28:31], v[132:135], v[180:183], v[28:31]
	v_mfma_f32_16x16x32_bf16 v[12:15], v[132:135], v[204:207], v[12:15]
	v_mfma_f32_16x16x32_bf16 v[12:15], v[120:123], v[200:203], v[12:15]
	v_mfma_f32_16x16x32_bf16 v[56:59], v[136:139], v[160:163], v[56:59]
	v_mfma_f32_16x16x32_bf16 v[56:59], v[140:143], v[164:167], v[56:59]
	v_mfma_f32_16x16x32_bf16 v[40:43], v[140:143], v[172:175], v[40:43]
	v_mfma_f32_16x16x32_bf16 v[40:43], v[136:139], v[168:171], v[40:43]
	v_mfma_f32_16x16x32_bf16 v[24:27], v[136:139], v[176:179], v[24:27]
	v_mfma_f32_16x16x32_bf16 v[24:27], v[140:143], v[180:183], v[24:27]
	v_mfma_f32_16x16x32_bf16 v[8:11], v[140:143], v[204:207], v[8:11]
	v_mfma_f32_16x16x32_bf16 v[8:11], v[136:139], v[200:203], v[8:11]
	v_mfma_f32_16x16x32_bf16 v[52:55], v[144:147], v[160:163], v[52:55]
	v_mfma_f32_16x16x32_bf16 v[52:55], v[148:151], v[164:167], v[52:55]
	v_mfma_f32_16x16x32_bf16 v[36:39], v[148:151], v[172:175], v[36:39]
	v_mfma_f32_16x16x32_bf16 v[36:39], v[144:147], v[168:171], v[36:39]
	v_mfma_f32_16x16x32_bf16 v[20:23], v[144:147], v[176:179], v[20:23]
	v_mfma_f32_16x16x32_bf16 v[20:23], v[148:151], v[180:183], v[20:23]
	v_mfma_f32_16x16x32_bf16 v[4:7], v[148:151], v[204:207], v[4:7]
	v_mfma_f32_16x16x32_bf16 v[4:7], v[144:147], v[200:203], v[4:7]
	v_mfma_f32_16x16x32_bf16 v[48:51], v[152:155], v[160:163], v[48:51]
	v_mfma_f32_16x16x32_bf16 v[48:51], v[156:159], v[164:167], v[48:51]
	v_mfma_f32_16x16x32_bf16 v[32:35], v[156:159], v[172:175], v[32:35]
	v_mfma_f32_16x16x32_bf16 v[32:35], v[152:155], v[168:171], v[32:35]
	s_setprio 2
	s_barrier
	v_mfma_f32_16x16x32_bf16 v[16:19], v[152:155], v[176:179], v[16:19]
	v_mfma_f32_16x16x32_bf16 v[16:19], v[156:159], v[180:183], v[16:19]
	v_mfma_f32_16x16x32_bf16 v[0:3], v[156:159], v[204:207], v[0:3]
	v_mfma_f32_16x16x32_bf16 v[0:3], v[152:155], v[200:203], v[0:3]
	s_setprio 0
	s_add_i32 s67, 0, 0x18000
	s_add_i32 s68, 0, 0x1c000
	v_add_u32_e32 v140, s67, v232
	v_add_u32_e32 v156, s68, v232
	ds_read_b128 v[120:123], v140
	ds_read_b128 v[132:135], v140 offset:1024
	ds_read_b128 v[136:139], v140 offset:2048
	ds_read_b128 v[140:143], v140 offset:3072
	ds_read_b128 v[144:147], v156
	ds_read_b128 v[148:151], v156 offset:1024
	ds_read_b128 v[152:155], v156 offset:2048
	ds_read_b128 v[156:159], v156 offset:3072
	s_add_u32 s42, s42, 0x40000
	s_addc_u32 s43, s43, 0
	s_mov_b32 m0, s54
	v_lshl_add_u64 v[216:217], s[42:43], 0, v[184:185]
	ds_read_b128 v[160:163], v235 offset:32768
	ds_read_b128 v[164:167], v235 offset:33792
	ds_read_b128 v[168:171], v235 offset:34816
	ds_read_b128 v[172:175], v235 offset:35840
	ds_read_b128 v[176:179], v235 offset:36864
	ds_read_b128 v[180:183], v235 offset:37888
	ds_read_b128 v[200:203], v235 offset:38912
	ds_read_b128 v[204:207], v235 offset:39936
	global_load_lds_dwordx4 v[216:217], off
	s_mov_b32 m0, s55
	v_lshl_add_u64 v[216:217], s[42:43], 0, v[188:189]
	global_load_lds_dwordx4 v[216:217], off
	s_waitcnt vmcnt(8) lgkmcnt(0)
	s_barrier
	s_setprio 1
	v_mfma_f32_16x16x32_bf16 v[128:131], v[120:123], v[160:163], v[128:131]
	v_mfma_f32_16x16x32_bf16 v[128:131], v[132:135], v[164:167], v[128:131]
	v_mfma_f32_16x16x32_bf16 v[108:111], v[132:135], v[172:175], v[108:111]
	v_mfma_f32_16x16x32_bf16 v[108:111], v[120:123], v[168:171], v[108:111]
	v_mfma_f32_16x16x32_bf16 v[92:95], v[120:123], v[176:179], v[92:95]
	v_mfma_f32_16x16x32_bf16 v[92:95], v[132:135], v[180:183], v[92:95]
	v_mfma_f32_16x16x32_bf16 v[76:79], v[132:135], v[204:207], v[76:79]
	v_mfma_f32_16x16x32_bf16 v[76:79], v[120:123], v[200:203], v[76:79]
	v_mfma_f32_16x16x32_bf16 v[124:127], v[136:139], v[160:163], v[124:127]
	v_mfma_f32_16x16x32_bf16 v[124:127], v[140:143], v[164:167], v[124:127]
	v_mfma_f32_16x16x32_bf16 v[104:107], v[140:143], v[172:175], v[104:107]
	v_mfma_f32_16x16x32_bf16 v[104:107], v[136:139], v[168:171], v[104:107]
	v_mfma_f32_16x16x32_bf16 v[88:91], v[136:139], v[176:179], v[88:91]
	v_mfma_f32_16x16x32_bf16 v[88:91], v[140:143], v[180:183], v[88:91]
	v_mfma_f32_16x16x32_bf16 v[72:75], v[140:143], v[204:207], v[72:75]
	v_mfma_f32_16x16x32_bf16 v[72:75], v[136:139], v[200:203], v[72:75]
	v_mfma_f32_16x16x32_bf16 v[116:119], v[144:147], v[160:163], v[116:119]
	v_mfma_f32_16x16x32_bf16 v[116:119], v[148:151], v[164:167], v[116:119]
	v_mfma_f32_16x16x32_bf16 v[100:103], v[148:151], v[172:175], v[100:103]
	v_mfma_f32_16x16x32_bf16 v[100:103], v[144:147], v[168:171], v[100:103]
	v_mfma_f32_16x16x32_bf16 v[84:87], v[144:147], v[176:179], v[84:87]
	v_mfma_f32_16x16x32_bf16 v[84:87], v[148:151], v[180:183], v[84:87]
	v_mfma_f32_16x16x32_bf16 v[68:71], v[148:151], v[204:207], v[68:71]
	v_mfma_f32_16x16x32_bf16 v[68:71], v[144:147], v[200:203], v[68:71]
	v_mfma_f32_16x16x32_bf16 v[112:115], v[152:155], v[160:163], v[112:115]
	v_mfma_f32_16x16x32_bf16 v[112:115], v[156:159], v[164:167], v[112:115]
	v_mfma_f32_16x16x32_bf16 v[96:99], v[156:159], v[172:175], v[96:99]
	v_mfma_f32_16x16x32_bf16 v[96:99], v[152:155], v[168:171], v[96:99]
	s_setprio 2
	s_barrier
	v_mfma_f32_16x16x32_bf16 v[80:83], v[152:155], v[176:179], v[80:83]
	v_mfma_f32_16x16x32_bf16 v[80:83], v[156:159], v[180:183], v[80:83]
	v_mfma_f32_16x16x32_bf16 v[64:67], v[156:159], v[204:207], v[64:67]
	v_mfma_f32_16x16x32_bf16 v[64:67], v[152:155], v[200:203], v[64:67]
	s_setprio 2
	s_add_i32 s42, s67, s49
	v_lshl_add_u64 v[208:209], v[208:209], 0, s[18:19]
	s_mov_b32 m0, s42
	ds_read_b128 v[160:163], v235 offset:49152
	ds_read_b128 v[164:167], v235 offset:50176
	ds_read_b128 v[168:171], v235 offset:51200
	ds_read_b128 v[172:175], v235 offset:52224
	ds_read_b128 v[176:179], v235 offset:53248
	ds_read_b128 v[180:183], v235 offset:54272
	ds_read_b128 v[200:203], v235 offset:55296
	ds_read_b128 v[204:207], v235 offset:56320
	global_load_lds_dwordx4 v[208:209], off
	s_add_i32 m0, s42, 0x2000
	s_add_u32 s40, s40, 0x40080
	v_lshl_add_u64 v[208:209], v[210:211], 0, s[18:19]
	s_addc_u32 s41, s41, 0
	s_add_i32 s42, s68, s49
	global_load_lds_dwordx4 v[208:209], off
	s_mov_b32 m0, s42
	v_lshl_add_u64 v[208:209], s[40:41], 0, v[186:187]
	global_load_lds_dwordx4 v[208:209], off
	s_add_i32 m0, s42, 0x2000
	v_lshl_add_u64 v[208:209], s[40:41], 0, v[190:191]
	global_load_lds_dwordx4 v[208:209], off
	s_mov_b32 m0, s57
	v_lshl_add_u64 v[208:209], v[212:213], 0, s[18:19]
	global_load_lds_dwordx4 v[208:209], off
	s_mov_b32 m0, s58
	v_lshl_add_u64 v[208:209], v[214:215], 0, s[18:19]
	global_load_lds_dwordx4 v[208:209], off
	s_waitcnt vmcnt(8) lgkmcnt(0)
	s_barrier
	s_setprio 1
	v_mfma_f32_16x16x32_bf16 v[60:63], v[120:123], v[160:163], v[60:63]
	v_mfma_f32_16x16x32_bf16 v[60:63], v[132:135], v[164:167], v[60:63]
	v_mfma_f32_16x16x32_bf16 v[44:47], v[132:135], v[172:175], v[44:47]
	v_mfma_f32_16x16x32_bf16 v[44:47], v[120:123], v[168:171], v[44:47]
	v_mfma_f32_16x16x32_bf16 v[28:31], v[120:123], v[176:179], v[28:31]
	v_mfma_f32_16x16x32_bf16 v[28:31], v[132:135], v[180:183], v[28:31]
	v_mfma_f32_16x16x32_bf16 v[12:15], v[132:135], v[204:207], v[12:15]
	v_mfma_f32_16x16x32_bf16 v[12:15], v[120:123], v[200:203], v[12:15]
	v_mfma_f32_16x16x32_bf16 v[56:59], v[136:139], v[160:163], v[56:59]
	v_mfma_f32_16x16x32_bf16 v[56:59], v[140:143], v[164:167], v[56:59]
	v_mfma_f32_16x16x32_bf16 v[40:43], v[140:143], v[172:175], v[40:43]
	v_mfma_f32_16x16x32_bf16 v[40:43], v[136:139], v[168:171], v[40:43]
	v_mfma_f32_16x16x32_bf16 v[24:27], v[136:139], v[176:179], v[24:27]
	v_mfma_f32_16x16x32_bf16 v[24:27], v[140:143], v[180:183], v[24:27]
	v_mfma_f32_16x16x32_bf16 v[8:11], v[140:143], v[204:207], v[8:11]
	v_mfma_f32_16x16x32_bf16 v[8:11], v[136:139], v[200:203], v[8:11]
	v_mfma_f32_16x16x32_bf16 v[52:55], v[144:147], v[160:163], v[52:55]
	v_mfma_f32_16x16x32_bf16 v[52:55], v[148:151], v[164:167], v[52:55]
	v_mfma_f32_16x16x32_bf16 v[36:39], v[148:151], v[172:175], v[36:39]
	v_mfma_f32_16x16x32_bf16 v[36:39], v[144:147], v[168:171], v[36:39]
	v_mfma_f32_16x16x32_bf16 v[20:23], v[144:147], v[176:179], v[20:23]
	v_mfma_f32_16x16x32_bf16 v[20:23], v[148:151], v[180:183], v[20:23]
	v_mfma_f32_16x16x32_bf16 v[4:7], v[148:151], v[204:207], v[4:7]
	v_mfma_f32_16x16x32_bf16 v[4:7], v[144:147], v[200:203], v[4:7]
	v_mfma_f32_16x16x32_bf16 v[48:51], v[152:155], v[160:163], v[48:51]
	v_mfma_f32_16x16x32_bf16 v[48:51], v[156:159], v[164:167], v[48:51]
	v_mfma_f32_16x16x32_bf16 v[32:35], v[156:159], v[172:175], v[32:35]
	v_mfma_f32_16x16x32_bf16 v[32:35], v[152:155], v[168:171], v[32:35]
	s_setprio 2
	s_barrier
	v_mfma_f32_16x16x32_bf16 v[16:19], v[152:155], v[176:179], v[16:19]
	v_mfma_f32_16x16x32_bf16 v[16:19], v[156:159], v[180:183], v[16:19]
	v_mfma_f32_16x16x32_bf16 v[0:3], v[156:159], v[204:207], v[0:3]
	v_mfma_f32_16x16x32_bf16 v[0:3], v[152:155], v[200:203], v[0:3]
	s_setprio 0
	s_add_i32 s66, s66, 2
	s_add_u32 s38, s38, 0x100
	s_addc_u32 s39, s39, 0
	s_add_u32 s64, s64, 0x100
	s_addc_u32 s65, s65, 0
	s_cmp_gt_u32 s66, 13
	s_cbranch_scc0 .LBB0_1146

.LBB0_1309:
	s_add_u32 s51, s26, 0x100
	s_addc_u32 s52, s27, 0
	s_mov_b32 s53, -2
	ds_read_b128 v[128:131], v197
	ds_read_b128 v[132:135], v197 offset:1024
	ds_read_b128 v[136:139], v197 offset:2048
	ds_read_b128 v[140:143], v197 offset:3072
	ds_read_b128 v[144:147], v198
	ds_read_b128 v[148:151], v198 offset:1024
	ds_read_b128 v[152:155], v198 offset:2048
	ds_read_b128 v[156:159], v198 offset:3072
	s_add_u32 s4, s24, 0x100
	s_addc_u32 s5, s25, 0
	s_cmp_eq_u32 s53, 40
	s_cselect_b32 s29, s21, s5
	s_cselect_b32 s28, s20, s4
	s_cselect_b32 s27, s23, s52
	s_cselect_b32 s26, s22, s51
	v_lshl_add_u64 v[212:213], s[24:25], 0, v[172:173]
	s_add_i32 m0, s36, 0xc000
	ds_read_b128 v[160:163], v199
	ds_read_b128 v[180:183], v199 offset:1024
	ds_read_b128 v[184:187], v199 offset:2048
	ds_read_b128 v[188:191], v199 offset:3072
	ds_read_b128 v[192:195], v199 offset:4096
	ds_read_b128 v[200:203], v199 offset:5120
	ds_read_b128 v[204:207], v199 offset:6144
	ds_read_b128 v[208:211], v199 offset:7168
	global_load_lds_dwordx4 v[212:213], off
	s_add_i32 m0, s36, 0xe000
	v_lshl_add_u64 v[212:213], s[24:25], 0, v[174:175]
	global_load_lds_dwordx4 v[212:213], off
	s_waitcnt vmcnt(8) lgkmcnt(0)
	s_barrier
	s_setprio 1
	v_mfma_f32_16x16x32_bf16 v[124:127], v[128:131], v[160:163], 0
	v_mfma_f32_16x16x32_bf16 v[124:127], v[132:135], v[180:183], v[124:127]
	v_mfma_f32_16x16x32_bf16 v[116:119], v[132:135], v[188:191], 0
	v_mfma_f32_16x16x32_bf16 v[116:119], v[128:131], v[184:187], v[116:119]
	v_mfma_f32_16x16x32_bf16 v[88:91], v[128:131], v[192:195], 0
	v_mfma_f32_16x16x32_bf16 v[88:91], v[132:135], v[200:203], v[88:91]
	v_mfma_f32_16x16x32_bf16 v[72:75], v[132:135], v[208:211], 0
	v_mfma_f32_16x16x32_bf16 v[72:75], v[128:131], v[204:207], v[72:75]
	v_mfma_f32_16x16x32_bf16 v[120:123], v[136:139], v[160:163], 0
	v_mfma_f32_16x16x32_bf16 v[120:123], v[140:143], v[180:183], v[120:123]
	v_mfma_f32_16x16x32_bf16 v[108:111], v[140:143], v[188:191], 0
	v_mfma_f32_16x16x32_bf16 v[108:111], v[136:139], v[184:187], v[108:111]
	v_mfma_f32_16x16x32_bf16 v[100:103], v[136:139], v[192:195], 0
	v_mfma_f32_16x16x32_bf16 v[100:103], v[140:143], v[200:203], v[100:103]
	v_mfma_f32_16x16x32_bf16 v[76:79], v[140:143], v[208:211], 0
	v_mfma_f32_16x16x32_bf16 v[76:79], v[136:139], v[204:207], v[76:79]
	v_mfma_f32_16x16x32_bf16 v[112:115], v[144:147], v[160:163], 0
	v_mfma_f32_16x16x32_bf16 v[112:115], v[148:151], v[180:183], v[112:115]
	v_mfma_f32_16x16x32_bf16 v[96:99], v[148:151], v[188:191], 0
	v_mfma_f32_16x16x32_bf16 v[96:99], v[144:147], v[184:187], v[96:99]
	v_mfma_f32_16x16x32_bf16 v[80:83], v[144:147], v[192:195], 0
	v_mfma_f32_16x16x32_bf16 v[80:83], v[148:151], v[200:203], v[80:83]
	v_mfma_f32_16x16x32_bf16 v[64:67], v[148:151], v[208:211], 0
	v_mfma_f32_16x16x32_bf16 v[64:67], v[144:147], v[204:207], v[64:67]
	v_mfma_f32_16x16x32_bf16 v[104:107], v[152:155], v[160:163], 0
	v_mfma_f32_16x16x32_bf16 v[104:107], v[156:159], v[180:183], v[104:107]
	v_mfma_f32_16x16x32_bf16 v[92:95], v[156:159], v[188:191], 0
	v_mfma_f32_16x16x32_bf16 v[92:95], v[152:155], v[184:187], v[92:95]
	s_setprio 2
	s_barrier
	v_mfma_f32_16x16x32_bf16 v[84:87], v[152:155], v[192:195], 0
	v_mfma_f32_16x16x32_bf16 v[84:87], v[156:159], v[200:203], v[84:87]
	v_mfma_f32_16x16x32_bf16 v[68:71], v[156:159], v[208:211], 0
	v_mfma_f32_16x16x32_bf16 v[68:71], v[152:155], v[204:207], v[68:71]
	s_setprio 2
	s_add_i32 s24, s45, s35
	v_lshl_add_u64 v[212:213], s[26:27], 0, v[166:167]
	s_mov_b32 m0, s24
	ds_read_b128 v[160:163], v199 offset:16384
	ds_read_b128 v[180:183], v199 offset:17408
	ds_read_b128 v[184:187], v199 offset:18432
	ds_read_b128 v[188:191], v199 offset:19456
	ds_read_b128 v[192:195], v199 offset:20480
	ds_read_b128 v[200:203], v199 offset:21504
	ds_read_b128 v[204:207], v199 offset:22528
	ds_read_b128 v[208:211], v199 offset:23552
	global_load_lds_dwordx4 v[212:213], off
	s_add_i32 m0, s24, 0x2000
	s_add_u32 s24, s26, 0xb0000
	v_lshl_add_u64 v[214:215], s[26:27], 0, v[170:171]
	s_addc_u32 s25, s27, 0
	s_add_i32 s54, s46, s35
	global_load_lds_dwordx4 v[214:215], off
	v_lshl_add_u64 v[216:217], s[24:25], 0, v[166:167]
	s_mov_b32 m0, s54
	v_lshl_add_u64 v[218:219], s[28:29], 0, v[168:169]
	global_load_lds_dwordx4 v[216:217], off
	s_add_i32 m0, s54, 0x2000
	v_lshl_add_u64 v[216:217], s[24:25], 0, v[170:171]
	global_load_lds_dwordx4 v[216:217], off
	s_mov_b32 m0, s36
	v_lshl_add_u64 v[216:217], s[28:29], 0, v[164:165]
	global_load_lds_dwordx4 v[216:217], off
	s_mov_b32 m0, s37
	s_nop 0
	global_load_lds_dwordx4 v[218:219], off
	s_waitcnt vmcnt(8) lgkmcnt(0)
	s_barrier
	s_setprio 1
	v_mfma_f32_16x16x32_bf16 v[56:59], v[128:131], v[160:163], 0
	v_mfma_f32_16x16x32_bf16 v[56:59], v[132:135], v[180:183], v[56:59]
	v_mfma_f32_16x16x32_bf16 v[40:43], v[132:135], v[188:191], 0
	v_mfma_f32_16x16x32_bf16 v[40:43], v[128:131], v[184:187], v[40:43]
	v_mfma_f32_16x16x32_bf16 v[24:27], v[128:131], v[192:195], 0
	v_mfma_f32_16x16x32_bf16 v[24:27], v[132:135], v[200:203], v[24:27]
	v_mfma_f32_16x16x32_bf16 v[8:11], v[132:135], v[208:211], 0
	v_mfma_f32_16x16x32_bf16 v[8:11], v[128:131], v[204:207], v[8:11]
	v_mfma_f32_16x16x32_bf16 v[60:63], v[136:139], v[160:163], 0
	v_mfma_f32_16x16x32_bf16 v[60:63], v[140:143], v[180:183], v[60:63]
	v_mfma_f32_16x16x32_bf16 v[44:47], v[140:143], v[188:191], 0
	v_mfma_f32_16x16x32_bf16 v[44:47], v[136:139], v[184:187], v[44:47]
	v_mfma_f32_16x16x32_bf16 v[28:31], v[136:139], v[192:195], 0
	v_mfma_f32_16x16x32_bf16 v[28:31], v[140:143], v[200:203], v[28:31]
	v_mfma_f32_16x16x32_bf16 v[12:15], v[140:143], v[208:211], 0
	v_mfma_f32_16x16x32_bf16 v[12:15], v[136:139], v[204:207], v[12:15]
	v_mfma_f32_16x16x32_bf16 v[48:51], v[144:147], v[160:163], 0
	v_mfma_f32_16x16x32_bf16 v[48:51], v[148:151], v[180:183], v[48:51]
	v_mfma_f32_16x16x32_bf16 v[32:35], v[148:151], v[188:191], 0
	v_mfma_f32_16x16x32_bf16 v[32:35], v[144:147], v[184:187], v[32:35]
	v_mfma_f32_16x16x32_bf16 v[16:19], v[144:147], v[192:195], 0
	v_mfma_f32_16x16x32_bf16 v[16:19], v[148:151], v[200:203], v[16:19]
	v_mfma_f32_16x16x32_bf16 v[0:3], v[148:151], v[208:211], 0
	v_mfma_f32_16x16x32_bf16 v[0:3], v[144:147], v[204:207], v[0:3]
	v_mfma_f32_16x16x32_bf16 v[52:55], v[152:155], v[160:163], 0
	v_mfma_f32_16x16x32_bf16 v[52:55], v[156:159], v[180:183], v[52:55]
	v_mfma_f32_16x16x32_bf16 v[36:39], v[156:159], v[188:191], 0
	v_mfma_f32_16x16x32_bf16 v[36:39], v[152:155], v[184:187], v[36:39]
	s_setprio 2
	s_barrier
	v_mfma_f32_16x16x32_bf16 v[20:23], v[152:155], v[192:195], 0
	v_mfma_f32_16x16x32_bf16 v[20:23], v[156:159], v[200:203], v[20:23]
	v_mfma_f32_16x16x32_bf16 v[4:7], v[156:159], v[208:211], 0
	v_mfma_f32_16x16x32_bf16 v[4:7], v[152:155], v[204:207], v[4:7]
	s_setprio 0
	s_add_i32 s54, 0, 0x18000
	s_add_i32 s55, 0, 0x1c000
	v_add_u32_e32 v140, s54, v196
	v_add_u32_e32 v156, s55, v196
	ds_read_b128 v[128:131], v140
	ds_read_b128 v[132:135], v140 offset:1024
	ds_read_b128 v[136:139], v140 offset:2048
	ds_read_b128 v[140:143], v140 offset:3072
	ds_read_b128 v[144:147], v156
	ds_read_b128 v[148:151], v156 offset:1024
	ds_read_b128 v[152:155], v156 offset:2048
	ds_read_b128 v[156:159], v156 offset:3072
	s_add_u32 s24, s28, 0xb0000
	s_addc_u32 s25, s29, 0
	s_mov_b32 m0, s38
	v_lshl_add_u64 v[220:221], s[24:25], 0, v[164:165]
	ds_read_b128 v[160:163], v199 offset:32768
	ds_read_b128 v[180:183], v199 offset:33792
	ds_read_b128 v[184:187], v199 offset:34816
	ds_read_b128 v[188:191], v199 offset:35840
	ds_read_b128 v[192:195], v199 offset:36864
	ds_read_b128 v[200:203], v199 offset:37888
	ds_read_b128 v[204:207], v199 offset:38912
	ds_read_b128 v[208:211], v199 offset:39936
	global_load_lds_dwordx4 v[220:221], off
	s_mov_b32 m0, s39
	v_lshl_add_u64 v[220:221], s[24:25], 0, v[168:169]
	global_load_lds_dwordx4 v[220:221], off
	s_waitcnt vmcnt(8) lgkmcnt(0)
	s_barrier
	s_setprio 1
	v_mfma_f32_16x16x32_bf16 v[124:127], v[128:131], v[160:163], v[124:127]
	v_mfma_f32_16x16x32_bf16 v[124:127], v[132:135], v[180:183], v[124:127]
	v_mfma_f32_16x16x32_bf16 v[116:119], v[132:135], v[188:191], v[116:119]
	v_mfma_f32_16x16x32_bf16 v[116:119], v[128:131], v[184:187], v[116:119]
	v_mfma_f32_16x16x32_bf16 v[88:91], v[128:131], v[192:195], v[88:91]
	v_mfma_f32_16x16x32_bf16 v[88:91], v[132:135], v[200:203], v[88:91]
	v_mfma_f32_16x16x32_bf16 v[72:75], v[132:135], v[208:211], v[72:75]
	v_mfma_f32_16x16x32_bf16 v[72:75], v[128:131], v[204:207], v[72:75]
	v_mfma_f32_16x16x32_bf16 v[120:123], v[136:139], v[160:163], v[120:123]
	v_mfma_f32_16x16x32_bf16 v[120:123], v[140:143], v[180:183], v[120:123]
	v_mfma_f32_16x16x32_bf16 v[108:111], v[140:143], v[188:191], v[108:111]
	v_mfma_f32_16x16x32_bf16 v[108:111], v[136:139], v[184:187], v[108:111]
	v_mfma_f32_16x16x32_bf16 v[100:103], v[136:139], v[192:195], v[100:103]
	v_mfma_f32_16x16x32_bf16 v[100:103], v[140:143], v[200:203], v[100:103]
	v_mfma_f32_16x16x32_bf16 v[76:79], v[140:143], v[208:211], v[76:79]
	v_mfma_f32_16x16x32_bf16 v[76:79], v[136:139], v[204:207], v[76:79]
	v_mfma_f32_16x16x32_bf16 v[112:115], v[144:147], v[160:163], v[112:115]
	v_mfma_f32_16x16x32_bf16 v[112:115], v[148:151], v[180:183], v[112:115]
	v_mfma_f32_16x16x32_bf16 v[96:99], v[148:151], v[188:191], v[96:99]
	v_mfma_f32_16x16x32_bf16 v[96:99], v[144:147], v[184:187], v[96:99]
	v_mfma_f32_16x16x32_bf16 v[80:83], v[144:147], v[192:195], v[80:83]
	v_mfma_f32_16x16x32_bf16 v[80:83], v[148:151], v[200:203], v[80:83]
	v_mfma_f32_16x16x32_bf16 v[64:67], v[148:151], v[208:211], v[64:67]
	v_mfma_f32_16x16x32_bf16 v[64:67], v[144:147], v[204:207], v[64:67]
	v_mfma_f32_16x16x32_bf16 v[104:107], v[152:155], v[160:163], v[104:107]
	v_mfma_f32_16x16x32_bf16 v[104:107], v[156:159], v[180:183], v[104:107]
	v_mfma_f32_16x16x32_bf16 v[92:95], v[156:159], v[188:191], v[92:95]
	v_mfma_f32_16x16x32_bf16 v[92:95], v[152:155], v[184:187], v[92:95]
	s_setprio 2
	s_barrier
	v_mfma_f32_16x16x32_bf16 v[84:87], v[152:155], v[192:195], v[84:87]
	v_mfma_f32_16x16x32_bf16 v[84:87], v[156:159], v[200:203], v[84:87]
	v_mfma_f32_16x16x32_bf16 v[68:71], v[156:159], v[208:211], v[68:71]
	v_mfma_f32_16x16x32_bf16 v[68:71], v[152:155], v[204:207], v[68:71]
	s_setprio 2
	s_add_i32 s24, s54, s35
	v_lshl_add_u64 v[212:213], v[212:213], 0, s[16:17]
	s_mov_b32 m0, s24
	ds_read_b128 v[160:163], v199 offset:49152
	ds_read_b128 v[180:183], v199 offset:50176
	ds_read_b128 v[184:187], v199 offset:51200
	ds_read_b128 v[188:191], v199 offset:52224
	ds_read_b128 v[192:195], v199 offset:53248
	ds_read_b128 v[200:203], v199 offset:54272
	ds_read_b128 v[204:207], v199 offset:55296
	ds_read_b128 v[208:211], v199 offset:56320
	global_load_lds_dwordx4 v[212:213], off
	s_add_i32 m0, s24, 0x2000
	s_add_u32 s24, s26, 0xb0080
	v_lshl_add_u64 v[212:213], v[214:215], 0, s[16:17]
	s_addc_u32 s25, s27, 0
	s_add_i32 s26, s55, s35
	global_load_lds_dwordx4 v[212:213], off
	s_mov_b32 m0, s26
	v_lshl_add_u64 v[212:213], s[24:25], 0, v[166:167]
	global_load_lds_dwordx4 v[212:213], off
	s_add_i32 m0, s26, 0x2000
	v_lshl_add_u64 v[212:213], s[24:25], 0, v[170:171]
	global_load_lds_dwordx4 v[212:213], off
	s_mov_b32 m0, s41
	v_lshl_add_u64 v[212:213], v[216:217], 0, s[16:17]
	global_load_lds_dwordx4 v[212:213], off
	s_mov_b32 m0, s42
	v_lshl_add_u64 v[212:213], v[218:219], 0, s[16:17]
	global_load_lds_dwordx4 v[212:213], off
	s_waitcnt vmcnt(8) lgkmcnt(0)
	s_barrier
	s_setprio 1
	v_mfma_f32_16x16x32_bf16 v[56:59], v[128:131], v[160:163], v[56:59]
	v_mfma_f32_16x16x32_bf16 v[56:59], v[132:135], v[180:183], v[56:59]
	v_mfma_f32_16x16x32_bf16 v[40:43], v[132:135], v[188:191], v[40:43]
	v_mfma_f32_16x16x32_bf16 v[40:43], v[128:131], v[184:187], v[40:43]
	v_mfma_f32_16x16x32_bf16 v[24:27], v[128:131], v[192:195], v[24:27]
	v_mfma_f32_16x16x32_bf16 v[24:27], v[132:135], v[200:203], v[24:27]
	v_mfma_f32_16x16x32_bf16 v[8:11], v[132:135], v[208:211], v[8:11]
	v_mfma_f32_16x16x32_bf16 v[8:11], v[128:131], v[204:207], v[8:11]
	v_mfma_f32_16x16x32_bf16 v[60:63], v[136:139], v[160:163], v[60:63]
	v_mfma_f32_16x16x32_bf16 v[60:63], v[140:143], v[180:183], v[60:63]
	v_mfma_f32_16x16x32_bf16 v[44:47], v[140:143], v[188:191], v[44:47]
	v_mfma_f32_16x16x32_bf16 v[44:47], v[136:139], v[184:187], v[44:47]
	v_mfma_f32_16x16x32_bf16 v[28:31], v[136:139], v[192:195], v[28:31]
	v_mfma_f32_16x16x32_bf16 v[28:31], v[140:143], v[200:203], v[28:31]
	v_mfma_f32_16x16x32_bf16 v[12:15], v[140:143], v[208:211], v[12:15]
	v_mfma_f32_16x16x32_bf16 v[12:15], v[136:139], v[204:207], v[12:15]
	v_mfma_f32_16x16x32_bf16 v[48:51], v[144:147], v[160:163], v[48:51]
	v_mfma_f32_16x16x32_bf16 v[48:51], v[148:151], v[180:183], v[48:51]
	v_mfma_f32_16x16x32_bf16 v[32:35], v[148:151], v[188:191], v[32:35]
	v_mfma_f32_16x16x32_bf16 v[32:35], v[144:147], v[184:187], v[32:35]
	v_mfma_f32_16x16x32_bf16 v[16:19], v[144:147], v[192:195], v[16:19]
	v_mfma_f32_16x16x32_bf16 v[16:19], v[148:151], v[200:203], v[16:19]
	v_mfma_f32_16x16x32_bf16 v[0:3], v[148:151], v[208:211], v[0:3]
	v_mfma_f32_16x16x32_bf16 v[0:3], v[144:147], v[204:207], v[0:3]
	v_mfma_f32_16x16x32_bf16 v[52:55], v[152:155], v[160:163], v[52:55]
	v_mfma_f32_16x16x32_bf16 v[52:55], v[156:159], v[180:183], v[52:55]
	v_mfma_f32_16x16x32_bf16 v[36:39], v[156:159], v[188:191], v[36:39]
	v_mfma_f32_16x16x32_bf16 v[36:39], v[152:155], v[184:187], v[36:39]
	s_setprio 2
	s_barrier
	v_mfma_f32_16x16x32_bf16 v[20:23], v[152:155], v[192:195], v[20:23]
	v_mfma_f32_16x16x32_bf16 v[20:23], v[156:159], v[200:203], v[20:23]
	v_mfma_f32_16x16x32_bf16 v[4:7], v[156:159], v[208:211], v[4:7]
	v_mfma_f32_16x16x32_bf16 v[4:7], v[152:155], v[204:207], v[4:7]
	s_setprio 0
	s_add_i32 s53, s53, 2
	s_add_u32 s51, s51, 0x100
	s_addc_u32 s52, s52, 0
	s_cmp_gt_u32 s53, 41
	s_mov_b64 s[24:25], s[4:5]
.LBB0_1310:
	ds_read_b128 v[128:131], v197
	ds_read_b128 v[132:135], v197 offset:1024
	ds_read_b128 v[136:139], v197 offset:2048
	ds_read_b128 v[140:143], v197 offset:3072
	ds_read_b128 v[144:147], v198
	ds_read_b128 v[148:151], v198 offset:1024
	ds_read_b128 v[152:155], v198 offset:2048
	ds_read_b128 v[156:159], v198 offset:3072
	s_add_u32 s4, s24, 0x100
	s_addc_u32 s5, s25, 0
	s_cmp_eq_u32 s53, 40
	s_cselect_b32 s29, s21, s5
	s_cselect_b32 s28, s20, s4
	s_cselect_b32 s27, s23, s52
	s_cselect_b32 s26, s22, s51
	v_lshl_add_u64 v[212:213], s[24:25], 0, v[172:173]
	s_add_i32 m0, s36, 0xc000
	ds_read_b128 v[160:163], v199
	ds_read_b128 v[180:183], v199 offset:1024
	ds_read_b128 v[184:187], v199 offset:2048
	ds_read_b128 v[188:191], v199 offset:3072
	ds_read_b128 v[192:195], v199 offset:4096
	ds_read_b128 v[200:203], v199 offset:5120
	ds_read_b128 v[204:207], v199 offset:6144
	ds_read_b128 v[208:211], v199 offset:7168
	global_load_lds_dwordx4 v[212:213], off
	s_add_i32 m0, s36, 0xe000
	v_lshl_add_u64 v[212:213], s[24:25], 0, v[174:175]
	global_load_lds_dwordx4 v[212:213], off
	s_waitcnt vmcnt(8) lgkmcnt(0)
	s_barrier
	s_setprio 1
	v_mfma_f32_16x16x32_bf16 v[124:127], v[128:131], v[160:163], v[124:127]
	v_mfma_f32_16x16x32_bf16 v[124:127], v[132:135], v[180:183], v[124:127]
	v_mfma_f32_16x16x32_bf16 v[116:119], v[132:135], v[188:191], v[116:119]
	v_mfma_f32_16x16x32_bf16 v[116:119], v[128:131], v[184:187], v[116:119]
	v_mfma_f32_16x16x32_bf16 v[88:91], v[128:131], v[192:195], v[88:91]
	v_mfma_f32_16x16x32_bf16 v[88:91], v[132:135], v[200:203], v[88:91]
	v_mfma_f32_16x16x32_bf16 v[72:75], v[132:135], v[208:211], v[72:75]
	v_mfma_f32_16x16x32_bf16 v[72:75], v[128:131], v[204:207], v[72:75]
	v_mfma_f32_16x16x32_bf16 v[120:123], v[136:139], v[160:163], v[120:123]
	v_mfma_f32_16x16x32_bf16 v[120:123], v[140:143], v[180:183], v[120:123]
	v_mfma_f32_16x16x32_bf16 v[108:111], v[140:143], v[188:191], v[108:111]
	v_mfma_f32_16x16x32_bf16 v[108:111], v[136:139], v[184:187], v[108:111]
	v_mfma_f32_16x16x32_bf16 v[100:103], v[136:139], v[192:195], v[100:103]
	v_mfma_f32_16x16x32_bf16 v[100:103], v[140:143], v[200:203], v[100:103]
	v_mfma_f32_16x16x32_bf16 v[76:79], v[140:143], v[208:211], v[76:79]
	v_mfma_f32_16x16x32_bf16 v[76:79], v[136:139], v[204:207], v[76:79]
	v_mfma_f32_16x16x32_bf16 v[112:115], v[144:147], v[160:163], v[112:115]
	v_mfma_f32_16x16x32_bf16 v[112:115], v[148:151], v[180:183], v[112:115]
	v_mfma_f32_16x16x32_bf16 v[96:99], v[148:151], v[188:191], v[96:99]
	v_mfma_f32_16x16x32_bf16 v[96:99], v[144:147], v[184:187], v[96:99]
	v_mfma_f32_16x16x32_bf16 v[80:83], v[144:147], v[192:195], v[80:83]
	v_mfma_f32_16x16x32_bf16 v[80:83], v[148:151], v[200:203], v[80:83]
	v_mfma_f32_16x16x32_bf16 v[64:67], v[148:151], v[208:211], v[64:67]
	v_mfma_f32_16x16x32_bf16 v[64:67], v[144:147], v[204:207], v[64:67]
	v_mfma_f32_16x16x32_bf16 v[104:107], v[152:155], v[160:163], v[104:107]
	v_mfma_f32_16x16x32_bf16 v[104:107], v[156:159], v[180:183], v[104:107]
	v_mfma_f32_16x16x32_bf16 v[92:95], v[156:159], v[188:191], v[92:95]
	v_mfma_f32_16x16x32_bf16 v[92:95], v[152:155], v[184:187], v[92:95]
	s_setprio 2
	s_barrier
	v_mfma_f32_16x16x32_bf16 v[84:87], v[152:155], v[192:195], v[84:87]
	v_mfma_f32_16x16x32_bf16 v[84:87], v[156:159], v[200:203], v[84:87]
	v_mfma_f32_16x16x32_bf16 v[68:71], v[156:159], v[208:211], v[68:71]
	v_mfma_f32_16x16x32_bf16 v[68:71], v[152:155], v[204:207], v[68:71]
	s_setprio 2
	s_add_i32 s24, s45, s35
	v_lshl_add_u64 v[212:213], s[26:27], 0, v[166:167]
	s_mov_b32 m0, s24
	ds_read_b128 v[160:163], v199 offset:16384
	ds_read_b128 v[180:183], v199 offset:17408
	ds_read_b128 v[184:187], v199 offset:18432
	ds_read_b128 v[188:191], v199 offset:19456
	ds_read_b128 v[192:195], v199 offset:20480
	ds_read_b128 v[200:203], v199 offset:21504
	ds_read_b128 v[204:207], v199 offset:22528
	ds_read_b128 v[208:211], v199 offset:23552
	global_load_lds_dwordx4 v[212:213], off
	s_add_i32 m0, s24, 0x2000
	s_add_u32 s24, s26, 0xb0000
	v_lshl_add_u64 v[214:215], s[26:27], 0, v[170:171]
	s_addc_u32 s25, s27, 0
	s_add_i32 s54, s46, s35
	global_load_lds_dwordx4 v[214:215], off
	v_lshl_add_u64 v[216:217], s[24:25], 0, v[166:167]
	s_mov_b32 m0, s54
	v_lshl_add_u64 v[218:219], s[28:29], 0, v[168:169]
	global_load_lds_dwordx4 v[216:217], off
	s_add_i32 m0, s54, 0x2000
	v_lshl_add_u64 v[216:217], s[24:25], 0, v[170:171]
	global_load_lds_dwordx4 v[216:217], off
	s_mov_b32 m0, s36
	v_lshl_add_u64 v[216:217], s[28:29], 0, v[164:165]
	global_load_lds_dwordx4 v[216:217], off
	s_mov_b32 m0, s37
	s_nop 0
	global_load_lds_dwordx4 v[218:219], off
	s_waitcnt vmcnt(8) lgkmcnt(0)
	s_barrier
	s_setprio 1
	v_mfma_f32_16x16x32_bf16 v[56:59], v[128:131], v[160:163], v[56:59]
	v_mfma_f32_16x16x32_bf16 v[56:59], v[132:135], v[180:183], v[56:59]
	v_mfma_f32_16x16x32_bf16 v[40:43], v[132:135], v[188:191], v[40:43]
	v_mfma_f32_16x16x32_bf16 v[40:43], v[128:131], v[184:187], v[40:43]
	v_mfma_f32_16x16x32_bf16 v[24:27], v[128:131], v[192:195], v[24:27]
	v_mfma_f32_16x16x32_bf16 v[24:27], v[132:135], v[200:203], v[24:27]
	v_mfma_f32_16x16x32_bf16 v[8:11], v[132:135], v[208:211], v[8:11]
	v_mfma_f32_16x16x32_bf16 v[8:11], v[128:131], v[204:207], v[8:11]
	v_mfma_f32_16x16x32_bf16 v[60:63], v[136:139], v[160:163], v[60:63]
	v_mfma_f32_16x16x32_bf16 v[60:63], v[140:143], v[180:183], v[60:63]
	v_mfma_f32_16x16x32_bf16 v[44:47], v[140:143], v[188:191], v[44:47]
	v_mfma_f32_16x16x32_bf16 v[44:47], v[136:139], v[184:187], v[44:47]
	v_mfma_f32_16x16x32_bf16 v[28:31], v[136:139], v[192:195], v[28:31]
	v_mfma_f32_16x16x32_bf16 v[28:31], v[140:143], v[200:203], v[28:31]
	v_mfma_f32_16x16x32_bf16 v[12:15], v[140:143], v[208:211], v[12:15]
	v_mfma_f32_16x16x32_bf16 v[12:15], v[136:139], v[204:207], v[12:15]
	v_mfma_f32_16x16x32_bf16 v[48:51], v[144:147], v[160:163], v[48:51]
	v_mfma_f32_16x16x32_bf16 v[48:51], v[148:151], v[180:183], v[48:51]
	v_mfma_f32_16x16x32_bf16 v[32:35], v[148:151], v[188:191], v[32:35]
	v_mfma_f32_16x16x32_bf16 v[32:35], v[144:147], v[184:187], v[32:35]
	v_mfma_f32_16x16x32_bf16 v[16:19], v[144:147], v[192:195], v[16:19]
	v_mfma_f32_16x16x32_bf16 v[16:19], v[148:151], v[200:203], v[16:19]
	v_mfma_f32_16x16x32_bf16 v[0:3], v[148:151], v[208:211], v[0:3]
	v_mfma_f32_16x16x32_bf16 v[0:3], v[144:147], v[204:207], v[0:3]
	v_mfma_f32_16x16x32_bf16 v[52:55], v[152:155], v[160:163], v[52:55]
	v_mfma_f32_16x16x32_bf16 v[52:55], v[156:159], v[180:183], v[52:55]
	v_mfma_f32_16x16x32_bf16 v[36:39], v[156:159], v[188:191], v[36:39]
	v_mfma_f32_16x16x32_bf16 v[36:39], v[152:155], v[184:187], v[36:39]
	s_setprio 2
	s_barrier
	v_mfma_f32_16x16x32_bf16 v[20:23], v[152:155], v[192:195], v[20:23]
	v_mfma_f32_16x16x32_bf16 v[20:23], v[156:159], v[200:203], v[20:23]
	v_mfma_f32_16x16x32_bf16 v[4:7], v[156:159], v[208:211], v[4:7]
	v_mfma_f32_16x16x32_bf16 v[4:7], v[152:155], v[204:207], v[4:7]
	s_setprio 0
	s_add_i32 s54, 0, 0x18000
	s_add_i32 s55, 0, 0x1c000
	v_add_u32_e32 v140, s54, v196
	v_add_u32_e32 v156, s55, v196
	ds_read_b128 v[128:131], v140
	ds_read_b128 v[132:135], v140 offset:1024
	ds_read_b128 v[136:139], v140 offset:2048
	ds_read_b128 v[140:143], v140 offset:3072
	ds_read_b128 v[144:147], v156
	ds_read_b128 v[148:151], v156 offset:1024
	ds_read_b128 v[152:155], v156 offset:2048
	ds_read_b128 v[156:159], v156 offset:3072
	s_add_u32 s24, s28, 0xb0000
	s_addc_u32 s25, s29, 0
	s_mov_b32 m0, s38
	v_lshl_add_u64 v[220:221], s[24:25], 0, v[164:165]
	ds_read_b128 v[160:163], v199 offset:32768
	ds_read_b128 v[180:183], v199 offset:33792
	ds_read_b128 v[184:187], v199 offset:34816
	ds_read_b128 v[188:191], v199 offset:35840
	ds_read_b128 v[192:195], v199 offset:36864
	ds_read_b128 v[200:203], v199 offset:37888
	ds_read_b128 v[204:207], v199 offset:38912
	ds_read_b128 v[208:211], v199 offset:39936
	global_load_lds_dwordx4 v[220:221], off
	s_mov_b32 m0, s39
	v_lshl_add_u64 v[220:221], s[24:25], 0, v[168:169]
	global_load_lds_dwordx4 v[220:221], off
	s_waitcnt vmcnt(8) lgkmcnt(0)
	s_barrier
	s_setprio 1
	v_mfma_f32_16x16x32_bf16 v[124:127], v[128:131], v[160:163], v[124:127]
	v_mfma_f32_16x16x32_bf16 v[124:127], v[132:135], v[180:183], v[124:127]
	v_mfma_f32_16x16x32_bf16 v[116:119], v[132:135], v[188:191], v[116:119]
	v_mfma_f32_16x16x32_bf16 v[116:119], v[128:131], v[184:187], v[116:119]
	v_mfma_f32_16x16x32_bf16 v[88:91], v[128:131], v[192:195], v[88:91]
	v_mfma_f32_16x16x32_bf16 v[88:91], v[132:135], v[200:203], v[88:91]
	v_mfma_f32_16x16x32_bf16 v[72:75], v[132:135], v[208:211], v[72:75]
	v_mfma_f32_16x16x32_bf16 v[72:75], v[128:131], v[204:207], v[72:75]
	v_mfma_f32_16x16x32_bf16 v[120:123], v[136:139], v[160:163], v[120:123]
	v_mfma_f32_16x16x32_bf16 v[120:123], v[140:143], v[180:183], v[120:123]
	v_mfma_f32_16x16x32_bf16 v[108:111], v[140:143], v[188:191], v[108:111]
	v_mfma_f32_16x16x32_bf16 v[108:111], v[136:139], v[184:187], v[108:111]
	v_mfma_f32_16x16x32_bf16 v[100:103], v[136:139], v[192:195], v[100:103]
	v_mfma_f32_16x16x32_bf16 v[100:103], v[140:143], v[200:203], v[100:103]
	v_mfma_f32_16x16x32_bf16 v[76:79], v[140:143], v[208:211], v[76:79]
	v_mfma_f32_16x16x32_bf16 v[76:79], v[136:139], v[204:207], v[76:79]
	v_mfma_f32_16x16x32_bf16 v[112:115], v[144:147], v[160:163], v[112:115]
	v_mfma_f32_16x16x32_bf16 v[112:115], v[148:151], v[180:183], v[112:115]
	v_mfma_f32_16x16x32_bf16 v[96:99], v[148:151], v[188:191], v[96:99]
	v_mfma_f32_16x16x32_bf16 v[96:99], v[144:147], v[184:187], v[96:99]
	v_mfma_f32_16x16x32_bf16 v[80:83], v[144:147], v[192:195], v[80:83]
	v_mfma_f32_16x16x32_bf16 v[80:83], v[148:151], v[200:203], v[80:83]
	v_mfma_f32_16x16x32_bf16 v[64:67], v[148:151], v[208:211], v[64:67]
	v_mfma_f32_16x16x32_bf16 v[64:67], v[144:147], v[204:207], v[64:67]
	v_mfma_f32_16x16x32_bf16 v[104:107], v[152:155], v[160:163], v[104:107]
	v_mfma_f32_16x16x32_bf16 v[104:107], v[156:159], v[180:183], v[104:107]
	v_mfma_f32_16x16x32_bf16 v[92:95], v[156:159], v[188:191], v[92:95]
	v_mfma_f32_16x16x32_bf16 v[92:95], v[152:155], v[184:187], v[92:95]
	s_setprio 2
	s_barrier
	v_mfma_f32_16x16x32_bf16 v[84:87], v[152:155], v[192:195], v[84:87]
	v_mfma_f32_16x16x32_bf16 v[84:87], v[156:159], v[200:203], v[84:87]
	v_mfma_f32_16x16x32_bf16 v[68:71], v[156:159], v[208:211], v[68:71]
	v_mfma_f32_16x16x32_bf16 v[68:71], v[152:155], v[204:207], v[68:71]
	s_setprio 2
	s_add_i32 s24, s54, s35
	v_lshl_add_u64 v[212:213], v[212:213], 0, s[16:17]
	s_mov_b32 m0, s24
	ds_read_b128 v[160:163], v199 offset:49152
	ds_read_b128 v[180:183], v199 offset:50176
	ds_read_b128 v[184:187], v199 offset:51200
	ds_read_b128 v[188:191], v199 offset:52224
	ds_read_b128 v[192:195], v199 offset:53248
	ds_read_b128 v[200:203], v199 offset:54272
	ds_read_b128 v[204:207], v199 offset:55296
	ds_read_b128 v[208:211], v199 offset:56320
	global_load_lds_dwordx4 v[212:213], off
	s_add_i32 m0, s24, 0x2000
	s_add_u32 s24, s26, 0xb0080
	v_lshl_add_u64 v[212:213], v[214:215], 0, s[16:17]
	s_addc_u32 s25, s27, 0
	s_add_i32 s26, s55, s35
	global_load_lds_dwordx4 v[212:213], off
	s_mov_b32 m0, s26
	v_lshl_add_u64 v[212:213], s[24:25], 0, v[166:167]
	global_load_lds_dwordx4 v[212:213], off
	s_add_i32 m0, s26, 0x2000
	v_lshl_add_u64 v[212:213], s[24:25], 0, v[170:171]
	global_load_lds_dwordx4 v[212:213], off
	s_mov_b32 m0, s41
	v_lshl_add_u64 v[212:213], v[216:217], 0, s[16:17]
	global_load_lds_dwordx4 v[212:213], off
	s_mov_b32 m0, s42
	v_lshl_add_u64 v[212:213], v[218:219], 0, s[16:17]
	global_load_lds_dwordx4 v[212:213], off
	s_waitcnt vmcnt(8) lgkmcnt(0)
	s_barrier
	s_setprio 1
	v_mfma_f32_16x16x32_bf16 v[56:59], v[128:131], v[160:163], v[56:59]
	v_mfma_f32_16x16x32_bf16 v[56:59], v[132:135], v[180:183], v[56:59]
	v_mfma_f32_16x16x32_bf16 v[40:43], v[132:135], v[188:191], v[40:43]
	v_mfma_f32_16x16x32_bf16 v[40:43], v[128:131], v[184:187], v[40:43]
	v_mfma_f32_16x16x32_bf16 v[24:27], v[128:131], v[192:195], v[24:27]
	v_mfma_f32_16x16x32_bf16 v[24:27], v[132:135], v[200:203], v[24:27]
	v_mfma_f32_16x16x32_bf16 v[8:11], v[132:135], v[208:211], v[8:11]
	v_mfma_f32_16x16x32_bf16 v[8:11], v[128:131], v[204:207], v[8:11]
	v_mfma_f32_16x16x32_bf16 v[60:63], v[136:139], v[160:163], v[60:63]
	v_mfma_f32_16x16x32_bf16 v[60:63], v[140:143], v[180:183], v[60:63]
	v_mfma_f32_16x16x32_bf16 v[44:47], v[140:143], v[188:191], v[44:47]
	v_mfma_f32_16x16x32_bf16 v[44:47], v[136:139], v[184:187], v[44:47]
	v_mfma_f32_16x16x32_bf16 v[28:31], v[136:139], v[192:195], v[28:31]
	v_mfma_f32_16x16x32_bf16 v[28:31], v[140:143], v[200:203], v[28:31]
	v_mfma_f32_16x16x32_bf16 v[12:15], v[140:143], v[208:211], v[12:15]
	v_mfma_f32_16x16x32_bf16 v[12:15], v[136:139], v[204:207], v[12:15]
	v_mfma_f32_16x16x32_bf16 v[48:51], v[144:147], v[160:163], v[48:51]
	v_mfma_f32_16x16x32_bf16 v[48:51], v[148:151], v[180:183], v[48:51]
	v_mfma_f32_16x16x32_bf16 v[32:35], v[148:151], v[188:191], v[32:35]
	v_mfma_f32_16x16x32_bf16 v[32:35], v[144:147], v[184:187], v[32:35]
	v_mfma_f32_16x16x32_bf16 v[16:19], v[144:147], v[192:195], v[16:19]
	v_mfma_f32_16x16x32_bf16 v[16:19], v[148:151], v[200:203], v[16:19]
	v_mfma_f32_16x16x32_bf16 v[0:3], v[148:151], v[208:211], v[0:3]
	v_mfma_f32_16x16x32_bf16 v[0:3], v[144:147], v[204:207], v[0:3]
	v_mfma_f32_16x16x32_bf16 v[52:55], v[152:155], v[160:163], v[52:55]
	v_mfma_f32_16x16x32_bf16 v[52:55], v[156:159], v[180:183], v[52:55]
	v_mfma_f32_16x16x32_bf16 v[36:39], v[156:159], v[188:191], v[36:39]
	v_mfma_f32_16x16x32_bf16 v[36:39], v[152:155], v[184:187], v[36:39]
	s_setprio 2
	s_barrier
	v_mfma_f32_16x16x32_bf16 v[20:23], v[152:155], v[192:195], v[20:23]
	v_mfma_f32_16x16x32_bf16 v[20:23], v[156:159], v[200:203], v[20:23]
	v_mfma_f32_16x16x32_bf16 v[4:7], v[156:159], v[208:211], v[4:7]
	v_mfma_f32_16x16x32_bf16 v[4:7], v[152:155], v[204:207], v[4:7]
	s_setprio 0
	s_add_i32 s53, s53, 2
	s_add_u32 s51, s51, 0x100
	s_addc_u32 s52, s52, 0
	s_cmp_gt_u32 s53, 41
	s_mov_b64 s[24:25], s[4:5]
	s_cbranch_scc0 .LBB0_1310
